# speedup vs baseline: 1.0219x; 1.0143x over previous
; __device__ void transpose_cvt(const float* __restrict__ W, const float* __restrict__ gain, int K, int N, u16* WT, bool winmap, float* tile0, int tid) {
;     ...
;   for (int t = blockIdx.x * 8 + wid; t < ntiles; t += NBLK * 8) {
;     const int k0 = (t / ntn) << 6, n0 = (t % ntn) << 6;
; #pragma unroll 16
;     for (int r = 0; r < 64; ++r) { float v = W[(size_t)(k0 + r) * N + n0 + lane]; if (gain) v *= gain[k0 + r]; tile[r * 65 + lane] = v; }
;     asm volatile("s_waitcnt lgkmcnt(0)" ::: "memory");
.LBB0_39:
.LBB0_40:
	v_lshl_add_u64 v[180:181], v[12:13], 0, s[18:19]
	global_load_dword v148, v[180:181], off
	v_add_co_u32_e32 v182, vcc, 0x3000, v180
	s_nop 1
	v_addc_co_u32_e32 v183, vcc, 0, v181, vcc
	global_load_dword v149, v[182:183], off offset:2304
	v_add_co_u32_e32 v182, vcc, 0x7000, v180
	s_nop 1
	v_addc_co_u32_e32 v183, vcc, 0, v181, vcc
	global_load_dword v150, v[182:183], off offset:512
	v_add_co_u32_e32 v182, vcc, 0xa000, v180
	s_nop 1
	v_addc_co_u32_e32 v183, vcc, 0, v181, vcc
	global_load_dword v151, v[182:183], off offset:2816
	v_add_co_u32_e32 v182, vcc, 0xe000, v180
	s_nop 1
	v_addc_co_u32_e32 v183, vcc, 0, v181, vcc
	global_load_dword v152, v[182:183], off offset:1024
	v_add_co_u32_e32 v182, vcc, 0x11000, v180
	s_nop 1
	v_addc_co_u32_e32 v183, vcc, 0, v181, vcc
	global_load_dword v153, v[182:183], off offset:3328
	v_add_co_u32_e32 v182, vcc, 0x15000, v180
	s_nop 1
	v_addc_co_u32_e32 v183, vcc, 0, v181, vcc
	global_load_dword v154, v[182:183], off offset:1536
	v_add_co_u32_e32 v182, vcc, 0x18000, v180
	s_nop 1
	v_addc_co_u32_e32 v183, vcc, 0, v181, vcc
	global_load_dword v155, v[182:183], off offset:3840
	v_add_co_u32_e32 v182, vcc, 0x1c000, v180
	s_nop 1
	v_addc_co_u32_e32 v183, vcc, 0, v181, vcc
	global_load_dword v156, v[182:183], off offset:2048
	v_add_co_u32_e32 v182, vcc, 0x20000, v180
	s_nop 1
	v_addc_co_u32_e32 v183, vcc, 0, v181, vcc
	global_load_dword v157, v[182:183], off offset:256
	v_add_co_u32_e32 v182, vcc, 0x23000, v180
	s_nop 1
	v_addc_co_u32_e32 v183, vcc, 0, v181, vcc
	global_load_dword v158, v[182:183], off offset:2560
	v_add_co_u32_e32 v182, vcc, 0x27000, v180
	s_nop 1
	v_addc_co_u32_e32 v183, vcc, 0, v181, vcc
	global_load_dword v159, v[182:183], off offset:768
	v_add_co_u32_e32 v182, vcc, 0x2a000, v180
	s_nop 1
	v_addc_co_u32_e32 v183, vcc, 0, v181, vcc
	global_load_dword v160, v[182:183], off offset:3072
	v_add_co_u32_e32 v182, vcc, 0x2e000, v180
	s_nop 1
	v_addc_co_u32_e32 v183, vcc, 0, v181, vcc
	global_load_dword v161, v[182:183], off offset:1280
	v_add_co_u32_e32 v182, vcc, 0x31000, v180
	s_nop 1
	v_addc_co_u32_e32 v183, vcc, 0, v181, vcc
	global_load_dword v162, v[182:183], off offset:3584
	v_add_co_u32_e32 v182, vcc, 0x35000, v180
	s_nop 1
	v_addc_co_u32_e32 v183, vcc, 0, v181, vcc
	global_load_dword v163, v[182:183], off offset:1792
	global_load_dwordx4 v[164:167], v[14:15], off offset:-60
	global_load_dwordx4 v[168:171], v[14:15], off offset:-44
	global_load_dwordx4 v[172:175], v[14:15], off offset:-28
	global_load_dwordx4 v[176:179], v[14:15], off offset:-12
	s_waitcnt vmcnt(0)
	v_mul_f32_e32 v148, v148, v164
	v_mul_f32_e32 v149, v149, v165
	v_mul_f32_e32 v150, v150, v166
	v_mul_f32_e32 v151, v151, v167
	v_mul_f32_e32 v152, v152, v168
	v_mul_f32_e32 v153, v153, v169
	v_mul_f32_e32 v154, v154, v170
	v_mul_f32_e32 v155, v155, v171
	v_mul_f32_e32 v156, v156, v172
	v_mul_f32_e32 v157, v157, v173
	v_mul_f32_e32 v158, v158, v174
	v_mul_f32_e32 v159, v159, v175
	v_mul_f32_e32 v160, v160, v176
	v_mul_f32_e32 v161, v161, v177
	v_mul_f32_e32 v162, v162, v178
	v_mul_f32_e32 v163, v163, v179
	ds_write_b32 v9, v148
	ds_write_b32 v9, v149 offset:260
	ds_write_b32 v9, v150 offset:520
	ds_write_b32 v9, v151 offset:780
	ds_write_b32 v9, v152 offset:1040
	ds_write_b32 v9, v153 offset:1300
	ds_write_b32 v9, v154 offset:1560
	ds_write_b32 v9, v155 offset:1820
	ds_write_b32 v9, v156 offset:2080
	ds_write_b32 v9, v157 offset:2340
	ds_write_b32 v9, v158 offset:2600
	ds_write_b32 v9, v159 offset:2860
	ds_write_b32 v9, v160 offset:3120
	ds_write_b32 v9, v161 offset:3380
	ds_write_b32 v9, v162 offset:3640
	ds_write_b32 v9, v163 offset:3900
	s_add_u32 s18, s18, 0x39000
	s_addc_u32 s19, s19, 0
	v_lshl_add_u64 v[14:15], v[14:15], 0, 64
	v_add_u32_e32 v9, 0x1040, v9
	s_cmp_eq_u32 s18, 0xe4000
	s_cbranch_scc0 .LBB0_40

; __device__ void transpose_cvt(const float* __restrict__ W, const float* __restrict__ gain, int K, int N, u16* WT, bool winmap, float* tile0, int tid) {
;     ...
;   for (int t = blockIdx.x * 8 + wid; t < ntiles; t += NBLK * 8) {
;     const int k0 = (t / ntn) << 6, n0 = (t % ntn) << 6;
; #pragma unroll 16
;     for (int r = 0; r < 64; ++r) { float v = W[(size_t)(k0 + r) * N + n0 + lane]; if (gain) v *= gain[k0 + r]; tile[r * 65 + lane] = v; }
;     asm volatile("s_waitcnt lgkmcnt(0)" ::: "memory");
.LBB0_301:
.LBB0_302:
	v_lshl_add_u64 v[180:181], v[12:13], 0, s[4:5]
	global_load_dword v148, v[180:181], off
	v_add_co_u32_e32 v182, vcc, 0x1000, v180
	s_nop 1
	v_addc_co_u32_e32 v183, vcc, 0, v181, vcc
	global_load_dword v149, v[182:183], off offset:2048
	v_add_co_u32_e32 v182, vcc, 0x3000, v180
	s_nop 1
	v_addc_co_u32_e32 v183, vcc, 0, v181, vcc
	global_load_dword v150, v[182:183], off
	v_add_co_u32_e32 v182, vcc, 0x4000, v180
	s_nop 1
	v_addc_co_u32_e32 v183, vcc, 0, v181, vcc
	global_load_dword v151, v[182:183], off offset:2048
	v_add_co_u32_e32 v182, vcc, 0x6000, v180
	s_nop 1
	v_addc_co_u32_e32 v183, vcc, 0, v181, vcc
	global_load_dword v152, v[182:183], off
	v_add_co_u32_e32 v182, vcc, 0x7000, v180
	s_nop 1
	v_addc_co_u32_e32 v183, vcc, 0, v181, vcc
	global_load_dword v153, v[182:183], off offset:2048
	v_add_co_u32_e32 v182, vcc, 0x9000, v180
	s_nop 1
	v_addc_co_u32_e32 v183, vcc, 0, v181, vcc
	global_load_dword v154, v[182:183], off
	v_add_co_u32_e32 v182, vcc, 0xa000, v180
	s_nop 1
	v_addc_co_u32_e32 v183, vcc, 0, v181, vcc
	global_load_dword v155, v[182:183], off offset:2048
	v_add_co_u32_e32 v182, vcc, 0xc000, v180
	s_nop 1
	v_addc_co_u32_e32 v183, vcc, 0, v181, vcc
	global_load_dword v156, v[182:183], off
	v_add_co_u32_e32 v182, vcc, 0xd000, v180
	s_nop 1
	v_addc_co_u32_e32 v183, vcc, 0, v181, vcc
	global_load_dword v157, v[182:183], off offset:2048
	v_add_co_u32_e32 v182, vcc, 0xf000, v180
	s_nop 1
	v_addc_co_u32_e32 v183, vcc, 0, v181, vcc
	global_load_dword v158, v[182:183], off
	v_add_co_u32_e32 v182, vcc, 0x10000, v180
	s_nop 1
	v_addc_co_u32_e32 v183, vcc, 0, v181, vcc
	global_load_dword v159, v[182:183], off offset:2048
	v_add_co_u32_e32 v182, vcc, 0x12000, v180
	s_nop 1
	v_addc_co_u32_e32 v183, vcc, 0, v181, vcc
	global_load_dword v160, v[182:183], off
	v_add_co_u32_e32 v182, vcc, 0x13000, v180
	s_nop 1
	v_addc_co_u32_e32 v183, vcc, 0, v181, vcc
	global_load_dword v161, v[182:183], off offset:2048
	v_add_co_u32_e32 v182, vcc, 0x15000, v180
	s_nop 1
	v_addc_co_u32_e32 v183, vcc, 0, v181, vcc
	global_load_dword v162, v[182:183], off
	v_add_co_u32_e32 v182, vcc, 0x16000, v180
	s_nop 1
	v_addc_co_u32_e32 v183, vcc, 0, v181, vcc
	global_load_dword v163, v[182:183], off offset:2048
	global_load_dwordx4 v[164:167], v[14:15], off offset:-60
	global_load_dwordx4 v[168:171], v[14:15], off offset:-44
	global_load_dwordx4 v[172:175], v[14:15], off offset:-28
	global_load_dwordx4 v[176:179], v[14:15], off offset:-12
	s_waitcnt vmcnt(0)
	v_mul_f32_e32 v148, v148, v164
	v_mul_f32_e32 v149, v149, v165
	v_mul_f32_e32 v150, v150, v166
	v_mul_f32_e32 v151, v151, v167
	v_mul_f32_e32 v152, v152, v168
	v_mul_f32_e32 v153, v153, v169
	v_mul_f32_e32 v154, v154, v170
	v_mul_f32_e32 v155, v155, v171
	v_mul_f32_e32 v156, v156, v172
	v_mul_f32_e32 v157, v157, v173
	v_mul_f32_e32 v158, v158, v174
	v_mul_f32_e32 v159, v159, v175
	v_mul_f32_e32 v160, v160, v176
	v_mul_f32_e32 v161, v161, v177
	v_mul_f32_e32 v162, v162, v178
	v_mul_f32_e32 v163, v163, v179
	ds_write_b32 v24, v148
	ds_write_b32 v24, v149 offset:260
	ds_write_b32 v24, v150 offset:520
	ds_write_b32 v24, v151 offset:780
	ds_write_b32 v24, v152 offset:1040
	ds_write_b32 v24, v153 offset:1300
	ds_write_b32 v24, v154 offset:1560
	ds_write_b32 v24, v155 offset:1820
	ds_write_b32 v24, v156 offset:2080
	ds_write_b32 v24, v157 offset:2340
	ds_write_b32 v24, v158 offset:2600
	ds_write_b32 v24, v159 offset:2860
	ds_write_b32 v24, v160 offset:3120
	ds_write_b32 v24, v161 offset:3380
	ds_write_b32 v24, v162 offset:3640
	ds_write_b32 v24, v163 offset:3900
	s_add_u32 s4, s4, 0x18000
	s_addc_u32 s5, s5, 0
	v_lshl_add_u64 v[14:15], v[14:15], 0, 64
	v_add_u32_e32 v24, 0x1040, v24
	s_cmp_eq_u32 s4, 0x60000
	s_cbranch_scc0 .LBB0_302

; __device__ void transpose_cvt(const float* __restrict__ W, const float* __restrict__ gain, int K, int N, u16* WT, bool winmap, float* tile0, int tid) {
;     ...
;   for (int t = blockIdx.x * 8 + wid; t < ntiles; t += NBLK * 8) {
;     const int k0 = (t / ntn) << 6, n0 = (t % ntn) << 6;
; #pragma unroll 16
;     for (int r = 0; r < 64; ++r) { float v = W[(size_t)(k0 + r) * N + n0 + lane]; if (gain) v *= gain[k0 + r]; tile[r * 65 + lane] = v; }
;     asm volatile("s_waitcnt lgkmcnt(0)" ::: "memory");
.LBB0_340:
.LBB0_341:
	v_lshl_add_u64 v[180:181], v[12:13], 0, s[6:7]
	global_load_dword v148, v[180:181], off
	v_add_co_u32_e32 v182, vcc, 0x2000, v180
	s_nop 1
	v_addc_co_u32_e32 v183, vcc, 0, v181, vcc
	global_load_dword v149, v[182:183], off
	v_add_co_u32_e32 v182, vcc, 0x4000, v180
	s_nop 1
	v_addc_co_u32_e32 v183, vcc, 0, v181, vcc
	global_load_dword v150, v[182:183], off
	v_add_co_u32_e32 v182, vcc, 0x6000, v180
	s_nop 1
	v_addc_co_u32_e32 v183, vcc, 0, v181, vcc
	global_load_dword v151, v[182:183], off
	v_add_co_u32_e32 v182, vcc, 0x8000, v180
	s_nop 1
	v_addc_co_u32_e32 v183, vcc, 0, v181, vcc
	global_load_dword v152, v[182:183], off
	v_add_co_u32_e32 v182, vcc, 0xa000, v180
	s_nop 1
	v_addc_co_u32_e32 v183, vcc, 0, v181, vcc
	global_load_dword v153, v[182:183], off
	v_add_co_u32_e32 v182, vcc, 0xc000, v180
	s_nop 1
	v_addc_co_u32_e32 v183, vcc, 0, v181, vcc
	global_load_dword v154, v[182:183], off
	v_add_co_u32_e32 v182, vcc, 0xe000, v180
	s_nop 1
	v_addc_co_u32_e32 v183, vcc, 0, v181, vcc
	global_load_dword v155, v[182:183], off
	v_add_co_u32_e32 v182, vcc, 0x10000, v180
	s_nop 1
	v_addc_co_u32_e32 v183, vcc, 0, v181, vcc
	global_load_dword v156, v[182:183], off
	v_add_co_u32_e32 v182, vcc, 0x12000, v180
	s_nop 1
	v_addc_co_u32_e32 v183, vcc, 0, v181, vcc
	global_load_dword v157, v[182:183], off
	v_add_co_u32_e32 v182, vcc, 0x14000, v180
	s_nop 1
	v_addc_co_u32_e32 v183, vcc, 0, v181, vcc
	global_load_dword v158, v[182:183], off
	v_add_co_u32_e32 v182, vcc, 0x16000, v180
	s_nop 1
	v_addc_co_u32_e32 v183, vcc, 0, v181, vcc
	global_load_dword v159, v[182:183], off
	v_add_co_u32_e32 v182, vcc, 0x18000, v180
	s_nop 1
	v_addc_co_u32_e32 v183, vcc, 0, v181, vcc
	global_load_dword v160, v[182:183], off
	v_add_co_u32_e32 v182, vcc, 0x1a000, v180
	s_nop 1
	v_addc_co_u32_e32 v183, vcc, 0, v181, vcc
	global_load_dword v161, v[182:183], off
	v_add_co_u32_e32 v182, vcc, 0x1c000, v180
	s_nop 1
	v_addc_co_u32_e32 v183, vcc, 0, v181, vcc
	global_load_dword v162, v[182:183], off
	v_add_co_u32_e32 v182, vcc, 0x1e000, v180
	s_nop 1
	v_addc_co_u32_e32 v183, vcc, 0, v181, vcc
	global_load_dword v163, v[182:183], off
	global_load_dwordx4 v[164:167], v[14:15], off offset:-60
	global_load_dwordx4 v[168:171], v[14:15], off offset:-44
	global_load_dwordx4 v[172:175], v[14:15], off offset:-28
	global_load_dwordx4 v[176:179], v[14:15], off offset:-12
	s_waitcnt vmcnt(0)
	v_mul_f32_e32 v148, v148, v164
	v_mul_f32_e32 v149, v149, v165
	v_mul_f32_e32 v150, v150, v166
	v_mul_f32_e32 v151, v151, v167
	v_mul_f32_e32 v152, v152, v168
	v_mul_f32_e32 v153, v153, v169
	v_mul_f32_e32 v154, v154, v170
	v_mul_f32_e32 v155, v155, v171
	v_mul_f32_e32 v156, v156, v172
	v_mul_f32_e32 v157, v157, v173
	v_mul_f32_e32 v158, v158, v174
	v_mul_f32_e32 v159, v159, v175
	v_mul_f32_e32 v160, v160, v176
	v_mul_f32_e32 v161, v161, v177
	v_mul_f32_e32 v162, v162, v178
	v_mul_f32_e32 v163, v163, v179
	ds_write_b32 v24, v148
	ds_write_b32 v24, v149 offset:260
	ds_write_b32 v24, v150 offset:520
	ds_write_b32 v24, v151 offset:780
	ds_write_b32 v24, v152 offset:1040
	ds_write_b32 v24, v153 offset:1300
	ds_write_b32 v24, v154 offset:1560
	ds_write_b32 v24, v155 offset:1820
	ds_write_b32 v24, v156 offset:2080
	ds_write_b32 v24, v157 offset:2340
	ds_write_b32 v24, v158 offset:2600
	ds_write_b32 v24, v159 offset:2860
	ds_write_b32 v24, v160 offset:3120
	ds_write_b32 v24, v161 offset:3380
	ds_write_b32 v24, v162 offset:3640
	ds_write_b32 v24, v163 offset:3900
	s_add_u32 s6, s6, 0x20000
	s_addc_u32 s7, s7, 0
	v_lshl_add_u64 v[14:15], v[14:15], 0, 64
	v_add_u32_e32 v24, 0x1040, v24
	s_cmp_eq_u32 s6, 0x80000
	s_cbranch_scc0 .LBB0_341

; __device__ void transpose_cvt(const float* __restrict__ W, const float* __restrict__ gain, int K, int N, u16* WT, bool winmap, float* tile0, int tid) {
;     ...
;   for (int t = blockIdx.x * 8 + wid; t < ntiles; t += NBLK * 8) {
;     const int k0 = (t / ntn) << 6, n0 = (t % ntn) << 6;
; #pragma unroll 16
;     for (int r = 0; r < 64; ++r) { float v = W[(size_t)(k0 + r) * N + n0 + lane]; if (gain) v *= gain[k0 + r]; tile[r * 65 + lane] = v; }
;     asm volatile("s_waitcnt lgkmcnt(0)" ::: "memory");
.LBB0_402:
.LBB0_403:
	v_lshl_add_u64 v[180:181], v[12:13], 0, s[10:11]
	global_load_dword v148, v[180:181], off
	v_add_co_u32_e32 v182, vcc, 0x4000, v180
	s_nop 1
	v_addc_co_u32_e32 v183, vcc, 0, v181, vcc
	global_load_dword v149, v[182:183], off
	v_add_co_u32_e32 v182, vcc, 0x8000, v180
	s_nop 1
	v_addc_co_u32_e32 v183, vcc, 0, v181, vcc
	global_load_dword v150, v[182:183], off
	v_add_co_u32_e32 v182, vcc, 0xc000, v180
	s_nop 1
	v_addc_co_u32_e32 v183, vcc, 0, v181, vcc
	global_load_dword v151, v[182:183], off
	v_add_co_u32_e32 v182, vcc, 0x10000, v180
	s_nop 1
	v_addc_co_u32_e32 v183, vcc, 0, v181, vcc
	global_load_dword v152, v[182:183], off
	v_add_co_u32_e32 v182, vcc, 0x14000, v180
	s_nop 1
	v_addc_co_u32_e32 v183, vcc, 0, v181, vcc
	global_load_dword v153, v[182:183], off
	v_add_co_u32_e32 v182, vcc, 0x18000, v180
	s_nop 1
	v_addc_co_u32_e32 v183, vcc, 0, v181, vcc
	global_load_dword v154, v[182:183], off
	v_add_co_u32_e32 v182, vcc, 0x1c000, v180
	s_nop 1
	v_addc_co_u32_e32 v183, vcc, 0, v181, vcc
	global_load_dword v155, v[182:183], off
	v_add_co_u32_e32 v182, vcc, 0x20000, v180
	s_nop 1
	v_addc_co_u32_e32 v183, vcc, 0, v181, vcc
	global_load_dword v156, v[182:183], off
	v_add_co_u32_e32 v182, vcc, 0x24000, v180
	s_nop 1
	v_addc_co_u32_e32 v183, vcc, 0, v181, vcc
	global_load_dword v157, v[182:183], off
	v_add_co_u32_e32 v182, vcc, 0x28000, v180
	s_nop 1
	v_addc_co_u32_e32 v183, vcc, 0, v181, vcc
	global_load_dword v158, v[182:183], off
	v_add_co_u32_e32 v182, vcc, 0x2c000, v180
	s_nop 1
	v_addc_co_u32_e32 v183, vcc, 0, v181, vcc
	global_load_dword v159, v[182:183], off
	v_add_co_u32_e32 v182, vcc, 0x30000, v180
	s_nop 1
	v_addc_co_u32_e32 v183, vcc, 0, v181, vcc
	global_load_dword v160, v[182:183], off
	v_add_co_u32_e32 v182, vcc, 0x34000, v180
	s_nop 1
	v_addc_co_u32_e32 v183, vcc, 0, v181, vcc
	global_load_dword v161, v[182:183], off
	v_add_co_u32_e32 v182, vcc, 0x38000, v180
	s_nop 1
	v_addc_co_u32_e32 v183, vcc, 0, v181, vcc
	global_load_dword v162, v[182:183], off
	v_add_co_u32_e32 v182, vcc, 0x3c000, v180
	s_nop 1
	v_addc_co_u32_e32 v183, vcc, 0, v181, vcc
	global_load_dword v163, v[182:183], off
	global_load_dwordx4 v[164:167], v[14:15], off offset:-60
	global_load_dwordx4 v[168:171], v[14:15], off offset:-44
	global_load_dwordx4 v[172:175], v[14:15], off offset:-28
	global_load_dwordx4 v[176:179], v[14:15], off offset:-12
	s_waitcnt vmcnt(0)
	v_mul_f32_e32 v148, v148, v164
	v_mul_f32_e32 v149, v149, v165
	v_mul_f32_e32 v150, v150, v166
	v_mul_f32_e32 v151, v151, v167
	v_mul_f32_e32 v152, v152, v168
	v_mul_f32_e32 v153, v153, v169
	v_mul_f32_e32 v154, v154, v170
	v_mul_f32_e32 v155, v155, v171
	v_mul_f32_e32 v156, v156, v172
	v_mul_f32_e32 v157, v157, v173
	v_mul_f32_e32 v158, v158, v174
	v_mul_f32_e32 v159, v159, v175
	v_mul_f32_e32 v160, v160, v176
	v_mul_f32_e32 v161, v161, v177
	v_mul_f32_e32 v162, v162, v178
	v_mul_f32_e32 v163, v163, v179
	ds_write_b32 v23, v148
	ds_write_b32 v23, v149 offset:260
	ds_write_b32 v23, v150 offset:520
	ds_write_b32 v23, v151 offset:780
	ds_write_b32 v23, v152 offset:1040
	ds_write_b32 v23, v153 offset:1300
	ds_write_b32 v23, v154 offset:1560
	ds_write_b32 v23, v155 offset:1820
	ds_write_b32 v23, v156 offset:2080
	ds_write_b32 v23, v157 offset:2340
	ds_write_b32 v23, v158 offset:2600
	ds_write_b32 v23, v159 offset:2860
	ds_write_b32 v23, v160 offset:3120
	ds_write_b32 v23, v161 offset:3380
	ds_write_b32 v23, v162 offset:3640
	ds_write_b32 v23, v163 offset:3900
	s_add_u32 s10, s10, 0x40000
	s_addc_u32 s11, s11, 0
	v_lshl_add_u64 v[14:15], v[14:15], 0, 64
	v_add_u32_e32 v23, 0x1040, v23
	s_cmp_eq_u32 s10, 0x100000
	s_cbranch_scc0 .LBB0_403

; __device__ __forceinline__ float sigmoidf_(float x) { return __fdividef(1.f, 1.f + __expf(-x)); }
; __device__ void phase2(const Params& p, char* smem, int wave_s) {
;     ...
;       const float* r = cv + tok * 512 + lane * 8;
;       const f32x4 a = *reinterpret_cast<const f32x4*>(r), b2 = *reinterpret_cast<const f32x4*>(r + 4);
;       float x[8] = {a[0], a[1], a[2], a[3], b2[0], b2[1], b2[2], b2[3]};
;       float sm = 0.f;
; #pragma unroll
;       for (int e = 0; e < 8; ++e) sm += x[e];
;       const float mu = wave_sum(sm) * (1.f / 512.f);
;       float d2 = 0.f;
; #pragma unroll
;       for (int e = 0; e < 8; ++e) { x[e] -= mu; d2 += x[e] * x[e]; }
;       const float rs = rsqrtf(wave_sum(d2) * (1.f / 512.f) + EPS);
;       float y[8];
; #pragma unroll
;       for (int e = 0; e < 8; ++e) { const float t_ = x[e] * rs * gl8[e] + bl8[e]; y[e] = t_ * sigmoidf_(t_); }
.LBB0_580:
	ds_read_b128 v[126:129], v210 offset:63488
	ds_read_b128 v[130:133], v210 offset:63504
	s_ashr_i32 s20, s42, 6
	s_ashr_i32 s21, s20, 31
	s_lshl_b64 s[42:43], s[20:21], 11
	s_waitcnt lgkmcnt(1)
	v_add_f32_e32 v45, 0, v126
	v_add_f32_e32 v45, v127, v45
	v_add_f32_e32 v45, v128, v45
	v_add_f32_e32 v45, v129, v45
	s_waitcnt lgkmcnt(0)
	v_add_f32_e32 v45, v130, v45
	v_add_f32_e32 v45, v131, v45
	v_add_f32_e32 v45, v132, v45
	v_add_f32_e32 v45, v133, v45
	v_mov_b32_e32 v134, v45
	s_or_b32 s42, s42, s47
	s_addk_i32 s56, 0x2000
	s_waitcnt lgkmcnt(0)
	s_nop 1
	v_permlane32_swap_b32_e32 v45, v134
	v_add_f32_e32 v45, v45, v134
	ds_bpermute_b32 v134, v204, v45
	s_waitcnt lgkmcnt(0)
	v_add_f32_e32 v45, v45, v134
	s_waitcnt lgkmcnt(0)
	s_nop 1
	v_add_f32_dpp v45, v45, v45 row_mirror row_mask:0xf bank_mask:0xf
	s_waitcnt lgkmcnt(0)
	s_nop 1
	v_add_f32_dpp v45, v45, v45 row_half_mirror row_mask:0xf bank_mask:0xf
	s_waitcnt lgkmcnt(0)
	s_nop 1
	v_add_f32_dpp v45, v45, v45 quad_perm:[2,3,0,1] row_mask:0xf bank_mask:0xf
	s_waitcnt lgkmcnt(0)
	s_nop 1
	v_add_f32_dpp v45, v45, v45 quad_perm:[1,0,3,2] row_mask:0xf bank_mask:0xf
	v_fmamk_f32 v137, v45, 0xbb000000, v127
	v_mul_f32_e32 v134, 0x3b000000, v45
	v_fmamk_f32 v136, v45, 0xbb000000, v126
	v_fmamk_f32 v128, v45, 0xbb000000, v128
	v_fmac_f32_e32 v129, 0xbb000000, v45
	v_mul_f32_e32 v45, v137, v137
	v_fmac_f32_e32 v45, v136, v136
	v_pk_add_f32 v[130:131], v[130:131], v[134:135] op_sel_hi:[1,0] neg_lo:[0,1] neg_hi:[0,1]
	v_fmac_f32_e32 v45, v128, v128
	v_pk_add_f32 v[126:127], v[132:133], v[134:135] op_sel_hi:[1,0] neg_lo:[0,1] neg_hi:[0,1]
	v_pk_mul_f32 v[132:133], v[130:131], v[130:131]
	v_fmac_f32_e32 v45, v129, v129
	v_add_f32_e32 v45, v132, v45
	v_pk_mul_f32 v[134:135], v[126:127], v[126:127]
	v_add_f32_e32 v45, v133, v45
	v_add_f32_e32 v45, v134, v45
	v_add_f32_e32 v45, v135, v45
	v_mov_b32_e32 v132, v45
	s_waitcnt lgkmcnt(0)
	s_nop 1
	v_permlane32_swap_b32_e32 v45, v132
	v_add_f32_e32 v45, v45, v132
	ds_bpermute_b32 v132, v204, v45
	s_waitcnt lgkmcnt(0)
	v_add_f32_e32 v45, v45, v132
	s_waitcnt lgkmcnt(0)
	s_nop 1
	v_add_f32_dpp v45, v45, v45 row_mirror row_mask:0xf bank_mask:0xf
	s_waitcnt lgkmcnt(0)
	s_nop 1
	v_add_f32_dpp v45, v45, v45 row_half_mirror row_mask:0xf bank_mask:0xf
	s_waitcnt lgkmcnt(0)
	s_nop 1
	v_add_f32_dpp v45, v45, v45 quad_perm:[2,3,0,1] row_mask:0xf bank_mask:0xf
	s_waitcnt lgkmcnt(0)
	s_nop 1
	v_add_f32_dpp v45, v45, v45 quad_perm:[1,0,3,2] row_mask:0xf bank_mask:0xf
	v_fmamk_f32 v45, v45, 0x3b000000, v211
	v_mul_f32_e32 v132, 0x4b800000, v45
	v_cmp_gt_f32_e32 vcc, s45, v45
	s_nop 1
	v_cndmask_b32_e32 v45, v45, v132, vcc
	v_rsq_f32_e32 v45, v45
	s_nop 0
	v_mul_f32_e32 v132, 0x45800000, v45
	v_cndmask_b32_e32 v45, v45, v132, vcc
	v_mul_f32_e32 v132, v136, v45
	v_mul_f32_e32 v133, v137, v45
	s_waitcnt vmcnt(0)
	v_fma_f32 v132, v8, v132, v12
	v_fma_f32 v133, v9, v133, v13
	v_mul_f32_e32 v134, 0xbfb8aa3b, v132
	v_mul_f32_e32 v135, 0xbfb8aa3b, v133
	v_exp_f32_e32 v134, v134
	v_mul_f32_e32 v128, v128, v45
	v_exp_f32_e32 v135, v135
	v_fma_f32 v128, v10, v128, v14
	v_mul_f32_e32 v136, 0xbfb8aa3b, v128
	v_exp_f32_e32 v136, v136
	v_add_f32_e32 v134, 1.0, v134
	v_add_f32_e32 v135, 1.0, v135
	v_div_scale_f32 v138, s[20:21], v134, v134, 1.0
	v_div_scale_f32 v140, s[20:21], v135, v135, 1.0
	v_rcp_f32_e32 v145, v138
	v_rcp_f32_e32 v146, v140
	v_add_f32_e32 v136, 1.0, v136
	v_mul_f32_e32 v129, v129, v45
	v_div_scale_f32 v142, s[22:23], v136, v136, 1.0
	v_fma_f32 v129, v11, v129, v15
	v_rcp_f32_e32 v147, v142
	v_fma_f32 v149, -v138, v145, 1.0
	v_mul_f32_e32 v137, 0xbfb8aa3b, v129
	v_div_scale_f32 v139, vcc, 1.0, v134, 1.0
	v_fma_f32 v150, -v140, v146, 1.0
	v_fmac_f32_e32 v145, v149, v145
	v_exp_f32_e32 v137, v137
	v_div_scale_f32 v141, s[20:21], 1.0, v135, 1.0
	v_fmac_f32_e32 v146, v150, v146
	v_mul_f32_e32 v149, v139, v145
	v_mul_f32_e32 v150, v141, v146
	v_fma_f32 v152, -v138, v149, v139
	v_fma_f32 v151, -v142, v147, 1.0
	v_fma_f32 v153, -v140, v150, v141
	v_fmac_f32_e32 v149, v152, v145
	v_div_scale_f32 v143, s[22:23], 1.0, v136, 1.0
	v_fmac_f32_e32 v147, v151, v147
	v_fmac_f32_e32 v150, v153, v146
	v_fma_f32 v138, -v138, v149, v139
	v_add_f32_e32 v137, 1.0, v137
	v_mul_f32_e32 v151, v143, v147
	v_fma_f32 v139, -v140, v150, v141
	v_div_fmas_f32 v138, v138, v145, v149
	s_mov_b64 vcc, s[20:21]
	v_div_scale_f32 v144, s[48:49], v137, v137, 1.0
	v_fma_f32 v154, -v142, v151, v143
	v_div_fixup_f32 v134, v138, v134, 1.0
	v_div_fmas_f32 v138, v139, v146, v150
	v_rcp_f32_e32 v148, v144
	v_fmac_f32_e32 v151, v154, v147
	v_mul_f32_e32 v139, v132, v134
	v_div_fixup_f32 v132, v138, v135, 1.0
	v_mul_f32_e32 v130, v130, v45
	v_fma_f32 v140, -v142, v151, v143
	v_mul_f32_e32 v138, v133, v132
	s_mov_b64 vcc, s[22:23]
	v_fma_f32 v133, v0, v130, v4
	v_div_fmas_f32 v132, v140, v147, v151
	v_mul_f32_e32 v130, 0xbfb8aa3b, v133
	v_div_fixup_f32 v132, v132, v136, 1.0
	v_exp_f32_e32 v130, v130
	v_mul_f32_e32 v140, v128, v132
	v_fma_f32 v128, -v144, v148, 1.0
	v_fmac_f32_e32 v148, v128, v148
	v_div_scale_f32 v128, vcc, 1.0, v137, 1.0
	v_mul_f32_e32 v132, v128, v148
	v_fma_f32 v134, -v144, v132, v128
	v_add_f32_e32 v130, 1.0, v130
	v_fmac_f32_e32 v132, v134, v148
	v_div_scale_f32 v134, s[20:21], v130, v130, 1.0
	v_rcp_f32_e32 v135, v134
	v_fma_f32 v128, -v144, v132, v128
	v_mul_f32_e32 v131, v131, v45
	v_div_fmas_f32 v128, v128, v148, v132
	v_fma_f32 v136, v1, v131, v5
	v_div_fixup_f32 v128, v128, v137, 1.0
	v_mul_f32_e32 v131, 0xbfb8aa3b, v136
	v_mul_f32_e32 v141, v129, v128
	v_fma_f32 v128, -v134, v135, 1.0
	v_exp_f32_e32 v131, v131
	v_fmac_f32_e32 v135, v128, v135
	v_div_scale_f32 v128, vcc, 1.0, v130, 1.0
	v_mul_f32_e32 v129, v128, v135
	v_fma_f32 v132, -v134, v129, v128
	v_fmac_f32_e32 v129, v132, v135
	v_add_f32_e32 v137, 1.0, v131
	v_fma_f32 v128, -v134, v129, v128
	v_div_scale_f32 v142, s[20:21], v137, v137, 1.0
	v_div_fmas_f32 v128, v128, v135, v129
	v_rcp_f32_e32 v143, v142
	v_div_fixup_f32 v132, v128, v130, 1.0
	ds_read_b128 v[128:131], v212 offset:63488
	v_mul_f32_e32 v144, v133, v132
	v_fma_f32 v132, -v142, v143, 1.0
	v_fmac_f32_e32 v143, v132, v143
	ds_read_b128 v[132:135], v212 offset:63504
	s_waitcnt lgkmcnt(1)
; __device__ __forceinline__ float sigmoidf_(float x) { return __fdividef(1.f, 1.f + __expf(-x)); }
; __device__ void phase2(const Params& p, char* smem, int wave_s) {
;     ...
;       const float* r = cv + tok * 512 + lane * 8;
;       const f32x4 a = *reinterpret_cast<const f32x4*>(r), b2 = *reinterpret_cast<const f32x4*>(r + 4);
;       float x[8] = {a[0], a[1], a[2], a[3], b2[0], b2[1], b2[2], b2[3]};
;       float sm = 0.f;
; #pragma unroll
;       for (int e = 0; e < 8; ++e) sm += x[e];
;       const float mu = wave_sum(sm) * (1.f / 512.f);
;       float d2 = 0.f;
; #pragma unroll
;       for (int e = 0; e < 8; ++e) { x[e] -= mu; d2 += x[e] * x[e]; }
;       const float rs = rsqrtf(wave_sum(d2) * (1.f / 512.f) + EPS);
;       float y[8];
; #pragma unroll
;       for (int e = 0; e < 8; ++e) { const float t_ = x[e] * rs * gl8[e] + bl8[e]; y[e] = t_ * sigmoidf_(t_); }
;       __builtin_nontemporal_store(u32x4{cvtpk(y[0], y[1]), cvtpk(y[2], y[3]), cvtpk(y[4], y[5]), cvtpk(y[6], y[7])},
;                                   reinterpret_cast<u32x4*>(u2 + (base + t0 + tok) * 512 + lane * 8));
	v_add_f32_e32 v145, 0, v128
	v_add_f32_e32 v145, v129, v145
	v_add_f32_e32 v145, v130, v145
	v_add_f32_e32 v145, v131, v145
	s_waitcnt lgkmcnt(0)
	v_add_f32_e32 v145, v132, v145
	v_add_f32_e32 v145, v133, v145
	v_add_f32_e32 v145, v134, v145
	v_add_f32_e32 v145, v135, v145
	v_mov_b32_e32 v146, v145
	v_div_scale_f32 v147, vcc, 1.0, v137, 1.0
	v_mul_f32_e32 v148, v147, v143
	v_fma_f32 v149, -v142, v148, v147
	s_waitcnt lgkmcnt(0)
	s_nop 1
	v_permlane32_swap_b32_e32 v145, v146
	v_add_f32_e32 v145, v145, v146
	ds_bpermute_b32 v146, v204, v145
	v_fmac_f32_e32 v148, v149, v143
	v_mul_f32_e32 v126, v126, v45
	v_fma_f32 v142, -v142, v148, v147
	v_fma_f32 v147, v2, v126, v6
	s_waitcnt lgkmcnt(0)
	v_add_f32_e32 v126, v145, v146
	v_mul_f32_e32 v146, 0xbfb8aa3b, v147
	v_div_fmas_f32 v142, v142, v143, v148
	v_exp_f32_e32 v146, v146
	v_div_fixup_f32 v137, v142, v137, 1.0
	s_waitcnt lgkmcnt(0)
	s_nop 1
	v_add_f32_dpp v126, v126, v126 row_mirror row_mask:0xf bank_mask:0xf
	v_add_f32_e32 v145, 1.0, v146
	v_div_scale_f32 v146, s[20:21], v145, v145, 1.0
	v_rcp_f32_e32 v148, v146
	s_waitcnt lgkmcnt(0)
	s_nop 1
	v_add_f32_dpp v126, v126, v126 row_half_mirror row_mask:0xf bank_mask:0xf
	v_mul_f32_e32 v142, v136, v137
	v_fma_f32 v136, -v146, v148, 1.0
	v_fmac_f32_e32 v148, v136, v148
	v_mul_f32_e32 v45, v127, v45
	s_waitcnt lgkmcnt(0)
	s_nop 1
	v_add_f32_dpp v126, v126, v126 quad_perm:[2,3,0,1] row_mask:0xf bank_mask:0xf
	v_fma_f32 v45, v3, v45, v7
	v_div_scale_f32 v143, vcc, 1.0, v145, 1.0
	v_mul_f32_e32 v149, v143, v148
	s_waitcnt lgkmcnt(0)
	s_nop 1
	v_add_f32_dpp v136, v126, v126 quad_perm:[1,0,3,2] row_mask:0xf bank_mask:0xf
	v_fmamk_f32 v152, v136, 0xbb000000, v129
	v_fmamk_f32 v151, v136, 0xbb000000, v128
	v_mul_f32_e32 v153, v152, v152
	v_mul_f32_e32 v126, 0x3b000000, v136
	v_fmac_f32_e32 v153, v151, v151
	v_fmamk_f32 v130, v136, 0xbb000000, v130
	v_fmac_f32_e32 v153, v130, v130
	v_fmac_f32_e32 v131, 0xbb000000, v136
	v_pk_add_f32 v[136:137], v[132:133], v[126:127] op_sel_hi:[1,0] neg_lo:[0,1] neg_hi:[0,1]
	v_fmac_f32_e32 v153, v131, v131
	v_pk_mul_f32 v[128:129], v[136:137], v[136:137]
	v_fma_f32 v150, -v146, v149, v143
	v_add_f32_e32 v128, v128, v153
	v_add_f32_e32 v153, v129, v128
	v_pk_add_f32 v[128:129], v[134:135], v[126:127] op_sel_hi:[1,0] neg_lo:[0,1] neg_hi:[0,1]
	v_fmac_f32_e32 v149, v150, v148
	v_pk_mul_f32 v[132:133], v[128:129], v[128:129]
	s_nop 0
	v_add_f32_e32 v126, v132, v153
	v_add_f32_e32 v126, v133, v126
	v_mov_b32_e32 v132, v126
	v_fma_f32 v133, -v146, v149, v143
	v_div_fmas_f32 v133, v133, v148, v149
	v_div_fixup_f32 v133, v133, v145, 1.0
	v_mul_f32_e32 v143, v147, v133
	s_waitcnt lgkmcnt(0)
	s_nop 1
	v_permlane32_swap_b32_e32 v126, v132
	v_add_f32_e32 v126, v126, v132
	ds_bpermute_b32 v127, v204, v126
	v_mul_f32_e32 v132, 0xbfb8aa3b, v45
	v_exp_f32_e32 v132, v132
	s_waitcnt lgkmcnt(0)
	v_add_f32_e32 v126, v126, v127
	v_add_f32_e32 v132, 1.0, v132
	v_div_scale_f32 v134, s[20:21], v132, v132, 1.0
	v_rcp_f32_e32 v135, v134
	s_waitcnt lgkmcnt(0)
	s_nop 1
	v_add_f32_dpp v126, v126, v126 row_mirror row_mask:0xf bank_mask:0xf
	v_fma_f32 v133, -v134, v135, 1.0
	v_fmac_f32_e32 v135, v133, v135
	v_div_scale_f32 v133, vcc, 1.0, v132, 1.0
	s_waitcnt lgkmcnt(0)
	s_nop 1
	v_add_f32_dpp v126, v126, v126 row_half_mirror row_mask:0xf bank_mask:0xf
	v_mul_f32_e32 v145, v133, v135
	v_fma_f32 v146, -v134, v145, v133
	v_fmac_f32_e32 v145, v146, v135
	v_fma_f32 v133, -v134, v145, v133
	s_waitcnt lgkmcnt(0)
	s_nop 1
	v_add_f32_dpp v126, v126, v126 quad_perm:[2,3,0,1] row_mask:0xf bank_mask:0xf
	v_div_fmas_f32 v133, v133, v135, v145
	v_div_fixup_f32 v132, v133, v132, 1.0
	v_mul_f32_e32 v45, v45, v132
	s_nop 0
	v_cvt_pk_bf16_f32 v132, v139, v138
	s_waitcnt lgkmcnt(0)
	s_nop 1
	v_add_f32_dpp v126, v126, v126 quad_perm:[1,0,3,2] row_mask:0xf bank_mask:0xf
	v_fmamk_f32 v126, v126, 0x3b000000, v211
	v_mul_f32_e32 v127, 0x4b800000, v126
	v_cmp_gt_f32_e32 vcc, s45, v126
	s_nop 0
	v_cvt_pk_bf16_f32 v133, v140, v141
	s_nop 0
	v_cvt_pk_bf16_f32 v135, v143, v45
	s_nop 0
	v_cvt_pk_bf16_f32 v134, v144, v142
	s_nop 1
	v_cndmask_b32_e32 v126, v126, v127, vcc
	v_rsq_f32_e32 v126, v126
	s_nop 0
	v_mul_f32_e32 v127, 0x45800000, v126
	v_cndmask_b32_e32 v138, v126, v127, vcc
	v_mul_f32_e32 v126, v151, v138
	v_fma_f32 v139, v8, v126, v12
	v_mul_f32_e32 v126, 0xbfb8aa3b, v139
	v_exp_f32_e32 v140, v126
	v_lshl_add_u64 v[126:127], s[42:43], 0, v[116:117]
	v_lshlrev_b64 v[126:127], 10, v[126:127]
	v_lshl_add_u64 v[126:127], v[118:119], 0, v[126:127]
	v_add_f32_e32 v45, 1.0, v140
	v_div_scale_f32 v140, s[20:21], v45, v45, 1.0
	v_rcp_f32_e32 v141, v140
	global_store_dwordx4 v[126:127], v[132:135], off nt
	v_mul_f32_e32 v130, v130, v138
	v_fma_f32 v130, v10, v130, v14
	v_mul_f32_e32 v132, v152, v138
	v_fma_f32 v132, v9, v132, v13
	v_mul_f32_e32 v133, 0xbfb8aa3b, v132
	v_exp_f32_e32 v133, v133
	v_fma_f32 v126, -v140, v141, 1.0
	v_fmac_f32_e32 v141, v126, v141
	v_div_scale_f32 v126, vcc, 1.0, v45, 1.0
	v_mul_f32_e32 v127, v126, v141
	v_fma_f32 v134, -v140, v127, v126
	v_add_f32_e32 v133, 1.0, v133
	v_fmac_f32_e32 v127, v134, v141
	v_div_scale_f32 v134, s[20:21], v133, v133, 1.0
	v_rcp_f32_e32 v135, v134
	v_fma_f32 v126, -v140, v127, v126
	v_div_fmas_f32 v126, v126, v141, v127
	v_div_fixup_f32 v45, v126, v45, 1.0
	v_mul_f32_e32 v45, v139, v45
	v_fma_f32 v126, -v134, v135, 1.0
	v_mul_f32_e32 v139, 0xbfb8aa3b, v130
	v_fmac_f32_e32 v135, v126, v135
	v_div_scale_f32 v126, vcc, 1.0, v133, 1.0
	v_exp_f32_e32 v139, v139
	v_mul_f32_e32 v127, v126, v135
	v_fma_f32 v140, -v134, v127, v126
	v_fmac_f32_e32 v127, v140, v135
	v_fma_f32 v126, -v134, v127, v126
	v_add_f32_e32 v134, 1.0, v139
; __device__ __forceinline__ float sigmoidf_(float x) { return __fdividef(1.f, 1.f + __expf(-x)); }
; __device__ void phase2(const Params& p, char* smem, int wave_s) {
;     ...
;       const float* r = cv + tok * 512 + lane * 8;
;       const f32x4 a = *reinterpret_cast<const f32x4*>(r), b2 = *reinterpret_cast<const f32x4*>(r + 4);
;       float x[8] = {a[0], a[1], a[2], a[3], b2[0], b2[1], b2[2], b2[3]};
;       float sm = 0.f;
; #pragma unroll
;       for (int e = 0; e < 8; ++e) sm += x[e];
;       const float mu = wave_sum(sm) * (1.f / 512.f);
;       float d2 = 0.f;
; #pragma unroll
;       for (int e = 0; e < 8; ++e) { x[e] -= mu; d2 += x[e] * x[e]; }
;       const float rs = rsqrtf(wave_sum(d2) * (1.f / 512.f) + EPS);
;       float y[8];
; #pragma unroll
;       for (int e = 0; e < 8; ++e) { const float t_ = x[e] * rs * gl8[e] + bl8[e]; y[e] = t_ * sigmoidf_(t_); }
;       __builtin_nontemporal_store(u32x4{cvtpk(y[0], y[1]), cvtpk(y[2], y[3]), cvtpk(y[4], y[5]), cvtpk(y[6], y[7])},
;                                   reinterpret_cast<u32x4*>(u2 + (base + t0 + tok) * 512 + lane * 8));
	v_div_scale_f32 v139, s[20:21], v134, v134, 1.0
	v_rcp_f32_e32 v140, v139
	v_div_fmas_f32 v126, v126, v135, v127
	v_mul_f32_e32 v131, v131, v138
	v_div_fixup_f32 v126, v126, v133, 1.0
	v_fma_f32 v131, v11, v131, v15
	v_mul_f32_e32 v141, v132, v126
	v_fma_f32 v126, -v139, v140, 1.0
	v_mul_f32_e32 v132, 0xbfb8aa3b, v131
	v_fmac_f32_e32 v140, v126, v140
	v_div_scale_f32 v126, vcc, 1.0, v134, 1.0
	v_exp_f32_e32 v132, v132
	v_mul_f32_e32 v127, v126, v140
	v_fma_f32 v133, -v139, v127, v126
	v_fmac_f32_e32 v127, v133, v140
	v_fma_f32 v126, -v139, v127, v126
	v_add_f32_e32 v132, 1.0, v132
	v_div_scale_f32 v133, s[20:21], v132, v132, 1.0
	v_div_fmas_f32 v126, v126, v140, v127
	v_rcp_f32_e32 v135, v133
	v_div_fixup_f32 v126, v126, v134, 1.0
	v_mul_f32_e32 v139, v130, v126
	v_mul_f32_e32 v130, v136, v138
	v_fma_f32 v134, v0, v130, v4
	v_mul_f32_e32 v130, 0xbfb8aa3b, v134
	v_fma_f32 v126, -v133, v135, 1.0
	v_exp_f32_e32 v130, v130
	v_fmac_f32_e32 v135, v126, v135
	v_div_scale_f32 v126, vcc, 1.0, v132, 1.0
	v_mul_f32_e32 v127, v126, v135
	v_fma_f32 v136, -v133, v127, v126
	v_fmac_f32_e32 v127, v136, v135
	v_add_f32_e32 v130, 1.0, v130
	v_fma_f32 v126, -v133, v127, v126
	v_div_scale_f32 v133, s[20:21], v130, v130, 1.0
	v_rcp_f32_e32 v136, v133
	v_div_fmas_f32 v126, v126, v135, v127
	v_div_fixup_f32 v126, v126, v132, 1.0
	v_mul_f32_e32 v140, v131, v126
	v_fma_f32 v126, -v133, v136, 1.0
	v_fmac_f32_e32 v136, v126, v136
	v_div_scale_f32 v126, vcc, 1.0, v130, 1.0
	v_mul_f32_e32 v127, v126, v136
	v_fma_f32 v131, -v133, v127, v126
	v_fmac_f32_e32 v127, v131, v136
	v_mul_f32_e32 v131, v137, v138
	v_fma_f32 v142, v1, v131, v5
	v_mul_f32_e32 v131, 0xbfb8aa3b, v142
	v_exp_f32_e32 v131, v131
	v_fma_f32 v126, -v133, v127, v126
	v_div_fmas_f32 v126, v126, v136, v127
	v_div_fixup_f32 v126, v126, v130, 1.0
	v_add_f32_e32 v127, 1.0, v131
	v_div_scale_f32 v143, s[20:21], v127, v127, 1.0
	v_rcp_f32_e32 v144, v143
	ds_read_b128 v[130:133], v213 offset:63488
	v_mul_f32_e32 v145, v134, v126
	ds_read_b128 v[134:137], v213 offset:63504
	v_fma_f32 v126, -v143, v144, 1.0
	v_fmac_f32_e32 v144, v126, v144
	s_waitcnt lgkmcnt(1)
	v_add_f32_e32 v126, 0, v130
	v_add_f32_e32 v126, v131, v126
	v_add_f32_e32 v126, v132, v126
	v_add_f32_e32 v126, v133, v126
	s_waitcnt lgkmcnt(0)
	v_add_f32_e32 v126, v134, v126
	v_add_f32_e32 v126, v135, v126
	v_add_f32_e32 v126, v136, v126
	v_add_f32_e32 v126, v137, v126
	v_mov_b32_e32 v146, v126
	v_div_scale_f32 v147, vcc, 1.0, v127, 1.0
	v_mul_f32_e32 v148, v147, v144
	v_fma_f32 v149, -v143, v148, v147
	s_waitcnt lgkmcnt(0)
	s_nop 1
	v_permlane32_swap_b32_e32 v126, v146
	v_add_f32_e32 v126, v126, v146
	ds_bpermute_b32 v146, v204, v126
	v_fmac_f32_e32 v148, v149, v144
	v_mul_f32_e32 v128, v128, v138
	v_fma_f32 v143, -v143, v148, v147
	v_fma_f32 v128, v2, v128, v6
	s_waitcnt lgkmcnt(0)
	v_add_f32_e32 v126, v126, v146
	v_mul_f32_e32 v147, 0xbfb8aa3b, v128
	v_div_fmas_f32 v143, v143, v144, v148
	v_exp_f32_e32 v147, v147
	v_div_fixup_f32 v127, v143, v127, 1.0
	s_waitcnt lgkmcnt(0)
	s_nop 1
	v_add_f32_dpp v126, v126, v126 row_mirror row_mask:0xf bank_mask:0xf
	v_add_f32_e32 v146, 1.0, v147
	v_div_scale_f32 v147, s[20:21], v146, v146, 1.0
	v_rcp_f32_e32 v148, v147
	s_waitcnt lgkmcnt(0)
	s_nop 1
	v_add_f32_dpp v126, v126, v126 row_half_mirror row_mask:0xf bank_mask:0xf
	v_mul_f32_e32 v142, v142, v127
	v_fma_f32 v127, -v147, v148, 1.0
	v_fmac_f32_e32 v148, v127, v148
	v_mul_f32_e32 v129, v129, v138
	s_waitcnt lgkmcnt(0)
	s_nop 1
	v_add_f32_dpp v126, v126, v126 quad_perm:[2,3,0,1] row_mask:0xf bank_mask:0xf
	v_fma_f32 v129, v3, v129, v7
	v_div_scale_f32 v143, vcc, 1.0, v146, 1.0
	v_mul_f32_e32 v144, v143, v148
	s_waitcnt lgkmcnt(0)
	s_nop 1
	v_add_f32_dpp v127, v126, v126 quad_perm:[1,0,3,2] row_mask:0xf bank_mask:0xf
	v_fmamk_f32 v151, v127, 0xbb000000, v131
	v_fmamk_f32 v150, v127, 0xbb000000, v130
	v_mul_f32_e32 v152, v151, v151
	v_mul_f32_e32 v126, 0x3b000000, v127
	v_fmac_f32_e32 v152, v150, v150
	v_fmamk_f32 v132, v127, 0xbb000000, v132
	v_fmac_f32_e32 v152, v132, v132
	v_fmac_f32_e32 v133, 0xbb000000, v127
	v_pk_add_f32 v[134:135], v[134:135], v[126:127] op_sel_hi:[1,0] neg_lo:[0,1] neg_hi:[0,1]
	v_fmac_f32_e32 v152, v133, v133
	v_pk_mul_f32 v[130:131], v[134:135], v[134:135]
	v_fma_f32 v149, -v147, v144, v143
	v_add_f32_e32 v127, v130, v152
	v_add_f32_e32 v152, v131, v127
	v_pk_add_f32 v[126:127], v[136:137], v[126:127] op_sel_hi:[1,0] neg_lo:[0,1] neg_hi:[0,1]
	v_mul_f32_e32 v137, 0xbfb8aa3b, v129
	v_pk_mul_f32 v[130:131], v[126:127], v[126:127]
	v_exp_f32_e32 v137, v137
	v_add_f32_e32 v130, v130, v152
	v_add_f32_e32 v130, v131, v130
	v_mov_b32_e32 v131, v130
	v_add_f32_e32 v137, 1.0, v137
	v_fmac_f32_e32 v144, v149, v148
	v_div_scale_f32 v138, s[20:21], v137, v137, 1.0
	s_waitcnt lgkmcnt(0)
	s_nop 1
	v_permlane32_swap_b32_e32 v130, v131
	v_add_f32_e32 v130, v130, v131
	ds_bpermute_b32 v131, v204, v130
	v_fma_f32 v136, -v147, v144, v143
	v_rcp_f32_e32 v143, v138
	v_div_fmas_f32 v136, v136, v148, v144
	v_div_fixup_f32 v136, v136, v146, 1.0
	s_waitcnt lgkmcnt(0)
	v_add_f32_e32 v130, v130, v131
	v_mul_f32_e32 v136, v128, v136
	v_fma_f32 v128, -v138, v143, 1.0
	v_fmac_f32_e32 v143, v128, v143
	s_waitcnt lgkmcnt(0)
	s_nop 1
	v_add_f32_dpp v130, v130, v130 row_mirror row_mask:0xf bank_mask:0xf
	s_waitcnt lgkmcnt(0)
	s_nop 1
	v_add_f32_dpp v128, v130, v130 row_half_mirror row_mask:0xf bank_mask:0xf
	v_div_scale_f32 v131, vcc, 1.0, v137, 1.0
	v_mul_f32_e32 v144, v131, v143
	v_fma_f32 v146, -v138, v144, v131
	s_waitcnt lgkmcnt(0)
; __device__ __forceinline__ float sigmoidf_(float x) { return __fdividef(1.f, 1.f + __expf(-x)); }
; __device__ void phase2(const Params& p, char* smem, int wave_s) {
;     ...
;       const float* r = cv + tok * 512 + lane * 8;
;       const f32x4 a = *reinterpret_cast<const f32x4*>(r), b2 = *reinterpret_cast<const f32x4*>(r + 4);
;       float x[8] = {a[0], a[1], a[2], a[3], b2[0], b2[1], b2[2], b2[3]};
;       float sm = 0.f;
; #pragma unroll
;       for (int e = 0; e < 8; ++e) sm += x[e];
;       const float mu = wave_sum(sm) * (1.f / 512.f);
;       float d2 = 0.f;
; #pragma unroll
;       for (int e = 0; e < 8; ++e) { x[e] -= mu; d2 += x[e] * x[e]; }
;       const float rs = rsqrtf(wave_sum(d2) * (1.f / 512.f) + EPS);
;       float y[8];
; #pragma unroll
;       for (int e = 0; e < 8; ++e) { const float t_ = x[e] * rs * gl8[e] + bl8[e]; y[e] = t_ * sigmoidf_(t_); }
;       __builtin_nontemporal_store(u32x4{cvtpk(y[0], y[1]), cvtpk(y[2], y[3]), cvtpk(y[4], y[5]), cvtpk(y[6], y[7])},
;                                   reinterpret_cast<u32x4*>(u2 + (base + t0 + tok) * 512 + lane * 8));
	s_nop 1
	v_add_f32_dpp v128, v128, v128 quad_perm:[2,3,0,1] row_mask:0xf bank_mask:0xf
	v_fmac_f32_e32 v144, v146, v143
	v_fma_f32 v131, -v138, v144, v131
	v_div_fmas_f32 v131, v131, v143, v144
	v_div_fixup_f32 v131, v131, v137, 1.0
	s_waitcnt lgkmcnt(0)
	s_nop 1
	v_add_f32_dpp v128, v128, v128 quad_perm:[1,0,3,2] row_mask:0xf bank_mask:0xf
	v_fmamk_f32 v128, v128, 0x3b000000, v211
	v_mul_f32_e32 v130, 0x4b800000, v128
	v_cmp_gt_f32_e32 vcc, s45, v128
	v_mul_f32_e32 v131, v129, v131
	s_nop 0
	v_cvt_pk_bf16_f32 v129, v139, v140
	s_nop 0
	v_cvt_pk_bf16_f32 v131, v136, v131
	v_lshl_add_u64 v[136:137], s[42:43], 0, v[120:121]
	v_cndmask_b32_e32 v128, v128, v130, vcc
	v_rsq_f32_e32 v130, v128
	s_nop 0
	v_cvt_pk_bf16_f32 v128, v45, v141
	v_lshlrev_b64 v[136:137], 10, v[136:137]
	v_lshl_add_u64 v[136:137], v[118:119], 0, v[136:137]
	v_mul_f32_e32 v45, 0x45800000, v130
	v_cndmask_b32_e32 v45, v130, v45, vcc
	v_mul_f32_e32 v130, v150, v45
	v_fma_f32 v138, v8, v130, v12
	v_mul_f32_e32 v130, 0xbfb8aa3b, v138
	v_exp_f32_e32 v139, v130
	s_nop 0
	v_cvt_pk_bf16_f32 v130, v145, v142
	global_store_dwordx4 v[136:137], v[128:131], off nt
	v_mul_f32_e32 v132, v132, v45
	v_add_f32_e32 v139, 1.0, v139
	v_div_scale_f32 v140, s[20:21], v139, v139, 1.0
	v_rcp_f32_e32 v141, v140
	v_mul_f32_e32 v130, v151, v45
	v_fma_f32 v130, v9, v130, v13
	v_mul_f32_e32 v131, 0xbfb8aa3b, v130
	v_exp_f32_e32 v131, v131
	v_fma_f32 v128, -v140, v141, 1.0
	v_fmac_f32_e32 v141, v128, v141
	v_div_scale_f32 v128, vcc, 1.0, v139, 1.0
	v_mul_f32_e32 v129, v128, v141
	v_fma_f32 v136, -v140, v129, v128
	v_add_f32_e32 v131, 1.0, v131
	v_fmac_f32_e32 v129, v136, v141
	v_div_scale_f32 v136, s[20:21], v131, v131, 1.0
	v_rcp_f32_e32 v137, v136
	v_fma_f32 v128, -v140, v129, v128
	v_div_fmas_f32 v128, v128, v141, v129
	v_div_fixup_f32 v128, v128, v139, 1.0
	v_fma_f32 v132, v10, v132, v14
	v_mul_f32_e32 v138, v138, v128
	v_fma_f32 v128, -v136, v137, 1.0
	v_mul_f32_e32 v139, 0xbfb8aa3b, v132
	v_fmac_f32_e32 v137, v128, v137
	v_div_scale_f32 v128, vcc, 1.0, v131, 1.0
	v_exp_f32_e32 v139, v139
	v_mul_f32_e32 v129, v128, v137
	v_fma_f32 v140, -v136, v129, v128
	v_fmac_f32_e32 v129, v140, v137
	v_fma_f32 v128, -v136, v129, v128
	v_add_f32_e32 v136, 1.0, v139
	v_div_scale_f32 v139, s[20:21], v136, v136, 1.0
	v_div_fmas_f32 v128, v128, v137, v129
	v_rcp_f32_e32 v140, v139
	v_div_fixup_f32 v128, v128, v131, 1.0
	v_mul_f32_e32 v137, v130, v128
	v_mul_f32_e32 v130, v133, v45
	v_fma_f32 v130, v11, v130, v15
	v_mul_f32_e32 v131, 0xbfb8aa3b, v130
	v_fma_f32 v128, -v139, v140, 1.0
	v_exp_f32_e32 v131, v131
	v_fmac_f32_e32 v140, v128, v140
	v_div_scale_f32 v128, vcc, 1.0, v136, 1.0
	v_mul_f32_e32 v129, v128, v140
	v_fma_f32 v133, -v139, v129, v128
	v_fmac_f32_e32 v129, v133, v140
	v_add_f32_e32 v131, 1.0, v131
	v_fma_f32 v128, -v139, v129, v128
	v_div_scale_f32 v133, s[20:21], v131, v131, 1.0
	v_rcp_f32_e32 v139, v133
	v_div_fmas_f32 v128, v128, v140, v129
	v_div_fixup_f32 v128, v128, v136, 1.0
	v_mul_f32_e32 v136, v132, v128
	v_mul_f32_e32 v132, v134, v45
	v_fma_f32 v132, v0, v132, v4
	v_fma_f32 v128, -v133, v139, 1.0
	v_mul_f32_e32 v134, 0xbfb8aa3b, v132
	v_fmac_f32_e32 v139, v128, v139
	v_div_scale_f32 v128, vcc, 1.0, v131, 1.0
	v_exp_f32_e32 v134, v134
	v_mul_f32_e32 v129, v128, v139
	v_fma_f32 v140, -v133, v129, v128
	v_fmac_f32_e32 v129, v140, v139
	v_fma_f32 v128, -v133, v129, v128
	v_add_f32_e32 v133, 1.0, v134
	v_div_scale_f32 v134, s[20:21], v133, v133, 1.0
	v_rcp_f32_e32 v140, v134
	v_div_fmas_f32 v128, v128, v139, v129
	v_div_fixup_f32 v128, v128, v131, 1.0
	v_mul_f32_e32 v139, v130, v128
	v_fma_f32 v128, -v134, v140, 1.0
	v_fmac_f32_e32 v140, v128, v140
	v_div_scale_f32 v128, vcc, 1.0, v133, 1.0
	v_mul_f32_e32 v129, v128, v140
	v_fma_f32 v130, -v134, v129, v128
	v_fmac_f32_e32 v129, v130, v140
	v_mul_f32_e32 v130, v135, v45
	v_fma_f32 v141, v1, v130, v5
	v_mul_f32_e32 v130, 0xbfb8aa3b, v141
	v_exp_f32_e32 v130, v130
	v_fma_f32 v128, -v134, v129, v128
	v_div_fmas_f32 v128, v128, v140, v129
	v_div_fixup_f32 v133, v128, v133, 1.0
	v_add_f32_e32 v140, 1.0, v130
	v_div_scale_f32 v142, s[20:21], v140, v140, 1.0
	v_rcp_f32_e32 v143, v142
	ds_read_b128 v[128:131], v214 offset:63488
	v_mul_f32_e32 v144, v132, v133
	v_div_scale_f32 v147, vcc, 1.0, v140, 1.0
	v_fma_f32 v132, -v142, v143, 1.0
	v_fmac_f32_e32 v143, v132, v143
	ds_read_b128 v[132:135], v214 offset:63504
	s_waitcnt lgkmcnt(1)
	v_add_f32_e32 v145, 0, v128
	v_add_f32_e32 v145, v129, v145
	v_add_f32_e32 v145, v130, v145
	v_add_f32_e32 v145, v131, v145
	s_waitcnt lgkmcnt(0)
	v_add_f32_e32 v145, v132, v145
	v_add_f32_e32 v145, v133, v145
	v_add_f32_e32 v145, v134, v145
	v_add_f32_e32 v145, v135, v145
	v_mov_b32_e32 v146, v145
	v_mul_f32_e32 v148, v147, v143
	v_fma_f32 v149, -v142, v148, v147
	v_fmac_f32_e32 v148, v149, v143
	v_mul_f32_e32 v126, v126, v45
	s_waitcnt lgkmcnt(0)
	s_nop 1
	v_permlane32_swap_b32_e32 v145, v146
	v_add_f32_e32 v145, v145, v146
	ds_bpermute_b32 v146, v204, v145
	v_fma_f32 v142, -v142, v148, v147
	v_fma_f32 v147, v2, v126, v6
	v_div_fmas_f32 v142, v142, v143, v148
	v_div_fixup_f32 v140, v142, v140, 1.0
	s_waitcnt lgkmcnt(0)
	v_add_f32_e32 v126, v145, v146
	v_mul_f32_e32 v146, 0xbfb8aa3b, v147
	v_exp_f32_e32 v146, v146
	v_mul_f32_e32 v140, v141, v140
	v_mul_f32_e32 v45, v127, v45
	s_waitcnt lgkmcnt(0)
	s_nop 1
	v_add_f32_dpp v126, v126, v126 row_mirror row_mask:0xf bank_mask:0xf
	v_add_f32_e32 v145, 1.0, v146
	v_div_scale_f32 v146, s[20:21], v145, v145, 1.0
	v_rcp_f32_e32 v148, v146
	s_waitcnt lgkmcnt(0)
; __device__ __forceinline__ float sigmoidf_(float x) { return __fdividef(1.f, 1.f + __expf(-x)); }
; __device__ void phase2(const Params& p, char* smem, int wave_s) {
;     ...
;       const float* r = cv + tok * 512 + lane * 8;
;       const f32x4 a = *reinterpret_cast<const f32x4*>(r), b2 = *reinterpret_cast<const f32x4*>(r + 4);
;       float x[8] = {a[0], a[1], a[2], a[3], b2[0], b2[1], b2[2], b2[3]};
;       float sm = 0.f;
; #pragma unroll
;       for (int e = 0; e < 8; ++e) sm += x[e];
;       const float mu = wave_sum(sm) * (1.f / 512.f);
;       float d2 = 0.f;
; #pragma unroll
;       for (int e = 0; e < 8; ++e) { x[e] -= mu; d2 += x[e] * x[e]; }
;       const float rs = rsqrtf(wave_sum(d2) * (1.f / 512.f) + EPS);
;       float y[8];
; #pragma unroll
;       for (int e = 0; e < 8; ++e) { const float t_ = x[e] * rs * gl8[e] + bl8[e]; y[e] = t_ * sigmoidf_(t_); }
	s_nop 1
	v_add_f32_dpp v126, v126, v126 row_half_mirror row_mask:0xf bank_mask:0xf
	v_fma_f32 v45, v3, v45, v7
	v_fma_f32 v141, -v146, v148, 1.0
	v_fmac_f32_e32 v148, v141, v148
	v_div_scale_f32 v142, vcc, 1.0, v145, 1.0
	s_waitcnt lgkmcnt(0)
	s_nop 1
	v_add_f32_dpp v126, v126, v126 quad_perm:[2,3,0,1] row_mask:0xf bank_mask:0xf
	v_mul_f32_e32 v143, v142, v148
	v_fma_f32 v149, -v146, v143, v142
	v_fmac_f32_e32 v143, v149, v148
	s_waitcnt lgkmcnt(0)
	s_nop 1
	v_add_f32_dpp v141, v126, v126 quad_perm:[1,0,3,2] row_mask:0xf bank_mask:0xf
	v_fmamk_f32 v151, v141, 0xbb000000, v129
	v_fmamk_f32 v150, v141, 0xbb000000, v128
	v_mul_f32_e32 v152, v151, v151
	v_mul_f32_e32 v126, 0x3b000000, v141
	v_fmac_f32_e32 v152, v150, v150
	v_fmamk_f32 v130, v141, 0xbb000000, v130
	v_fmac_f32_e32 v152, v130, v130
	v_fmac_f32_e32 v131, 0xbb000000, v141
	v_pk_add_f32 v[132:133], v[132:133], v[126:127] op_sel_hi:[1,0] neg_lo:[0,1] neg_hi:[0,1]
	v_fmac_f32_e32 v152, v131, v131
	v_pk_mul_f32 v[128:129], v[132:133], v[132:133]
	v_pk_add_f32 v[134:135], v[134:135], v[126:127] op_sel_hi:[1,0] neg_lo:[0,1] neg_hi:[0,1]
	v_add_f32_e32 v128, v128, v152
	v_add_f32_e32 v141, v129, v128
	v_pk_mul_f32 v[128:129], v[134:135], v[134:135]
	s_nop 0
	v_add_f32_e32 v126, v128, v141
	v_add_f32_e32 v126, v129, v126
	v_mov_b32_e32 v128, v126
	v_fma_f32 v129, -v146, v143, v142
	v_div_fmas_f32 v129, v129, v148, v143
	v_div_fixup_f32 v129, v129, v145, 1.0
	v_mul_f32_e32 v129, v147, v129
	s_waitcnt lgkmcnt(0)
	s_nop 1
	v_permlane32_swap_b32_e32 v126, v128
	v_add_f32_e32 v126, v126, v128
	ds_bpermute_b32 v127, v204, v126
	v_mul_f32_e32 v128, 0xbfb8aa3b, v45
	v_exp_f32_e32 v128, v128
	s_waitcnt lgkmcnt(0)
	v_add_f32_e32 v126, v126, v127
	v_add_f32_e32 v128, 1.0, v128
	v_div_scale_f32 v141, s[20:21], v128, v128, 1.0
	v_rcp_f32_e32 v142, v141
	s_waitcnt lgkmcnt(0)
	s_nop 1
	v_add_f32_dpp v126, v126, v126 row_mirror row_mask:0xf bank_mask:0xf
	v_fma_f32 v143, -v141, v142, 1.0
	v_fmac_f32_e32 v142, v143, v142
	v_div_scale_f32 v143, vcc, 1.0, v128, 1.0
	s_waitcnt lgkmcnt(0)
	s_nop 1
	v_add_f32_dpp v126, v126, v126 row_half_mirror row_mask:0xf bank_mask:0xf
	v_mul_f32_e32 v145, v143, v142
	v_fma_f32 v146, -v141, v145, v143
	v_fmac_f32_e32 v145, v146, v142
	v_fma_f32 v141, -v141, v145, v143
	s_waitcnt lgkmcnt(0)
	s_nop 1
	v_add_f32_dpp v126, v126, v126 quad_perm:[2,3,0,1] row_mask:0xf bank_mask:0xf
	v_div_fmas_f32 v141, v141, v142, v145
	v_div_fixup_f32 v128, v141, v128, 1.0
	v_mul_f32_e32 v45, v45, v128
	s_nop 0
	v_cvt_pk_bf16_f32 v129, v129, v45
	s_waitcnt lgkmcnt(0)
; __device__ __forceinline__ float sigmoidf_(float x) { return __fdividef(1.f, 1.f + __expf(-x)); }
; __device__ void phase2(const Params& p, char* smem, int wave_s) {
;     ...
;       const float rs = rsqrtf(wave_sum(d2) * (1.f / 512.f) + EPS);
;       float y[8];
; #pragma unroll
;       for (int e = 0; e < 8; ++e) { const float t_ = x[e] * rs * gl8[e] + bl8[e]; y[e] = t_ * sigmoidf_(t_); }
;       __builtin_nontemporal_store(u32x4{cvtpk(y[0], y[1]), cvtpk(y[2], y[3]), cvtpk(y[4], y[5]), cvtpk(y[6], y[7])},
;                                   reinterpret_cast<u32x4*>(u2 + (base + t0 + tok) * 512 + lane * 8));
;     }
	s_nop 1
	v_add_f32_dpp v126, v126, v126 quad_perm:[1,0,3,2] row_mask:0xf bank_mask:0xf
	v_fmamk_f32 v126, v126, 0x3b000000, v211
	v_mul_f32_e32 v127, 0x4b800000, v126
	v_cmp_gt_f32_e32 vcc, s45, v126
	s_nop 1
	v_cndmask_b32_e32 v126, v126, v127, vcc
	v_rsq_f32_e32 v141, v126
	s_nop 0
	v_cvt_pk_bf16_f32 v126, v138, v137
	s_nop 0
	v_cvt_pk_bf16_f32 v127, v136, v139
	v_lshl_add_u64 v[136:137], s[42:43], 0, v[122:123]
	v_mul_f32_e32 v128, 0x45800000, v141
	v_cndmask_b32_e32 v138, v141, v128, vcc
	v_mul_f32_e32 v128, v150, v138
	v_fma_f32 v139, v8, v128, v12
	v_mul_f32_e32 v128, 0xbfb8aa3b, v139
	v_exp_f32_e32 v141, v128
	v_lshlrev_b64 v[136:137], 10, v[136:137]
	s_nop 0
	v_cvt_pk_bf16_f32 v128, v144, v140
	v_lshl_add_u64 v[136:137], v[118:119], 0, v[136:137]
	v_add_f32_e32 v45, 1.0, v141
	v_div_scale_f32 v140, s[20:21], v45, v45, 1.0
	v_rcp_f32_e32 v141, v140
	global_store_dwordx4 v[136:137], v[126:129], off nt
	v_mul_f32_e32 v130, v130, v138
	v_fma_f32 v130, v10, v130, v14
	v_mul_f32_e32 v128, v151, v138
	v_fma_f32 v128, v9, v128, v13
	v_mul_f32_e32 v129, 0xbfb8aa3b, v128
	v_exp_f32_e32 v129, v129
	v_fma_f32 v126, -v140, v141, 1.0
	v_fmac_f32_e32 v141, v126, v141
	v_div_scale_f32 v126, vcc, 1.0, v45, 1.0
	v_mul_f32_e32 v127, v126, v141
	v_fma_f32 v136, -v140, v127, v126
	v_add_f32_e32 v129, 1.0, v129
	v_fmac_f32_e32 v127, v136, v141
	v_div_scale_f32 v136, s[20:21], v129, v129, 1.0
	v_rcp_f32_e32 v137, v136
	v_fma_f32 v126, -v140, v127, v126
	v_div_fmas_f32 v126, v126, v141, v127
	v_div_fixup_f32 v45, v126, v45, 1.0
	v_mul_f32_e32 v45, v139, v45
	v_fma_f32 v126, -v136, v137, 1.0
	v_mul_f32_e32 v139, 0xbfb8aa3b, v130
	v_fmac_f32_e32 v137, v126, v137
	v_div_scale_f32 v126, vcc, 1.0, v129, 1.0
	v_exp_f32_e32 v139, v139
	v_mul_f32_e32 v127, v126, v137
	v_fma_f32 v140, -v136, v127, v126
	v_fmac_f32_e32 v127, v140, v137
	v_fma_f32 v126, -v136, v127, v126
	v_add_f32_e32 v136, 1.0, v139
	v_div_scale_f32 v139, s[20:21], v136, v136, 1.0
	v_div_fmas_f32 v126, v126, v137, v127
	v_rcp_f32_e32 v140, v139
	v_div_fixup_f32 v126, v126, v129, 1.0
	v_mul_f32_e32 v129, v131, v138
	v_fma_f32 v129, v11, v129, v15
	v_mul_f32_e32 v131, 0xbfb8aa3b, v129
	v_exp_f32_e32 v131, v131
	v_fma_f32 v127, -v139, v140, 1.0
	v_fmac_f32_e32 v140, v127, v140
	v_div_scale_f32 v127, vcc, 1.0, v136, 1.0
	v_mul_f32_e32 v126, v128, v126
	v_mul_f32_e32 v128, v127, v140
	v_fma_f32 v137, -v139, v128, v127
	v_add_f32_e32 v131, 1.0, v131
	v_fmac_f32_e32 v128, v137, v140
	v_div_scale_f32 v137, s[20:21], v131, v131, 1.0
	v_fma_f32 v127, -v139, v128, v127
	v_rcp_f32_e32 v139, v137
	v_mul_f32_e32 v132, v132, v138
	v_div_fmas_f32 v127, v127, v140, v128
	v_fma_f32 v132, v0, v132, v4
	v_div_fixup_f32 v127, v127, v136, 1.0
	v_mul_f32_e32 v136, 0xbfb8aa3b, v132
	v_fma_f32 v128, -v137, v139, 1.0
	v_exp_f32_e32 v136, v136
	v_fmac_f32_e32 v139, v128, v139
	v_div_scale_f32 v128, vcc, 1.0, v131, 1.0
	v_mul_f32_e32 v127, v130, v127
	v_mul_f32_e32 v130, v128, v139
	v_fma_f32 v140, -v137, v130, v128
	v_fmac_f32_e32 v130, v140, v139
	v_add_f32_e32 v136, 1.0, v136
	v_fma_f32 v128, -v137, v130, v128
	v_div_scale_f32 v137, s[20:21], v136, v136, 1.0
	v_rcp_f32_e32 v140, v137
	v_div_fmas_f32 v128, v128, v139, v130
	v_div_fixup_f32 v128, v128, v131, 1.0
	v_mul_f32_e32 v131, v133, v138
	v_fma_f32 v131, v1, v131, v5
	v_mul_f32_e32 v133, 0xbfb8aa3b, v131
	v_mul_f32_e32 v128, v129, v128
	v_fma_f32 v129, -v137, v140, 1.0
	v_exp_f32_e32 v133, v133
	v_fmac_f32_e32 v140, v129, v140
	v_div_scale_f32 v129, vcc, 1.0, v136, 1.0
	v_mul_f32_e32 v130, v129, v140
	v_fma_f32 v139, -v137, v130, v129
	v_fmac_f32_e32 v130, v139, v140
	v_add_f32_e32 v133, 1.0, v133
	v_fma_f32 v129, -v137, v130, v129
	v_div_scale_f32 v137, s[20:21], v133, v133, 1.0
	v_rcp_f32_e32 v139, v137
	v_mul_f32_e32 v134, v134, v138
	v_div_fmas_f32 v129, v129, v140, v130
	v_fma_f32 v134, v2, v134, v6
	v_div_fixup_f32 v129, v129, v136, 1.0
	v_mul_f32_e32 v136, 0xbfb8aa3b, v134
	v_fma_f32 v130, -v137, v139, 1.0
	v_exp_f32_e32 v136, v136
	v_fmac_f32_e32 v139, v130, v139
	v_div_scale_f32 v130, vcc, 1.0, v133, 1.0
	v_mul_f32_e32 v129, v132, v129
	v_mul_f32_e32 v132, v130, v139
	v_fma_f32 v140, -v137, v132, v130
	v_fmac_f32_e32 v132, v140, v139
	v_add_f32_e32 v136, 1.0, v136
	v_fma_f32 v130, -v137, v132, v130
	v_div_scale_f32 v137, s[20:21], v136, v136, 1.0
	v_rcp_f32_e32 v140, v137
	v_div_fmas_f32 v130, v130, v139, v132
	v_div_fixup_f32 v130, v130, v133, 1.0
	v_mul_f32_e32 v133, v135, v138
	v_fma_f32 v133, v3, v133, v7
	v_mul_f32_e32 v135, 0xbfb8aa3b, v133
	v_mul_f32_e32 v130, v131, v130
	v_fma_f32 v131, -v137, v140, 1.0
	v_exp_f32_e32 v135, v135
	v_fmac_f32_e32 v140, v131, v140
	v_div_scale_f32 v131, vcc, 1.0, v136, 1.0
	v_mul_f32_e32 v132, v131, v140
	v_fma_f32 v138, -v137, v132, v131
	v_fmac_f32_e32 v132, v138, v140
	v_add_f32_e32 v135, 1.0, v135
	v_fma_f32 v131, -v137, v132, v131
	v_div_scale_f32 v137, s[20:21], v135, v135, 1.0
	v_rcp_f32_e32 v138, v137
	v_div_fmas_f32 v131, v131, v140, v132
	v_div_fixup_f32 v131, v131, v136, 1.0
	v_mul_f32_e32 v131, v134, v131
	v_fma_f32 v132, -v137, v138, 1.0
	v_fmac_f32_e32 v138, v132, v138
	v_div_scale_f32 v132, vcc, 1.0, v135, 1.0
	v_mul_f32_e32 v134, v132, v138
	v_fma_f32 v136, -v137, v134, v132
	v_fmac_f32_e32 v134, v136, v138
	v_fma_f32 v132, -v137, v134, v132
	v_div_fmas_f32 v132, v132, v138, v134
	v_div_fixup_f32 v132, v132, v135, 1.0
	v_mul_f32_e32 v132, v133, v132
	s_nop 0
	v_cvt_pk_bf16_f32 v127, v127, v128
	s_nop 0
	v_cvt_pk_bf16_f32 v128, v129, v130
	s_nop 0
	v_cvt_pk_bf16_f32 v129, v131, v132
	v_lshl_add_u64 v[130:131], s[42:43], 0, v[124:125]
	v_lshlrev_b64 v[130:131], 10, v[130:131]
	v_lshl_add_u64 v[130:131], v[118:119], 0, v[130:131]
	s_andn2_b64 vcc, exec, s[40:41]
	s_mov_b32 s42, s46
	s_nop 0
	v_cvt_pk_bf16_f32 v126, v45, v126
	global_store_dwordx4 v[130:131], v[126:129], off nt
	s_cbranch_vccz .LBB0_616

; template <int EPI, int nN, int lda, int ldb, int K, int ldc>
; __device__ __forceinline__ void gemm_phase(const Params& p, const u16* __restrict__ A, const u16* __restrict__ Bt, u16* C, u16* shm, int wave_s) {
;     ...
;         f32x4 pre32[16]; u32x2 pre16a[16], pre16b[16]; unsigned pre8[16];
; #pragma unroll
;         for (int i = 0; i < 16; ++i) {
;           const size_t grow = (size_t)(brow + ai * 128 + i * 8 + wid); const int col = bcol + lane * 4;
;           if constexpr (EPI == EPI_CONVG) pre8[i] = *reinterpret_cast<const unsigned*>((const unsigned char*)p.out + grow * 2048 + 1024 + col);
;           else if constexpr (EPI == EPI_MERGE) { pre8[i] = *reinterpret_cast<const unsigned*>((const unsigned char*)p.out + grow * 2048 + col);
;                                                  pre16b[i] = *reinterpret_cast<const u32x2*>(C + grow * 1024 + col); }
;           else if constexpr (EPI == EPI_RESX) pre32[i] = *reinterpret_cast<const f32x4*>(xrow(p, (int)grow) + col);
;           else if constexpr (EPI == EPI_RESOUT) pre16a[i] = *reinterpret_cast<const u32x2*>((const u16*)(p.ws + OFF_HFN) + grow * DM + col);
;         }
.LBB0_822:
	s_or_b64 exec, exec, s[48:49]
	v_ashrrev_i32_e32 v192, 6, v176
	v_lshrrev_b32_e32 v64, 2, v176
	v_lshrrev_b32_e32 v66, 2, v207
	v_add_u32_e32 v196, s4, v192
	v_and_b32_e32 v211, 63, v207
	v_lshlrev_b32_e32 v65, 5, v192
	v_and_b32_e32 v66, 12, v66
	v_and_or_b32 v209, v64, s74, v208
	v_add_u32_e32 v64, 0xffff0000, v196
	v_ashrrev_i32_e32 v197, 31, v196
	v_cmp_gt_i32_e32 vcc, s66, v196
	v_and_or_b32 v210, v65, s73, v66
	v_lshl_or_b32 v194, v211, 2, s46
	v_cndmask_b32_e32 v65, 0, v197, vcc
	v_cndmask_b32_e32 v64, v64, v196, vcc
	v_mov_b32_e32 v212, s39
	v_mov_b32_e32 v213, s37
	v_mov_b32_e32 v214, s38
	v_mov_b32_e32 v215, s36
	v_ashrrev_i32_e32 v195, 31, v194
	v_cndmask_b32_e32 v67, v212, v213, vcc
	v_cndmask_b32_e32 v66, v214, v215, vcc
	v_lshlrev_b64 v[64:65], 12, v[64:65]
	v_lshl_add_u64 v[64:65], v[66:67], 0, v[64:65]
	v_lshlrev_b64 v[198:199], 2, v[194:195]
	v_lshl_add_u64 v[64:65], v[64:65], 0, v[198:199]
	global_load_dwordx4 v[188:191], v[64:65], off
	v_add_u32_e32 v64, 8, v196
	v_add_u32_e32 v66, 0xffff0008, v196
	v_ashrrev_i32_e32 v65, 31, v64
	v_cmp_gt_i32_e32 vcc, s66, v64
	v_lshlrev_b32_e32 v209, 10, v209
	s_ashr_i32 s43, s42, 31
	v_cndmask_b32_e32 v65, 0, v65, vcc
	v_cndmask_b32_e32 v64, v66, v64, vcc
	v_cndmask_b32_e32 v67, v212, v213, vcc
	v_cndmask_b32_e32 v66, v214, v215, vcc
	v_lshlrev_b64 v[64:65], 12, v[64:65]
	v_lshl_add_u64 v[64:65], v[66:67], 0, v[64:65]
	v_lshl_add_u64 v[64:65], v[64:65], 0, v[198:199]
	global_load_dwordx4 v[176:179], v[64:65], off
	v_add_u32_e32 v64, 16, v196
	v_add_u32_e32 v66, 0xffff0010, v196
	v_ashrrev_i32_e32 v65, 31, v64
	v_cmp_gt_i32_e32 vcc, s66, v64
	s_nop 1
	v_cndmask_b32_e32 v65, 0, v65, vcc
	v_cndmask_b32_e32 v64, v66, v64, vcc
	v_cndmask_b32_e32 v67, v212, v213, vcc
	v_cndmask_b32_e32 v66, v214, v215, vcc
	v_lshlrev_b64 v[64:65], 12, v[64:65]
	v_lshl_add_u64 v[64:65], v[66:67], 0, v[64:65]
	v_lshl_add_u64 v[64:65], v[64:65], 0, v[198:199]
	global_load_dwordx4 v[124:127], v[64:65], off
	v_add_u32_e32 v64, 24, v196
	v_add_u32_e32 v66, 0xffff0018, v196
	v_ashrrev_i32_e32 v65, 31, v64
	v_cmp_gt_i32_e32 vcc, s66, v64
	s_nop 1
	v_cndmask_b32_e32 v65, 0, v65, vcc
	v_cndmask_b32_e32 v64, v66, v64, vcc
	v_cndmask_b32_e32 v67, v212, v213, vcc
	v_cndmask_b32_e32 v66, v214, v215, vcc
	v_lshlrev_b64 v[64:65], 12, v[64:65]
	v_lshl_add_u64 v[64:65], v[66:67], 0, v[64:65]
	v_lshl_add_u64 v[64:65], v[64:65], 0, v[198:199]
	global_load_dwordx4 v[112:115], v[64:65], off
	v_add_u32_e32 v64, 32, v196
	v_add_u32_e32 v66, 0xffff0020, v196
	v_ashrrev_i32_e32 v65, 31, v64
	v_cmp_gt_i32_e32 vcc, s66, v64
	s_nop 1
	v_cndmask_b32_e32 v65, 0, v65, vcc
	v_cndmask_b32_e32 v64, v66, v64, vcc
	v_cndmask_b32_e32 v67, v212, v213, vcc
	v_cndmask_b32_e32 v66, v214, v215, vcc
	v_lshlrev_b64 v[64:65], 12, v[64:65]
	v_lshl_add_u64 v[64:65], v[66:67], 0, v[64:65]
	v_lshl_add_u64 v[64:65], v[64:65], 0, v[198:199]
	global_load_dwordx4 v[108:111], v[64:65], off
	v_add_u32_e32 v64, 40, v196
	v_add_u32_e32 v66, 0xffff0028, v196
	v_ashrrev_i32_e32 v65, 31, v64
	v_cmp_gt_i32_e32 vcc, s66, v64
	s_nop 1
	v_cndmask_b32_e32 v65, 0, v65, vcc
	v_cndmask_b32_e32 v64, v66, v64, vcc
	v_cndmask_b32_e32 v67, v212, v213, vcc
	v_cndmask_b32_e32 v66, v214, v215, vcc
	v_lshlrev_b64 v[64:65], 12, v[64:65]
	v_lshl_add_u64 v[64:65], v[66:67], 0, v[64:65]
	v_lshl_add_u64 v[64:65], v[64:65], 0, v[198:199]
	global_load_dwordx4 v[104:107], v[64:65], off
	v_add_u32_e32 v64, 48, v196
	v_add_u32_e32 v66, 0xffff0030, v196
	v_ashrrev_i32_e32 v65, 31, v64
	v_cmp_gt_i32_e32 vcc, s66, v64
	s_nop 1
	v_cndmask_b32_e32 v65, 0, v65, vcc
	v_cndmask_b32_e32 v64, v66, v64, vcc
	v_cndmask_b32_e32 v67, v212, v213, vcc
	v_cndmask_b32_e32 v66, v214, v215, vcc
	v_lshlrev_b64 v[64:65], 12, v[64:65]
	v_lshl_add_u64 v[64:65], v[66:67], 0, v[64:65]
	v_lshl_add_u64 v[64:65], v[64:65], 0, v[198:199]
	global_load_dwordx4 v[100:103], v[64:65], off
	v_add_u32_e32 v64, 56, v196
	v_add_u32_e32 v66, 0xffff0038, v196
	v_ashrrev_i32_e32 v65, 31, v64
	v_cmp_gt_i32_e32 vcc, s66, v64
	s_nop 1
	v_cndmask_b32_e32 v65, 0, v65, vcc
	v_cndmask_b32_e32 v64, v66, v64, vcc
	v_cndmask_b32_e32 v67, v212, v213, vcc
	v_cndmask_b32_e32 v66, v214, v215, vcc
	v_lshlrev_b64 v[64:65], 12, v[64:65]
	v_lshl_add_u64 v[64:65], v[66:67], 0, v[64:65]
	v_lshl_add_u64 v[64:65], v[64:65], 0, v[198:199]
	global_load_dwordx4 v[96:99], v[64:65], off
	v_add_u32_e32 v64, 64, v196
	v_add_u32_e32 v66, 0xffff0040, v196
	v_ashrrev_i32_e32 v65, 31, v64
	v_cmp_gt_i32_e32 vcc, s66, v64
	s_nop 1
	v_cndmask_b32_e32 v65, 0, v65, vcc
	v_cndmask_b32_e32 v64, v66, v64, vcc
	v_cndmask_b32_e32 v67, v212, v213, vcc
	v_cndmask_b32_e32 v66, v214, v215, vcc
	v_lshlrev_b64 v[64:65], 12, v[64:65]
	v_lshl_add_u64 v[64:65], v[66:67], 0, v[64:65]
	v_lshl_add_u64 v[64:65], v[64:65], 0, v[198:199]
	global_load_dwordx4 v[92:95], v[64:65], off
	v_add_u32_e32 v64, 0x48, v196
	v_add_u32_e32 v66, 0xffff0048, v196
	v_ashrrev_i32_e32 v65, 31, v64
	v_cmp_gt_i32_e32 vcc, s66, v64
	s_nop 1
	v_cndmask_b32_e32 v65, 0, v65, vcc
	v_cndmask_b32_e32 v64, v66, v64, vcc
	v_cndmask_b32_e32 v67, v212, v213, vcc
	v_cndmask_b32_e32 v66, v214, v215, vcc
	v_lshlrev_b64 v[64:65], 12, v[64:65]
	v_lshl_add_u64 v[64:65], v[66:67], 0, v[64:65]
	v_lshl_add_u64 v[64:65], v[64:65], 0, v[198:199]
	global_load_dwordx4 v[88:91], v[64:65], off
	v_add_u32_e32 v64, 0x50, v196
	v_add_u32_e32 v66, 0xffff0050, v196
	v_ashrrev_i32_e32 v65, 31, v64
	v_cmp_gt_i32_e32 vcc, s66, v64
	s_nop 1
	v_cndmask_b32_e32 v65, 0, v65, vcc
	v_cndmask_b32_e32 v64, v66, v64, vcc
	v_cndmask_b32_e32 v67, v212, v213, vcc
	v_cndmask_b32_e32 v66, v214, v215, vcc
	v_lshlrev_b64 v[64:65], 12, v[64:65]
; __device__ __forceinline__ u32x2 pack4(f32x4 v) { return u32x2{cvtpk(v[0], v[1]), cvtpk(v[2], v[3])}; }
; __device__ __forceinline__ f32x4 unpack4(u32x2 w) { return f32x4{bflo(w[0]), bfhi(w[0]), bflo(w[1]), bfhi(w[1])}; }
; template <int EPI, int nN, int lda, int ldb, int K, int ldc>
; __device__ __forceinline__ void gemm_phase(const Params& p, const u16* __restrict__ A, const u16* __restrict__ Bt, u16* C, u16* shm, int wave_s) {
;     ...
;         _Pragma("unroll") for (int m = 0; m < 4; ++m) _Pragma("unroll") for (int bj = 0; bj < 2; ++bj) _Pragma("unroll") for (int n = 0; n < 2; ++n)
;           stg_w32(stg, wr * 64 + m * 16 + fr, tcol + E_C, acc[ai][bj][m][n]);
;         __syncthreads();
; #pragma unroll
;         for (int i = 0; i < 16; ++i) {
;           const int r = i * 8 + wid;
;           const f32x4 v = stg_r32(stg, r, lane);
;           const size_t grow = (size_t)(brow + ai * 128 + r);
;           const int col = bcol + lane * 4;
;           if constexpr (EPI == EPI_CONVG) {
;             *reinterpret_cast<u32x2*>(C + grow * 1024 + col) = pack4(v * unpack4u8(pre8[i]));
;           } else if constexpr (EPI == EPI_MERGE) {
;             __builtin_nontemporal_store(pack4(v * unpack4u8(pre8[i]) + unpack4(pre16b[i])), reinterpret_cast<u32x2*>(C + grow * 1024 + col));
;           } else if constexpr (EPI == EPI_RESX) {
;             const f32x4 o = pre32[i] + v;
;             __builtin_nontemporal_store(pack4(o), reinterpret_cast<u32x2*>((u16*)(p.ws + OFF_HFN) + grow * DM + col));
;             const float ss = wave_sum(o[0] * o[0] + o[1] * o[1] + o[2] * o[2] + o[3] * o[3]);
;             if (lane == 0) ((float*)(p.ws + OFF_PSQ))[grow * 4 + pn] = ss;
	v_lshl_add_u64 v[64:65], v[66:67], 0, v[64:65]
	v_lshl_add_u64 v[64:65], v[64:65], 0, v[198:199]
	global_load_dwordx4 v[84:87], v[64:65], off
	v_add_u32_e32 v64, 0x58, v196
	v_add_u32_e32 v66, 0xffff0058, v196
	v_ashrrev_i32_e32 v65, 31, v64
	v_cmp_gt_i32_e32 vcc, s66, v64
	s_nop 1
	v_cndmask_b32_e32 v65, 0, v65, vcc
	v_cndmask_b32_e32 v64, v66, v64, vcc
	v_cndmask_b32_e32 v67, v212, v213, vcc
	v_cndmask_b32_e32 v66, v214, v215, vcc
	v_lshlrev_b64 v[64:65], 12, v[64:65]
	v_lshl_add_u64 v[64:65], v[66:67], 0, v[64:65]
	v_lshl_add_u64 v[64:65], v[64:65], 0, v[198:199]
	global_load_dwordx4 v[80:83], v[64:65], off
	v_add_u32_e32 v64, 0x60, v196
	v_add_u32_e32 v66, 0xffff0060, v196
	v_ashrrev_i32_e32 v65, 31, v64
	v_cmp_gt_i32_e32 vcc, s66, v64
	s_nop 1
	v_cndmask_b32_e32 v65, 0, v65, vcc
	v_cndmask_b32_e32 v64, v66, v64, vcc
	v_cndmask_b32_e32 v67, v212, v213, vcc
	v_cndmask_b32_e32 v66, v214, v215, vcc
	v_lshlrev_b64 v[64:65], 12, v[64:65]
	v_lshl_add_u64 v[64:65], v[66:67], 0, v[64:65]
	v_lshl_add_u64 v[64:65], v[64:65], 0, v[198:199]
	global_load_dwordx4 v[76:79], v[64:65], off
	v_add_u32_e32 v64, 0x68, v196
	v_add_u32_e32 v66, 0xffff0068, v196
	v_ashrrev_i32_e32 v65, 31, v64
	v_cmp_gt_i32_e32 vcc, s66, v64
	s_nop 1
	v_cndmask_b32_e32 v65, 0, v65, vcc
	v_cndmask_b32_e32 v64, v66, v64, vcc
	v_cndmask_b32_e32 v67, v212, v213, vcc
	v_cndmask_b32_e32 v66, v214, v215, vcc
	v_lshlrev_b64 v[64:65], 12, v[64:65]
	v_lshl_add_u64 v[64:65], v[66:67], 0, v[64:65]
	v_lshl_add_u64 v[64:65], v[64:65], 0, v[198:199]
	global_load_dwordx4 v[72:75], v[64:65], off
	v_add_u32_e32 v64, 0x70, v196
	v_add_u32_e32 v66, 0xffff0070, v196
	v_ashrrev_i32_e32 v65, 31, v64
	v_cmp_gt_i32_e32 vcc, s66, v64
	s_nop 1
	v_cndmask_b32_e32 v65, 0, v65, vcc
	v_cndmask_b32_e32 v64, v66, v64, vcc
	v_cndmask_b32_e32 v67, v212, v213, vcc
	v_cndmask_b32_e32 v66, v214, v215, vcc
	v_lshlrev_b64 v[64:65], 12, v[64:65]
	v_lshl_add_u64 v[64:65], v[66:67], 0, v[64:65]
	v_lshl_add_u64 v[64:65], v[64:65], 0, v[198:199]
	global_load_dwordx4 v[68:71], v[64:65], off
	v_add_u32_e32 v64, 0x78, v196
	v_cmp_gt_i32_e32 vcc, s66, v64
	v_add_u32_e32 v66, 0xffff0078, v196
	v_ashrrev_i32_e32 v65, 31, v64
	v_cndmask_b32_e32 v67, v212, v213, vcc
	v_lshrrev_b32_e32 v212, 2, v210
	v_xor_b32_e32 v210, v212, v208
	v_lshlrev_b32_e32 v210, 4, v210
	v_or_b32_e32 v213, v209, v210
	ds_write_b128 v213, v[164:167]
	v_bitop3_b32 v164, v212, v208, 4 bitop3:0x36
	v_lshlrev_b32_e32 v164, 4, v164
	v_or_b32_e32 v165, v209, v164
	ds_write_b128 v165, v[160:163]
	v_bitop3_b32 v160, v212, v208, 32 bitop3:0x36
	v_lshlrev_b32_e32 v160, 4, v160
	v_or_b32_e32 v161, v209, v160
	ds_write_b128 v161, v[184:187]
	v_bitop3_b32 v161, v212, v208, 36 bitop3:0x36
	v_lshlrev_b32_e32 v161, 4, v161
	v_cndmask_b32_e32 v65, 0, v65, vcc
	v_cndmask_b32_e32 v64, v66, v64, vcc
	v_or_b32_e32 v162, v209, v161
	v_cndmask_b32_e32 v66, v214, v215, vcc
	v_lshlrev_b64 v[64:65], 12, v[64:65]
	ds_write_b128 v162, v[180:183]
	v_bitop3_b32 v162, v212, v208, 16 bitop3:0x1e
	v_lshl_add_u64 v[64:65], v[66:67], 0, v[64:65]
	v_lshlrev_b32_e32 v162, 4, v162
	v_lshl_add_u64 v[64:65], v[64:65], 0, v[198:199]
	v_or_b32_e32 v163, 16, v208
	v_or_b32_e32 v165, v209, v162
	global_load_dwordx4 v[64:67], v[64:65], off
	ds_write_b128 v165, v[148:151] offset:16384
	v_bitop3_b32 v148, v212, v163, 4 bitop3:0x36
	v_lshlrev_b32_e32 v148, 4, v148
	v_or_b32_e32 v149, v209, v148
	ds_write_b128 v149, v[144:147] offset:16384
	v_bitop3_b32 v144, v212, v163, 32 bitop3:0x36
	v_lshlrev_b32_e32 v144, 4, v144
	v_or_b32_e32 v145, v209, v144
	ds_write_b128 v145, v[172:175] offset:16384
	v_bitop3_b32 v145, v212, v163, 36 bitop3:0x36
	v_lshlrev_b32_e32 v145, 4, v145
	v_or_b32_e32 v146, v209, v145
	ds_write_b128 v146, v[168:171] offset:16384
	v_bitop3_b32 v146, v212, v208, 32 bitop3:0x1e
	v_lshlrev_b32_e32 v146, 4, v146
	v_or_b32_e32 v149, 32, v208
	v_or_b32_e32 v147, v209, v146
	ds_write_b128 v147, v[132:135] offset:32768
	v_bitop3_b32 v132, v212, v149, 4 bitop3:0x36
	v_lshlrev_b32_e32 v135, 4, v132
	v_or_b32_e32 v132, v209, v135
	ds_write_b128 v132, v[128:131] offset:32768
	v_bitop3_b32 v128, v212, v208, 32 bitop3:0x14
	v_lshlrev_b32_e32 v147, 4, v128
	v_or_b32_e32 v128, v209, v147
	ds_write_b128 v128, v[156:159] offset:32768
	v_bitop3_b32 v128, v212, v149, 36 bitop3:0x36
	v_lshlrev_b32_e32 v149, 4, v128
	v_bitop3_b32 v129, v212, v208, 48 bitop3:0x1e
	v_or_b32_e32 v128, v209, v149
	v_lshlrev_b32_e32 v150, 4, v129
	ds_write_b128 v128, v[152:155] offset:32768
	v_or_b32_e32 v128, 48, v208
	v_or_b32_e32 v129, v209, v150
	ds_write_b128 v129, v[120:123] offset:49152
	v_bitop3_b32 v120, v212, v128, 4 bitop3:0x36
	v_lshlrev_b32_e32 v151, 4, v120
	v_or_b32_e32 v120, v209, v151
	ds_write_b128 v120, v[116:119] offset:49152
	v_bitop3_b32 v116, v212, v128, 32 bitop3:0x36
	v_lshlrev_b32_e32 v152, 4, v116
	v_or_b32_e32 v116, v209, v152
	ds_write_b128 v116, v[140:143] offset:49152
	v_bitop3_b32 v116, v212, v128, 36 bitop3:0x36
	v_lshlrev_b32_e32 v140, 4, v116
	v_or_b32_e32 v116, v209, v140
	ds_write_b128 v116, v[136:139] offset:49152
	v_xor_b32_e32 v116, v192, v207
	v_lshlrev_b32_e32 v116, 4, v116
	v_lshlrev_b32_e32 v139, 10, v192
	v_and_b32_e32 v128, 0x3f0, v116
	v_or_b32_e32 v116, v139, v128
	s_waitcnt vmcnt(0) lgkmcnt(0)
	s_barrier
	ds_read_b128 v[116:119], v116
	v_cmp_eq_u32_e32 vcc, 0, v211
	s_waitcnt lgkmcnt(0)
	v_pk_add_f32 v[116:117], v[188:189], v[116:117]
	s_nop 0
	v_mul_f32_e32 v120, v117, v117
	v_pk_add_f32 v[118:119], v[190:191], v[118:119]
	v_fmac_f32_e32 v120, v116, v116
	v_fmac_f32_e32 v120, v118, v118
	v_fmac_f32_e32 v120, v119, v119
	v_mov_b32_e32 v121, v120
	s_waitcnt lgkmcnt(0)
	s_nop 1
	v_permlane32_swap_b32_e32 v120, v121
	v_add_f32_e32 v120, v120, v121
	ds_bpermute_b32 v121, v201, v120
	s_waitcnt lgkmcnt(0)
	v_add_f32_e32 v120, v120, v121
	s_nop 1
	v_mov_b32_dpp v121, v120 row_mirror row_mask:0xf bank_mask:0xf
	s_waitcnt lgkmcnt(0)
	v_add_f32_e32 v120, v120, v121
	s_nop 1
	v_mov_b32_dpp v121, v120 row_half_mirror row_mask:0xf bank_mask:0xf
	s_waitcnt lgkmcnt(0)
	v_add_f32_e32 v122, v120, v121
	s_nop 1
	v_mov_b32_dpp v123, v122 quad_perm:[2,3,0,1] row_mask:0xf bank_mask:0xf
	s_nop 0
	v_cvt_pk_bf16_f32 v120, v116, v117
	s_nop 0
	v_cvt_pk_bf16_f32 v121, v118, v119
	v_lshlrev_b64 v[118:119], 11, v[196:197]
	v_lshl_add_u64 v[118:119], s[30:31], 0, v[118:119]
	s_waitcnt lgkmcnt(0)
	v_add_f32_e32 v116, v122, v123
	s_nop 1
	v_mov_b32_dpp v117, v116 quad_perm:[1,0,3,2] row_mask:0xf bank_mask:0xf
	v_lshl_add_u64 v[118:119], v[194:195], 1, v[118:119]
	global_store_dwordx2 v[118:119], v[120:121], off nt
	s_and_saveexec_b64 s[46:47], vcc
	s_cbranch_execz .LBB0_824
	s_waitcnt lgkmcnt(0)
	v_add_f32_e32 v118, v116, v117
	v_lshl_add_u64 v[116:117], v[196:197], 4, s[8:9]
	v_lshl_add_u64 v[116:117], s[42:43], 2, v[116:117]
	global_store_dword v[116:117], v118, off
; __device__ __forceinline__ u32x2 pack4(f32x4 v) { return u32x2{cvtpk(v[0], v[1]), cvtpk(v[2], v[3])}; }
; __device__ __forceinline__ f32x4 unpack4(u32x2 w) { return f32x4{bflo(w[0]), bfhi(w[0]), bflo(w[1]), bfhi(w[1])}; }
; template <int EPI, int nN, int lda, int ldb, int K, int ldc>
; __device__ __forceinline__ void gemm_phase(const Params& p, const u16* __restrict__ A, const u16* __restrict__ Bt, u16* C, u16* shm, int wave_s) {
;     ...
;         for (int i = 0; i < 16; ++i) {
;           const int r = i * 8 + wid;
;           const f32x4 v = stg_r32(stg, r, lane);
;           const size_t grow = (size_t)(brow + ai * 128 + r);
;           const int col = bcol + lane * 4;
;           if constexpr (EPI == EPI_CONVG) {
;             *reinterpret_cast<u32x2*>(C + grow * 1024 + col) = pack4(v * unpack4u8(pre8[i]));
;           } else if constexpr (EPI == EPI_MERGE) {
;             __builtin_nontemporal_store(pack4(v * unpack4u8(pre8[i]) + unpack4(pre16b[i])), reinterpret_cast<u32x2*>(C + grow * 1024 + col));
;           } else if constexpr (EPI == EPI_RESX) {
;             const f32x4 o = pre32[i] + v;
;             __builtin_nontemporal_store(pack4(o), reinterpret_cast<u32x2*>((u16*)(p.ws + OFF_HFN) + grow * DM + col));
;             const float ss = wave_sum(o[0] * o[0] + o[1] * o[1] + o[2] * o[2] + o[3] * o[3]);
;             if (lane == 0) ((float*)(p.ws + OFF_PSQ))[grow * 4 + pn] = ss;
.LBB0_824:
	s_or_b64 exec, exec, s[46:47]
	v_add_u32_e32 v129, 8, v192
	v_xor_b32_e32 v116, v129, v207
	v_lshlrev_b32_e32 v116, 4, v116
	v_lshlrev_b32_e32 v141, 10, v129
	v_and_b32_e32 v143, 0x3f0, v116
	v_or_b32_e32 v116, v141, v143
	s_waitcnt lgkmcnt(0)
	ds_read_b128 v[116:119], v116
	s_waitcnt lgkmcnt(0)
	v_pk_add_f32 v[120:121], v[176:177], v[116:117]
	s_nop 0
	v_mul_f32_e32 v116, v121, v121
	v_pk_add_f32 v[118:119], v[178:179], v[118:119]
	v_fmac_f32_e32 v116, v120, v120
	v_fmac_f32_e32 v116, v118, v118
	v_fmac_f32_e32 v116, v119, v119
	v_mov_b32_e32 v117, v116
	s_nop 0
	v_cvt_pk_bf16_f32 v120, v120, v121
	s_nop 0
	v_cvt_pk_bf16_f32 v121, v118, v119
	s_waitcnt lgkmcnt(0)
	s_nop 1
	v_permlane32_swap_b32_e32 v116, v117
	v_add_f32_e32 v116, v116, v117
	ds_bpermute_b32 v117, v201, v116
	s_waitcnt lgkmcnt(0)
	v_add_f32_e32 v116, v116, v117
	s_nop 1
	v_mov_b32_dpp v117, v116 row_mirror row_mask:0xf bank_mask:0xf
	s_waitcnt lgkmcnt(0)
	v_add_f32_e32 v116, v116, v117
	s_nop 1
	v_mov_b32_dpp v117, v116 row_half_mirror row_mask:0xf bank_mask:0xf
	s_waitcnt lgkmcnt(0)
	v_add_f32_e32 v122, v116, v117
	s_nop 1
	v_mov_b32_dpp v123, v122 quad_perm:[2,3,0,1] row_mask:0xf bank_mask:0xf
	v_add_u32_e32 v116, s4, v129
	v_ashrrev_i32_e32 v117, 31, v116
	s_waitcnt lgkmcnt(0)
	v_add_f32_e32 v118, v122, v123
	s_nop 1
	v_mov_b32_dpp v119, v118 quad_perm:[1,0,3,2] row_mask:0xf bank_mask:0xf
	v_lshlrev_b64 v[122:123], 11, v[116:117]
	v_lshl_add_u64 v[122:123], s[30:31], 0, v[122:123]
	v_lshl_add_u64 v[122:123], v[194:195], 1, v[122:123]
	global_store_dwordx2 v[122:123], v[120:121], off nt
	s_and_saveexec_b64 s[46:47], vcc
	s_cbranch_execz .LBB0_826
	v_lshl_add_u64 v[116:117], v[116:117], 4, s[8:9]
	s_waitcnt lgkmcnt(0)
	v_add_f32_e32 v118, v118, v119
	v_lshl_add_u64 v[116:117], s[42:43], 2, v[116:117]
	global_store_dword v[116:117], v118, off
.LBB0_826:
	s_or_b64 exec, exec, s[46:47]
	v_add_u32_e32 v130, 16, v192
	v_xor_b32_e32 v116, v130, v207
	v_lshlrev_b32_e32 v116, 4, v116
	v_lshlrev_b32_e32 v153, 10, v130
	v_and_b32_e32 v155, 0x3f0, v116
	v_or_b32_e32 v116, v153, v155
	s_waitcnt lgkmcnt(0)
	ds_read_b128 v[116:119], v116
	s_waitcnt lgkmcnt(0)
	v_pk_add_f32 v[120:121], v[124:125], v[116:117]
	s_nop 0
	v_mul_f32_e32 v116, v121, v121
	v_pk_add_f32 v[118:119], v[126:127], v[118:119]
	v_fmac_f32_e32 v116, v120, v120
	v_fmac_f32_e32 v116, v118, v118
	v_fmac_f32_e32 v116, v119, v119
	v_mov_b32_e32 v117, v116
	s_nop 0
	v_cvt_pk_bf16_f32 v120, v120, v121
	s_nop 0
	v_cvt_pk_bf16_f32 v121, v118, v119
	s_waitcnt lgkmcnt(0)
	s_nop 1
	v_permlane32_swap_b32_e32 v116, v117
	v_add_f32_e32 v116, v116, v117
	ds_bpermute_b32 v117, v201, v116
	s_waitcnt lgkmcnt(0)
	v_add_f32_e32 v116, v116, v117
	s_nop 1
	v_mov_b32_dpp v117, v116 row_mirror row_mask:0xf bank_mask:0xf
	s_waitcnt lgkmcnt(0)
	v_add_f32_e32 v116, v116, v117
	s_nop 1
	v_mov_b32_dpp v117, v116 row_half_mirror row_mask:0xf bank_mask:0xf
	s_waitcnt lgkmcnt(0)
	v_add_f32_e32 v122, v116, v117
	s_nop 1
	v_mov_b32_dpp v123, v122 quad_perm:[2,3,0,1] row_mask:0xf bank_mask:0xf
	v_add_u32_e32 v116, s4, v130
	v_ashrrev_i32_e32 v117, 31, v116
	s_waitcnt lgkmcnt(0)
	v_add_f32_e32 v118, v122, v123
	s_nop 1
	v_mov_b32_dpp v119, v118 quad_perm:[1,0,3,2] row_mask:0xf bank_mask:0xf
	v_lshlrev_b64 v[122:123], 11, v[116:117]
	v_lshl_add_u64 v[122:123], s[30:31], 0, v[122:123]
	v_lshl_add_u64 v[122:123], v[194:195], 1, v[122:123]
	global_store_dwordx2 v[122:123], v[120:121], off nt
	s_and_saveexec_b64 s[46:47], vcc
	s_cbranch_execz .LBB0_828
	v_lshl_add_u64 v[116:117], v[116:117], 4, s[8:9]
	s_waitcnt lgkmcnt(0)
	v_add_f32_e32 v118, v118, v119
	v_lshl_add_u64 v[116:117], s[42:43], 2, v[116:117]
	global_store_dword v[116:117], v118, off
.LBB0_828:
	s_or_b64 exec, exec, s[46:47]
	v_add_u32_e32 v131, 24, v192
	v_xor_b32_e32 v116, v131, v207
	v_lshlrev_b32_e32 v116, 4, v116
	v_lshlrev_b32_e32 v156, 10, v131
	v_and_b32_e32 v158, 0x3f0, v116
	v_or_b32_e32 v116, v156, v158
	s_waitcnt lgkmcnt(0)
	ds_read_b128 v[116:119], v116
	s_waitcnt lgkmcnt(0)
	v_pk_add_f32 v[116:117], v[112:113], v[116:117]
	s_nop 0
	v_mul_f32_e32 v112, v117, v117
	v_pk_add_f32 v[114:115], v[114:115], v[118:119]
	v_fmac_f32_e32 v112, v116, v116
	v_fmac_f32_e32 v112, v114, v114
	v_fmac_f32_e32 v112, v115, v115
	v_mov_b32_e32 v113, v112
	s_nop 0
	v_cvt_pk_bf16_f32 v116, v116, v117
	s_nop 0
	v_cvt_pk_bf16_f32 v117, v114, v115
	s_waitcnt lgkmcnt(0)
	s_nop 1
	v_permlane32_swap_b32_e32 v112, v113
	v_add_f32_e32 v112, v112, v113
	ds_bpermute_b32 v113, v201, v112
	s_waitcnt lgkmcnt(0)
	v_add_f32_e32 v112, v112, v113
	s_nop 1
	v_mov_b32_dpp v113, v112 row_mirror row_mask:0xf bank_mask:0xf
	s_waitcnt lgkmcnt(0)
	v_add_f32_e32 v112, v112, v113
	s_nop 1
	v_mov_b32_dpp v113, v112 row_half_mirror row_mask:0xf bank_mask:0xf
	s_waitcnt lgkmcnt(0)
	v_add_f32_e32 v118, v112, v113
	s_nop 1
	v_mov_b32_dpp v119, v118 quad_perm:[2,3,0,1] row_mask:0xf bank_mask:0xf
	v_add_u32_e32 v112, s4, v131
	v_ashrrev_i32_e32 v113, 31, v112
	s_waitcnt lgkmcnt(0)
	v_add_f32_e32 v114, v118, v119
	s_nop 1
	v_mov_b32_dpp v115, v114 quad_perm:[1,0,3,2] row_mask:0xf bank_mask:0xf
	v_lshlrev_b64 v[118:119], 11, v[112:113]
	v_lshl_add_u64 v[118:119], s[30:31], 0, v[118:119]
	v_lshl_add_u64 v[118:119], v[194:195], 1, v[118:119]
	global_store_dwordx2 v[118:119], v[116:117], off nt
	s_and_saveexec_b64 s[46:47], vcc
	s_cbranch_execz .LBB0_830
	v_lshl_add_u64 v[112:113], v[112:113], 4, s[8:9]
	s_waitcnt lgkmcnt(0)
	v_add_f32_e32 v114, v114, v115
	v_lshl_add_u64 v[112:113], s[42:43], 2, v[112:113]
	global_store_dword v[112:113], v114, off
; __device__ __forceinline__ u32x2 pack4(f32x4 v) { return u32x2{cvtpk(v[0], v[1]), cvtpk(v[2], v[3])}; }
; __device__ __forceinline__ f32x4 unpack4(u32x2 w) { return f32x4{bflo(w[0]), bfhi(w[0]), bflo(w[1]), bfhi(w[1])}; }
; template <int EPI, int nN, int lda, int ldb, int K, int ldc>
; __device__ __forceinline__ void gemm_phase(const Params& p, const u16* __restrict__ A, const u16* __restrict__ Bt, u16* C, u16* shm, int wave_s) {
;     ...
;         for (int i = 0; i < 16; ++i) {
;           const int r = i * 8 + wid;
;           const f32x4 v = stg_r32(stg, r, lane);
;           const size_t grow = (size_t)(brow + ai * 128 + r);
;           const int col = bcol + lane * 4;
;           if constexpr (EPI == EPI_CONVG) {
;             *reinterpret_cast<u32x2*>(C + grow * 1024 + col) = pack4(v * unpack4u8(pre8[i]));
;           } else if constexpr (EPI == EPI_MERGE) {
;             __builtin_nontemporal_store(pack4(v * unpack4u8(pre8[i]) + unpack4(pre16b[i])), reinterpret_cast<u32x2*>(C + grow * 1024 + col));
;           } else if constexpr (EPI == EPI_RESX) {
;             const f32x4 o = pre32[i] + v;
;             __builtin_nontemporal_store(pack4(o), reinterpret_cast<u32x2*>((u16*)(p.ws + OFF_HFN) + grow * DM + col));
;             const float ss = wave_sum(o[0] * o[0] + o[1] * o[1] + o[2] * o[2] + o[3] * o[3]);
;             if (lane == 0) ((float*)(p.ws + OFF_PSQ))[grow * 4 + pn] = ss;
.LBB0_830:
	s_or_b64 exec, exec, s[46:47]
	v_add_u32_e32 v132, 32, v192
	v_xor_b32_e32 v112, v132, v207
	v_lshlrev_b32_e32 v112, 4, v112
	v_lshlrev_b32_e32 v159, 10, v132
	v_and_b32_e32 v165, 0x3f0, v112
	v_or_b32_e32 v112, v159, v165
	s_waitcnt lgkmcnt(0)
	ds_read_b128 v[112:115], v112
	s_waitcnt lgkmcnt(0)
	v_pk_add_f32 v[112:113], v[108:109], v[112:113]
	s_nop 0
	v_mul_f32_e32 v108, v113, v113
	v_pk_add_f32 v[110:111], v[110:111], v[114:115]
	v_fmac_f32_e32 v108, v112, v112
	v_fmac_f32_e32 v108, v110, v110
	v_fmac_f32_e32 v108, v111, v111
	v_mov_b32_e32 v109, v108
	s_nop 0
	v_cvt_pk_bf16_f32 v112, v112, v113
	s_nop 0
	v_cvt_pk_bf16_f32 v113, v110, v111
	s_waitcnt lgkmcnt(0)
	s_nop 1
	v_permlane32_swap_b32_e32 v108, v109
	v_add_f32_e32 v108, v108, v109
	ds_bpermute_b32 v109, v201, v108
	s_waitcnt lgkmcnt(0)
	v_add_f32_e32 v108, v108, v109
	s_nop 1
	v_mov_b32_dpp v109, v108 row_mirror row_mask:0xf bank_mask:0xf
	s_waitcnt lgkmcnt(0)
	v_add_f32_e32 v108, v108, v109
	s_nop 1
	v_mov_b32_dpp v109, v108 row_half_mirror row_mask:0xf bank_mask:0xf
	s_waitcnt lgkmcnt(0)
	v_add_f32_e32 v114, v108, v109
	s_nop 1
	v_mov_b32_dpp v115, v114 quad_perm:[2,3,0,1] row_mask:0xf bank_mask:0xf
	v_add_u32_e32 v108, s4, v132
	v_ashrrev_i32_e32 v109, 31, v108
	s_waitcnt lgkmcnt(0)
	v_add_f32_e32 v110, v114, v115
	s_nop 1
	v_mov_b32_dpp v111, v110 quad_perm:[1,0,3,2] row_mask:0xf bank_mask:0xf
	v_lshlrev_b64 v[114:115], 11, v[108:109]
	v_lshl_add_u64 v[114:115], s[30:31], 0, v[114:115]
	v_lshl_add_u64 v[114:115], v[194:195], 1, v[114:115]
	global_store_dwordx2 v[114:115], v[112:113], off nt
	s_and_saveexec_b64 s[46:47], vcc
	s_cbranch_execz .LBB0_832
	v_lshl_add_u64 v[108:109], v[108:109], 4, s[8:9]
	s_waitcnt lgkmcnt(0)
	v_add_f32_e32 v110, v110, v111
	v_lshl_add_u64 v[108:109], s[42:43], 2, v[108:109]
	global_store_dword v[108:109], v110, off
.LBB0_832:
	s_or_b64 exec, exec, s[46:47]
	v_add_u32_e32 v133, 40, v192
	v_xor_b32_e32 v108, v133, v207
	v_lshlrev_b32_e32 v108, 4, v108
	v_lshlrev_b32_e32 v166, 10, v133
	v_and_b32_e32 v168, 0x3f0, v108
	v_or_b32_e32 v108, v166, v168
	s_waitcnt lgkmcnt(0)
	ds_read_b128 v[108:111], v108
	s_waitcnt lgkmcnt(0)
	v_pk_add_f32 v[108:109], v[104:105], v[108:109]
	s_nop 0
	v_mul_f32_e32 v104, v109, v109
	v_pk_add_f32 v[106:107], v[106:107], v[110:111]
	v_fmac_f32_e32 v104, v108, v108
	v_fmac_f32_e32 v104, v106, v106
	v_fmac_f32_e32 v104, v107, v107
	v_mov_b32_e32 v105, v104
	s_nop 0
	v_cvt_pk_bf16_f32 v108, v108, v109
	s_nop 0
	v_cvt_pk_bf16_f32 v109, v106, v107
	s_waitcnt lgkmcnt(0)
	s_nop 1
	v_permlane32_swap_b32_e32 v104, v105
	v_add_f32_e32 v104, v104, v105
	ds_bpermute_b32 v105, v201, v104
	s_waitcnt lgkmcnt(0)
	v_add_f32_e32 v104, v104, v105
	s_nop 1
	v_mov_b32_dpp v105, v104 row_mirror row_mask:0xf bank_mask:0xf
	s_waitcnt lgkmcnt(0)
	v_add_f32_e32 v104, v104, v105
	s_nop 1
	v_mov_b32_dpp v105, v104 row_half_mirror row_mask:0xf bank_mask:0xf
	s_waitcnt lgkmcnt(0)
	v_add_f32_e32 v110, v104, v105
	s_nop 1
	v_mov_b32_dpp v111, v110 quad_perm:[2,3,0,1] row_mask:0xf bank_mask:0xf
	v_add_u32_e32 v104, s4, v133
	v_ashrrev_i32_e32 v105, 31, v104
	s_waitcnt lgkmcnt(0)
	v_add_f32_e32 v106, v110, v111
	s_nop 1
	v_mov_b32_dpp v107, v106 quad_perm:[1,0,3,2] row_mask:0xf bank_mask:0xf
	v_lshlrev_b64 v[110:111], 11, v[104:105]
	v_lshl_add_u64 v[110:111], s[30:31], 0, v[110:111]
	v_lshl_add_u64 v[110:111], v[194:195], 1, v[110:111]
	global_store_dwordx2 v[110:111], v[108:109], off nt
	s_and_saveexec_b64 s[46:47], vcc
	s_cbranch_execz .LBB0_834
	v_lshl_add_u64 v[104:105], v[104:105], 4, s[8:9]
	s_waitcnt lgkmcnt(0)
	v_add_f32_e32 v106, v106, v107
	v_lshl_add_u64 v[104:105], s[42:43], 2, v[104:105]
	global_store_dword v[104:105], v106, off
.LBB0_834:
	s_or_b64 exec, exec, s[46:47]
	v_add_u32_e32 v134, 48, v192
	v_xor_b32_e32 v104, v134, v207
	v_lshlrev_b32_e32 v104, 4, v104
	v_lshlrev_b32_e32 v169, 10, v134
	v_and_b32_e32 v171, 0x3f0, v104
	v_or_b32_e32 v104, v169, v171
	s_waitcnt lgkmcnt(0)
	ds_read_b128 v[104:107], v104
	s_waitcnt lgkmcnt(0)
	v_pk_add_f32 v[104:105], v[100:101], v[104:105]
	s_nop 0
	v_mul_f32_e32 v100, v105, v105
	v_pk_add_f32 v[102:103], v[102:103], v[106:107]
	v_fmac_f32_e32 v100, v104, v104
	v_fmac_f32_e32 v100, v102, v102
	v_fmac_f32_e32 v100, v103, v103
	v_mov_b32_e32 v101, v100
	s_nop 0
	v_cvt_pk_bf16_f32 v104, v104, v105
	s_nop 0
	v_cvt_pk_bf16_f32 v105, v102, v103
	s_waitcnt lgkmcnt(0)
	s_nop 1
	v_permlane32_swap_b32_e32 v100, v101
	v_add_f32_e32 v100, v100, v101
	ds_bpermute_b32 v101, v201, v100
	s_waitcnt lgkmcnt(0)
	v_add_f32_e32 v100, v100, v101
	s_nop 1
	v_mov_b32_dpp v101, v100 row_mirror row_mask:0xf bank_mask:0xf
	s_waitcnt lgkmcnt(0)
	v_add_f32_e32 v100, v100, v101
	s_nop 1
	v_mov_b32_dpp v101, v100 row_half_mirror row_mask:0xf bank_mask:0xf
	s_waitcnt lgkmcnt(0)
	v_add_f32_e32 v106, v100, v101
	s_nop 1
	v_mov_b32_dpp v107, v106 quad_perm:[2,3,0,1] row_mask:0xf bank_mask:0xf
	v_add_u32_e32 v100, s4, v134
	v_ashrrev_i32_e32 v101, 31, v100
	s_waitcnt lgkmcnt(0)
	v_add_f32_e32 v102, v106, v107
	s_nop 1
	v_mov_b32_dpp v103, v102 quad_perm:[1,0,3,2] row_mask:0xf bank_mask:0xf
	v_lshlrev_b64 v[106:107], 11, v[100:101]
	v_lshl_add_u64 v[106:107], s[30:31], 0, v[106:107]
	v_lshl_add_u64 v[106:107], v[194:195], 1, v[106:107]
	global_store_dwordx2 v[106:107], v[104:105], off nt
	s_and_saveexec_b64 s[46:47], vcc
	s_cbranch_execz .LBB0_836
	v_lshl_add_u64 v[100:101], v[100:101], 4, s[8:9]
	s_waitcnt lgkmcnt(0)
	v_add_f32_e32 v102, v102, v103
	v_lshl_add_u64 v[100:101], s[42:43], 2, v[100:101]
	global_store_dword v[100:101], v102, off
; __device__ __forceinline__ u32x2 pack4(f32x4 v) { return u32x2{cvtpk(v[0], v[1]), cvtpk(v[2], v[3])}; }
; __device__ __forceinline__ f32x4 unpack4(u32x2 w) { return f32x4{bflo(w[0]), bfhi(w[0]), bflo(w[1]), bfhi(w[1])}; }
; template <int EPI, int nN, int lda, int ldb, int K, int ldc>
; __device__ __forceinline__ void gemm_phase(const Params& p, const u16* __restrict__ A, const u16* __restrict__ Bt, u16* C, u16* shm, int wave_s) {
;     ...
;         for (int i = 0; i < 16; ++i) {
;           const int r = i * 8 + wid;
;           const f32x4 v = stg_r32(stg, r, lane);
;           const size_t grow = (size_t)(brow + ai * 128 + r);
;           const int col = bcol + lane * 4;
;           if constexpr (EPI == EPI_CONVG) {
;             *reinterpret_cast<u32x2*>(C + grow * 1024 + col) = pack4(v * unpack4u8(pre8[i]));
;           } else if constexpr (EPI == EPI_MERGE) {
;             __builtin_nontemporal_store(pack4(v * unpack4u8(pre8[i]) + unpack4(pre16b[i])), reinterpret_cast<u32x2*>(C + grow * 1024 + col));
;           } else if constexpr (EPI == EPI_RESX) {
;             const f32x4 o = pre32[i] + v;
;             __builtin_nontemporal_store(pack4(o), reinterpret_cast<u32x2*>((u16*)(p.ws + OFF_HFN) + grow * DM + col));
;             const float ss = wave_sum(o[0] * o[0] + o[1] * o[1] + o[2] * o[2] + o[3] * o[3]);
;             if (lane == 0) ((float*)(p.ws + OFF_PSQ))[grow * 4 + pn] = ss;
.LBB0_836:
	s_or_b64 exec, exec, s[46:47]
	v_add_u32_e32 v136, 56, v192
	v_xor_b32_e32 v100, v136, v207
	v_lshlrev_b32_e32 v100, 4, v100
	v_lshlrev_b32_e32 v172, 10, v136
	v_and_b32_e32 v173, 0x3f0, v100
	v_or_b32_e32 v100, v172, v173
	s_waitcnt lgkmcnt(0)
	ds_read_b128 v[100:103], v100
	s_waitcnt lgkmcnt(0)
	v_pk_add_f32 v[100:101], v[96:97], v[100:101]
	s_nop 0
	v_mul_f32_e32 v96, v101, v101
	v_pk_add_f32 v[98:99], v[98:99], v[102:103]
	v_fmac_f32_e32 v96, v100, v100
	v_fmac_f32_e32 v96, v98, v98
	v_fmac_f32_e32 v96, v99, v99
	v_mov_b32_e32 v97, v96
	s_nop 0
	v_cvt_pk_bf16_f32 v100, v100, v101
	s_nop 0
	v_cvt_pk_bf16_f32 v101, v98, v99
	s_waitcnt lgkmcnt(0)
	s_nop 1
	v_permlane32_swap_b32_e32 v96, v97
	v_add_f32_e32 v96, v96, v97
	ds_bpermute_b32 v97, v201, v96
	s_waitcnt lgkmcnt(0)
	v_add_f32_e32 v96, v96, v97
	s_nop 1
	v_mov_b32_dpp v97, v96 row_mirror row_mask:0xf bank_mask:0xf
	s_waitcnt lgkmcnt(0)
	v_add_f32_e32 v96, v96, v97
	s_nop 1
	v_mov_b32_dpp v97, v96 row_half_mirror row_mask:0xf bank_mask:0xf
	s_waitcnt lgkmcnt(0)
	v_add_f32_e32 v102, v96, v97
	s_nop 1
	v_mov_b32_dpp v103, v102 quad_perm:[2,3,0,1] row_mask:0xf bank_mask:0xf
	v_add_u32_e32 v96, s4, v136
	v_ashrrev_i32_e32 v97, 31, v96
	s_waitcnt lgkmcnt(0)
	v_add_f32_e32 v98, v102, v103
	s_nop 1
	v_mov_b32_dpp v99, v98 quad_perm:[1,0,3,2] row_mask:0xf bank_mask:0xf
	v_lshlrev_b64 v[102:103], 11, v[96:97]
	v_lshl_add_u64 v[102:103], s[30:31], 0, v[102:103]
	v_lshl_add_u64 v[102:103], v[194:195], 1, v[102:103]
	global_store_dwordx2 v[102:103], v[100:101], off nt
	s_and_saveexec_b64 s[46:47], vcc
	s_cbranch_execz .LBB0_838
	v_lshl_add_u64 v[96:97], v[96:97], 4, s[8:9]
	s_waitcnt lgkmcnt(0)
	v_add_f32_e32 v98, v98, v99
	v_lshl_add_u64 v[96:97], s[42:43], 2, v[96:97]
	global_store_dword v[96:97], v98, off
.LBB0_838:
	s_or_b64 exec, exec, s[46:47]
	v_add_u32_e32 v137, 64, v192
	v_lshlrev_b32_e32 v174, 10, v137
	v_or_b32_e32 v96, v174, v128
	s_waitcnt lgkmcnt(0)
	ds_read_b128 v[96:99], v96
	s_waitcnt lgkmcnt(0)
	v_pk_add_f32 v[96:97], v[92:93], v[96:97]
	s_nop 0
	v_mul_f32_e32 v92, v97, v97
	v_pk_add_f32 v[94:95], v[94:95], v[98:99]
	v_fmac_f32_e32 v92, v96, v96
	v_fmac_f32_e32 v92, v94, v94
	v_fmac_f32_e32 v92, v95, v95
	v_mov_b32_e32 v93, v92
	s_nop 0
	v_cvt_pk_bf16_f32 v96, v96, v97
	s_nop 0
	v_cvt_pk_bf16_f32 v97, v94, v95
	s_waitcnt lgkmcnt(0)
	s_nop 1
	v_permlane32_swap_b32_e32 v92, v93
	v_add_f32_e32 v92, v92, v93
	ds_bpermute_b32 v93, v201, v92
	s_waitcnt lgkmcnt(0)
	v_add_f32_e32 v92, v92, v93
	s_nop 1
	v_mov_b32_dpp v93, v92 row_mirror row_mask:0xf bank_mask:0xf
	s_waitcnt lgkmcnt(0)
	v_add_f32_e32 v92, v92, v93
	s_nop 1
	v_mov_b32_dpp v93, v92 row_half_mirror row_mask:0xf bank_mask:0xf
	s_waitcnt lgkmcnt(0)
	v_add_f32_e32 v98, v92, v93
	s_nop 1
	v_mov_b32_dpp v99, v98 quad_perm:[2,3,0,1] row_mask:0xf bank_mask:0xf
	v_add_u32_e32 v92, s4, v137
	v_ashrrev_i32_e32 v93, 31, v92
	s_waitcnt lgkmcnt(0)
	v_add_f32_e32 v94, v98, v99
	s_nop 1
	v_mov_b32_dpp v95, v94 quad_perm:[1,0,3,2] row_mask:0xf bank_mask:0xf
	v_lshlrev_b64 v[98:99], 11, v[92:93]
	v_lshl_add_u64 v[98:99], s[30:31], 0, v[98:99]
	v_lshl_add_u64 v[98:99], v[194:195], 1, v[98:99]
	global_store_dwordx2 v[98:99], v[96:97], off nt
	s_and_saveexec_b64 s[46:47], vcc
	s_cbranch_execz .LBB0_840
	v_lshl_add_u64 v[92:93], v[92:93], 4, s[8:9]
	s_waitcnt lgkmcnt(0)
	v_add_f32_e32 v94, v94, v95
	v_lshl_add_u64 v[92:93], s[42:43], 2, v[92:93]
	global_store_dword v[92:93], v94, off
.LBB0_840:
	s_or_b64 exec, exec, s[46:47]
	v_add_u32_e32 v138, 0x48, v192
	v_xor_b32_e32 v92, v138, v207
	v_lshlrev_b32_e32 v92, 4, v92
	v_lshlrev_b32_e32 v175, 10, v138
	v_and_b32_e32 v176, 0x3f0, v92
	v_or_b32_e32 v92, v175, v176
	s_waitcnt lgkmcnt(0)
	ds_read_b128 v[92:95], v92
	s_waitcnt lgkmcnt(0)
	v_pk_add_f32 v[92:93], v[88:89], v[92:93]
	s_nop 0
	v_mul_f32_e32 v88, v93, v93
	v_pk_add_f32 v[90:91], v[90:91], v[94:95]
	v_fmac_f32_e32 v88, v92, v92
	v_fmac_f32_e32 v88, v90, v90
	v_fmac_f32_e32 v88, v91, v91
	v_mov_b32_e32 v89, v88
	s_nop 0
	v_cvt_pk_bf16_f32 v92, v92, v93
	s_nop 0
	v_cvt_pk_bf16_f32 v93, v90, v91
	s_waitcnt lgkmcnt(0)
	s_nop 1
	v_permlane32_swap_b32_e32 v88, v89
	v_add_f32_e32 v88, v88, v89
	ds_bpermute_b32 v89, v201, v88
	s_waitcnt lgkmcnt(0)
	v_add_f32_e32 v88, v88, v89
	s_nop 1
	v_mov_b32_dpp v89, v88 row_mirror row_mask:0xf bank_mask:0xf
	s_waitcnt lgkmcnt(0)
	v_add_f32_e32 v88, v88, v89
	s_nop 1
	v_mov_b32_dpp v89, v88 row_half_mirror row_mask:0xf bank_mask:0xf
	s_waitcnt lgkmcnt(0)
	v_add_f32_e32 v94, v88, v89
	s_nop 1
	v_mov_b32_dpp v95, v94 quad_perm:[2,3,0,1] row_mask:0xf bank_mask:0xf
	v_add_u32_e32 v88, s4, v138
	v_ashrrev_i32_e32 v89, 31, v88
	s_waitcnt lgkmcnt(0)
	v_add_f32_e32 v90, v94, v95
	s_nop 1
	v_mov_b32_dpp v91, v90 quad_perm:[1,0,3,2] row_mask:0xf bank_mask:0xf
	v_lshlrev_b64 v[94:95], 11, v[88:89]
	v_lshl_add_u64 v[94:95], s[30:31], 0, v[94:95]
	v_lshl_add_u64 v[94:95], v[194:195], 1, v[94:95]
	global_store_dwordx2 v[94:95], v[92:93], off nt
	s_and_saveexec_b64 s[46:47], vcc
	s_cbranch_execz .LBB0_842
	v_lshl_add_u64 v[88:89], v[88:89], 4, s[8:9]
	s_waitcnt lgkmcnt(0)
	v_add_f32_e32 v90, v90, v91
	v_lshl_add_u64 v[88:89], s[42:43], 2, v[88:89]
	global_store_dword v[88:89], v90, off
; __device__ __forceinline__ u32x2 pack4(f32x4 v) { return u32x2{cvtpk(v[0], v[1]), cvtpk(v[2], v[3])}; }
; __device__ __forceinline__ f32x4 unpack4(u32x2 w) { return f32x4{bflo(w[0]), bfhi(w[0]), bflo(w[1]), bfhi(w[1])}; }
; template <int EPI, int nN, int lda, int ldb, int K, int ldc>
; __device__ __forceinline__ void gemm_phase(const Params& p, const u16* __restrict__ A, const u16* __restrict__ Bt, u16* C, u16* shm, int wave_s) {
;     ...
;         for (int i = 0; i < 16; ++i) {
;           const int r = i * 8 + wid;
;           const f32x4 v = stg_r32(stg, r, lane);
;           const size_t grow = (size_t)(brow + ai * 128 + r);
;           const int col = bcol + lane * 4;
;           if constexpr (EPI == EPI_CONVG) {
;             *reinterpret_cast<u32x2*>(C + grow * 1024 + col) = pack4(v * unpack4u8(pre8[i]));
;           } else if constexpr (EPI == EPI_MERGE) {
;             __builtin_nontemporal_store(pack4(v * unpack4u8(pre8[i]) + unpack4(pre16b[i])), reinterpret_cast<u32x2*>(C + grow * 1024 + col));
;           } else if constexpr (EPI == EPI_RESX) {
;             const f32x4 o = pre32[i] + v;
;             __builtin_nontemporal_store(pack4(o), reinterpret_cast<u32x2*>((u16*)(p.ws + OFF_HFN) + grow * DM + col));
;             const float ss = wave_sum(o[0] * o[0] + o[1] * o[1] + o[2] * o[2] + o[3] * o[3]);
;             if (lane == 0) ((float*)(p.ws + OFF_PSQ))[grow * 4 + pn] = ss;
.LBB0_842:
	s_or_b64 exec, exec, s[46:47]
	v_add_u32_e32 v142, 0x50, v192
	v_xor_b32_e32 v88, v142, v207
	v_lshlrev_b32_e32 v88, 4, v88
	v_lshlrev_b32_e32 v177, 10, v142
	v_and_b32_e32 v178, 0x3f0, v88
	v_or_b32_e32 v88, v177, v178
	s_waitcnt lgkmcnt(0)
	ds_read_b128 v[88:91], v88
	s_waitcnt lgkmcnt(0)
	v_pk_add_f32 v[88:89], v[84:85], v[88:89]
	s_nop 0
	v_mul_f32_e32 v84, v89, v89
	v_pk_add_f32 v[86:87], v[86:87], v[90:91]
	v_fmac_f32_e32 v84, v88, v88
	v_fmac_f32_e32 v84, v86, v86
	v_fmac_f32_e32 v84, v87, v87
	v_mov_b32_e32 v85, v84
	s_nop 0
	v_cvt_pk_bf16_f32 v88, v88, v89
	s_nop 0
	v_cvt_pk_bf16_f32 v89, v86, v87
	s_waitcnt lgkmcnt(0)
	s_nop 1
	v_permlane32_swap_b32_e32 v84, v85
	v_add_f32_e32 v84, v84, v85
	ds_bpermute_b32 v85, v201, v84
	s_waitcnt lgkmcnt(0)
	v_add_f32_e32 v84, v84, v85
	s_nop 1
	v_mov_b32_dpp v85, v84 row_mirror row_mask:0xf bank_mask:0xf
	s_waitcnt lgkmcnt(0)
	v_add_f32_e32 v84, v84, v85
	s_nop 1
	v_mov_b32_dpp v85, v84 row_half_mirror row_mask:0xf bank_mask:0xf
	s_waitcnt lgkmcnt(0)
	v_add_f32_e32 v90, v84, v85
	s_nop 1
	v_mov_b32_dpp v91, v90 quad_perm:[2,3,0,1] row_mask:0xf bank_mask:0xf
	v_add_u32_e32 v84, s4, v142
	v_ashrrev_i32_e32 v85, 31, v84
	s_waitcnt lgkmcnt(0)
	v_add_f32_e32 v86, v90, v91
	s_nop 1
	v_mov_b32_dpp v87, v86 quad_perm:[1,0,3,2] row_mask:0xf bank_mask:0xf
	v_lshlrev_b64 v[90:91], 11, v[84:85]
	v_lshl_add_u64 v[90:91], s[30:31], 0, v[90:91]
	v_lshl_add_u64 v[90:91], v[194:195], 1, v[90:91]
	global_store_dwordx2 v[90:91], v[88:89], off nt
	s_and_saveexec_b64 s[46:47], vcc
	s_cbranch_execz .LBB0_844
	v_lshl_add_u64 v[84:85], v[84:85], 4, s[8:9]
	s_waitcnt lgkmcnt(0)
	v_add_f32_e32 v86, v86, v87
	v_lshl_add_u64 v[84:85], s[42:43], 2, v[84:85]
	global_store_dword v[84:85], v86, off
.LBB0_844:
	s_or_b64 exec, exec, s[46:47]
	v_add_u32_e32 v154, 0x58, v192
	v_xor_b32_e32 v84, v154, v207
	v_lshlrev_b32_e32 v84, 4, v84
	v_lshlrev_b32_e32 v179, 10, v154
	v_and_b32_e32 v180, 0x3f0, v84
	v_or_b32_e32 v84, v179, v180
	s_waitcnt lgkmcnt(0)
	ds_read_b128 v[84:87], v84
	s_waitcnt lgkmcnt(0)
	v_pk_add_f32 v[84:85], v[80:81], v[84:85]
	s_nop 0
	v_mul_f32_e32 v80, v85, v85
	v_pk_add_f32 v[82:83], v[82:83], v[86:87]
	v_fmac_f32_e32 v80, v84, v84
	v_fmac_f32_e32 v80, v82, v82
	v_fmac_f32_e32 v80, v83, v83
	v_mov_b32_e32 v81, v80
	s_nop 0
	v_cvt_pk_bf16_f32 v84, v84, v85
	s_nop 0
	v_cvt_pk_bf16_f32 v85, v82, v83
	s_waitcnt lgkmcnt(0)
	s_nop 1
	v_permlane32_swap_b32_e32 v80, v81
	v_add_f32_e32 v80, v80, v81
	ds_bpermute_b32 v81, v201, v80
	s_waitcnt lgkmcnt(0)
	v_add_f32_e32 v80, v80, v81
	s_nop 1
	v_mov_b32_dpp v81, v80 row_mirror row_mask:0xf bank_mask:0xf
	s_waitcnt lgkmcnt(0)
	v_add_f32_e32 v80, v80, v81
	s_nop 1
	v_mov_b32_dpp v81, v80 row_half_mirror row_mask:0xf bank_mask:0xf
	s_waitcnt lgkmcnt(0)
	v_add_f32_e32 v86, v80, v81
	s_nop 1
	v_mov_b32_dpp v87, v86 quad_perm:[2,3,0,1] row_mask:0xf bank_mask:0xf
	v_add_u32_e32 v80, s4, v154
	v_ashrrev_i32_e32 v81, 31, v80
	s_waitcnt lgkmcnt(0)
	v_add_f32_e32 v82, v86, v87
	s_nop 1
	v_mov_b32_dpp v83, v82 quad_perm:[1,0,3,2] row_mask:0xf bank_mask:0xf
	v_lshlrev_b64 v[86:87], 11, v[80:81]
	v_lshl_add_u64 v[86:87], s[30:31], 0, v[86:87]
	v_lshl_add_u64 v[86:87], v[194:195], 1, v[86:87]
	global_store_dwordx2 v[86:87], v[84:85], off nt
	s_and_saveexec_b64 s[46:47], vcc
	s_cbranch_execz .LBB0_846
	v_lshl_add_u64 v[80:81], v[80:81], 4, s[8:9]
	s_waitcnt lgkmcnt(0)
	v_add_f32_e32 v82, v82, v83
	v_lshl_add_u64 v[80:81], s[42:43], 2, v[80:81]
	global_store_dword v[80:81], v82, off
.LBB0_846:
	s_or_b64 exec, exec, s[46:47]
	v_add_u32_e32 v157, 0x60, v192
	v_xor_b32_e32 v80, v157, v207
	v_lshlrev_b32_e32 v80, 4, v80
	v_lshlrev_b32_e32 v181, 10, v157
	v_and_b32_e32 v182, 0x3f0, v80
	v_or_b32_e32 v80, v181, v182
	s_waitcnt lgkmcnt(0)
	ds_read_b128 v[80:83], v80
	s_waitcnt lgkmcnt(0)
	v_pk_add_f32 v[80:81], v[76:77], v[80:81]
	s_nop 0
	v_mul_f32_e32 v76, v81, v81
	v_pk_add_f32 v[78:79], v[78:79], v[82:83]
	v_fmac_f32_e32 v76, v80, v80
	v_fmac_f32_e32 v76, v78, v78
	v_fmac_f32_e32 v76, v79, v79
	v_mov_b32_e32 v77, v76
	s_nop 0
	v_cvt_pk_bf16_f32 v80, v80, v81
	s_nop 0
	v_cvt_pk_bf16_f32 v81, v78, v79
	s_waitcnt lgkmcnt(0)
	s_nop 1
	v_permlane32_swap_b32_e32 v76, v77
	v_add_f32_e32 v76, v76, v77
	ds_bpermute_b32 v77, v201, v76
	s_waitcnt lgkmcnt(0)
	v_add_f32_e32 v76, v76, v77
	s_nop 1
	v_mov_b32_dpp v77, v76 row_mirror row_mask:0xf bank_mask:0xf
	s_waitcnt lgkmcnt(0)
	v_add_f32_e32 v76, v76, v77
	s_nop 1
	v_mov_b32_dpp v77, v76 row_half_mirror row_mask:0xf bank_mask:0xf
	s_waitcnt lgkmcnt(0)
	v_add_f32_e32 v82, v76, v77
	s_nop 1
	v_mov_b32_dpp v83, v82 quad_perm:[2,3,0,1] row_mask:0xf bank_mask:0xf
	v_add_u32_e32 v76, s4, v157
	v_ashrrev_i32_e32 v77, 31, v76
	s_waitcnt lgkmcnt(0)
	v_add_f32_e32 v78, v82, v83
	s_nop 1
	v_mov_b32_dpp v79, v78 quad_perm:[1,0,3,2] row_mask:0xf bank_mask:0xf
	v_lshlrev_b64 v[82:83], 11, v[76:77]
	v_lshl_add_u64 v[82:83], s[30:31], 0, v[82:83]
	v_lshl_add_u64 v[82:83], v[194:195], 1, v[82:83]
	global_store_dwordx2 v[82:83], v[80:81], off nt
	s_and_saveexec_b64 s[46:47], vcc
	s_cbranch_execz .LBB0_848
	v_lshl_add_u64 v[76:77], v[76:77], 4, s[8:9]
	s_waitcnt lgkmcnt(0)
	v_add_f32_e32 v78, v78, v79
	v_lshl_add_u64 v[76:77], s[42:43], 2, v[76:77]
	global_store_dword v[76:77], v78, off
; __device__ __forceinline__ u32x2 pack4(f32x4 v) { return u32x2{cvtpk(v[0], v[1]), cvtpk(v[2], v[3])}; }
; __device__ __forceinline__ f32x4 unpack4(u32x2 w) { return f32x4{bflo(w[0]), bfhi(w[0]), bflo(w[1]), bfhi(w[1])}; }
; template <int EPI, int nN, int lda, int ldb, int K, int ldc>
; __device__ __forceinline__ void gemm_phase(const Params& p, const u16* __restrict__ A, const u16* __restrict__ Bt, u16* C, u16* shm, int wave_s) {
;     ...
;         for (int i = 0; i < 16; ++i) {
;           const int r = i * 8 + wid;
;           const f32x4 v = stg_r32(stg, r, lane);
;           const size_t grow = (size_t)(brow + ai * 128 + r);
;           const int col = bcol + lane * 4;
;           if constexpr (EPI == EPI_CONVG) {
;             *reinterpret_cast<u32x2*>(C + grow * 1024 + col) = pack4(v * unpack4u8(pre8[i]));
;           } else if constexpr (EPI == EPI_MERGE) {
;             __builtin_nontemporal_store(pack4(v * unpack4u8(pre8[i]) + unpack4(pre16b[i])), reinterpret_cast<u32x2*>(C + grow * 1024 + col));
;           } else if constexpr (EPI == EPI_RESX) {
;             const f32x4 o = pre32[i] + v;
;             __builtin_nontemporal_store(pack4(o), reinterpret_cast<u32x2*>((u16*)(p.ws + OFF_HFN) + grow * DM + col));
;             const float ss = wave_sum(o[0] * o[0] + o[1] * o[1] + o[2] * o[2] + o[3] * o[3]);
;             if (lane == 0) ((float*)(p.ws + OFF_PSQ))[grow * 4 + pn] = ss;
.LBB0_848:
	s_or_b64 exec, exec, s[46:47]
	v_add_u32_e32 v163, 0x68, v192
	v_xor_b32_e32 v76, v163, v207
	v_lshlrev_b32_e32 v76, 4, v76
	v_lshlrev_b32_e32 v183, 10, v163
	v_and_b32_e32 v184, 0x3f0, v76
	v_or_b32_e32 v76, v183, v184
	s_waitcnt lgkmcnt(0)
	ds_read_b128 v[76:79], v76
	s_waitcnt lgkmcnt(0)
	v_pk_add_f32 v[76:77], v[72:73], v[76:77]
	s_nop 0
	v_mul_f32_e32 v72, v77, v77
	v_pk_add_f32 v[74:75], v[74:75], v[78:79]
	v_fmac_f32_e32 v72, v76, v76
	v_fmac_f32_e32 v72, v74, v74
	v_fmac_f32_e32 v72, v75, v75
	v_mov_b32_e32 v73, v72
	s_nop 0
	v_cvt_pk_bf16_f32 v76, v76, v77
	s_nop 0
	v_cvt_pk_bf16_f32 v77, v74, v75
	s_waitcnt lgkmcnt(0)
	s_nop 1
	v_permlane32_swap_b32_e32 v72, v73
	v_add_f32_e32 v72, v72, v73
	ds_bpermute_b32 v73, v201, v72
	s_waitcnt lgkmcnt(0)
	v_add_f32_e32 v72, v72, v73
	s_nop 1
	v_mov_b32_dpp v73, v72 row_mirror row_mask:0xf bank_mask:0xf
	s_waitcnt lgkmcnt(0)
	v_add_f32_e32 v72, v72, v73
	s_nop 1
	v_mov_b32_dpp v73, v72 row_half_mirror row_mask:0xf bank_mask:0xf
	s_waitcnt lgkmcnt(0)
	v_add_f32_e32 v78, v72, v73
	s_nop 1
	v_mov_b32_dpp v79, v78 quad_perm:[2,3,0,1] row_mask:0xf bank_mask:0xf
	v_add_u32_e32 v72, s4, v163
	v_ashrrev_i32_e32 v73, 31, v72
	s_waitcnt lgkmcnt(0)
	v_add_f32_e32 v74, v78, v79
	s_nop 1
	v_mov_b32_dpp v75, v74 quad_perm:[1,0,3,2] row_mask:0xf bank_mask:0xf
	v_lshlrev_b64 v[78:79], 11, v[72:73]
	v_lshl_add_u64 v[78:79], s[30:31], 0, v[78:79]
	v_lshl_add_u64 v[78:79], v[194:195], 1, v[78:79]
	global_store_dwordx2 v[78:79], v[76:77], off nt
	s_and_saveexec_b64 s[46:47], vcc
	s_cbranch_execz .LBB0_850
	v_lshl_add_u64 v[72:73], v[72:73], 4, s[8:9]
	s_waitcnt lgkmcnt(0)
	v_add_f32_e32 v74, v74, v75
	v_lshl_add_u64 v[72:73], s[42:43], 2, v[72:73]
	global_store_dword v[72:73], v74, off
.LBB0_850:
	s_or_b64 exec, exec, s[46:47]
	v_add_u32_e32 v167, 0x70, v192
	v_xor_b32_e32 v72, v167, v207
	v_lshlrev_b32_e32 v72, 4, v72
	v_lshlrev_b32_e32 v185, 10, v167
	v_and_b32_e32 v186, 0x3f0, v72
	v_or_b32_e32 v72, v185, v186
	s_waitcnt lgkmcnt(0)
	ds_read_b128 v[72:75], v72
	s_waitcnt lgkmcnt(0)
	v_pk_add_f32 v[72:73], v[68:69], v[72:73]
	s_nop 0
	v_mul_f32_e32 v68, v73, v73
	v_pk_add_f32 v[70:71], v[70:71], v[74:75]
	v_fmac_f32_e32 v68, v72, v72
	v_fmac_f32_e32 v68, v70, v70
	v_fmac_f32_e32 v68, v71, v71
	v_mov_b32_e32 v69, v68
	s_nop 0
	v_cvt_pk_bf16_f32 v72, v72, v73
	s_nop 0
	v_cvt_pk_bf16_f32 v73, v70, v71
	s_waitcnt lgkmcnt(0)
	s_nop 1
	v_permlane32_swap_b32_e32 v68, v69
	v_add_f32_e32 v68, v68, v69
	ds_bpermute_b32 v69, v201, v68
	s_waitcnt lgkmcnt(0)
	v_add_f32_e32 v68, v68, v69
	s_nop 1
	v_mov_b32_dpp v69, v68 row_mirror row_mask:0xf bank_mask:0xf
	s_waitcnt lgkmcnt(0)
	v_add_f32_e32 v68, v68, v69
	s_nop 1
	v_mov_b32_dpp v69, v68 row_half_mirror row_mask:0xf bank_mask:0xf
	s_waitcnt lgkmcnt(0)
	v_add_f32_e32 v74, v68, v69
	s_nop 1
	v_mov_b32_dpp v75, v74 quad_perm:[2,3,0,1] row_mask:0xf bank_mask:0xf
	v_add_u32_e32 v68, s4, v167
	v_ashrrev_i32_e32 v69, 31, v68
	s_waitcnt lgkmcnt(0)
	v_add_f32_e32 v70, v74, v75
	s_nop 1
	v_mov_b32_dpp v71, v70 quad_perm:[1,0,3,2] row_mask:0xf bank_mask:0xf
	v_lshlrev_b64 v[74:75], 11, v[68:69]
	v_lshl_add_u64 v[74:75], s[30:31], 0, v[74:75]
	v_lshl_add_u64 v[74:75], v[194:195], 1, v[74:75]
	global_store_dwordx2 v[74:75], v[72:73], off nt
	s_and_saveexec_b64 s[46:47], vcc
	s_cbranch_execz .LBB0_852
	v_lshl_add_u64 v[68:69], v[68:69], 4, s[8:9]
	s_waitcnt lgkmcnt(0)
	v_add_f32_e32 v70, v70, v71
	v_lshl_add_u64 v[68:69], s[42:43], 2, v[68:69]
	global_store_dword v[68:69], v70, off
.LBB0_852:
	s_or_b64 exec, exec, s[46:47]
	v_add_u32_e32 v170, 0x78, v192
	v_xor_b32_e32 v68, v170, v207
	v_lshlrev_b32_e32 v68, 4, v68
	v_lshlrev_b32_e32 v187, 10, v170
	v_and_b32_e32 v188, 0x3f0, v68
	v_or_b32_e32 v68, v187, v188
	s_waitcnt lgkmcnt(0)
	ds_read_b128 v[68:71], v68
	s_waitcnt lgkmcnt(0)
	v_pk_add_f32 v[68:69], v[64:65], v[68:69]
	s_nop 0
	v_mul_f32_e32 v64, v69, v69
	v_pk_add_f32 v[66:67], v[66:67], v[70:71]
	v_fmac_f32_e32 v64, v68, v68
	v_fmac_f32_e32 v64, v66, v66
	v_fmac_f32_e32 v64, v67, v67
	v_mov_b32_e32 v65, v64
	s_nop 0
	v_cvt_pk_bf16_f32 v68, v68, v69
	s_nop 0
	v_cvt_pk_bf16_f32 v69, v66, v67
	s_waitcnt lgkmcnt(0)
	s_nop 1
	v_permlane32_swap_b32_e32 v64, v65
	v_add_f32_e32 v64, v64, v65
	ds_bpermute_b32 v65, v201, v64
	s_waitcnt lgkmcnt(0)
	v_add_f32_e32 v64, v64, v65
	s_nop 1
	v_mov_b32_dpp v65, v64 row_mirror row_mask:0xf bank_mask:0xf
	s_waitcnt lgkmcnt(0)
	v_add_f32_e32 v64, v64, v65
	s_nop 1
	v_mov_b32_dpp v65, v64 row_half_mirror row_mask:0xf bank_mask:0xf
	s_waitcnt lgkmcnt(0)
	v_add_f32_e32 v70, v64, v65
	s_nop 1
	v_mov_b32_dpp v71, v70 quad_perm:[2,3,0,1] row_mask:0xf bank_mask:0xf
	v_add_u32_e32 v64, s4, v170
	v_ashrrev_i32_e32 v65, 31, v64
	s_waitcnt lgkmcnt(0)
	v_add_f32_e32 v66, v70, v71
	s_nop 1
	v_mov_b32_dpp v67, v66 quad_perm:[1,0,3,2] row_mask:0xf bank_mask:0xf
	v_lshlrev_b64 v[70:71], 11, v[64:65]
	v_lshl_add_u64 v[70:71], s[30:31], 0, v[70:71]
	v_lshl_add_u64 v[70:71], v[194:195], 1, v[70:71]
	global_store_dwordx2 v[70:71], v[68:69], off nt
	s_and_saveexec_b64 s[4:5], vcc
	s_cbranch_execz .LBB0_854
	v_lshl_add_u64 v[64:65], v[64:65], 4, s[8:9]
	v_lshl_add_u64 v[64:65], s[42:43], 2, v[64:65]
	s_waitcnt lgkmcnt(0)
	v_add_f32_e32 v66, v66, v67
	global_store_dword v[64:65], v66, off
; template <int EPI, int nN, int lda, int ldb, int K, int ldc>
; __device__ __forceinline__ void gemm_phase(const Params& p, const u16* __restrict__ A, const u16* __restrict__ Bt, u16* C, u16* shm, int wave_s) {
;     ...
;         for (int i = 0; i < 16; ++i) {
;           const size_t grow = (size_t)(brow + ai * 128 + i * 8 + wid); const int col = bcol + lane * 4;
;           if constexpr (EPI == EPI_CONVG) pre8[i] = *reinterpret_cast<const unsigned*>((const unsigned char*)p.out + grow * 2048 + 1024 + col);
;           else if constexpr (EPI == EPI_MERGE) { pre8[i] = *reinterpret_cast<const unsigned*>((const unsigned char*)p.out + grow * 2048 + col);
;                                                  pre16b[i] = *reinterpret_cast<const u32x2*>(C + grow * 1024 + col); }
;           else if constexpr (EPI == EPI_RESX) pre32[i] = *reinterpret_cast<const f32x4*>(xrow(p, (int)grow) + col);
;           else if constexpr (EPI == EPI_RESOUT) pre16a[i] = *reinterpret_cast<const u32x2*>((const u16*)(p.ws + OFF_HFN) + grow * DM + col);
;         }
.LBB0_854:
	s_or_b64 exec, exec, s[4:5]
	v_add_u32_e32 v64, 0x80, v196
	v_add_u32_e32 v66, 0xffff0080, v196
	v_ashrrev_i32_e32 v65, 31, v64
	v_cmp_gt_i32_e64 s[4:5], s66, v64
	v_mov_b32_e32 v189, s39
	v_mov_b32_e32 v190, s37
	v_cndmask_b32_e64 v65, 0, v65, s[4:5]
	v_cndmask_b32_e64 v64, v66, v64, s[4:5]
	v_mov_b32_e32 v191, s38
	v_mov_b32_e32 v197, s36
	s_waitcnt lgkmcnt(0)
	v_cndmask_b32_e64 v67, v189, v190, s[4:5]
	v_cndmask_b32_e64 v66, v191, v197, s[4:5]
	v_lshlrev_b64 v[64:65], 12, v[64:65]
	v_lshl_add_u64 v[64:65], v[66:67], 0, v[64:65]
	v_lshl_add_u64 v[64:65], v[64:65], 0, v[198:199]
	s_barrier
	global_load_dwordx4 v[124:127], v[64:65], off
	v_add_u32_e32 v64, 0x88, v196
	v_add_u32_e32 v66, 0xffff0088, v196
	v_ashrrev_i32_e32 v65, 31, v64
	v_cmp_gt_i32_e64 s[4:5], s66, v64
	s_nop 1
	v_cndmask_b32_e64 v65, 0, v65, s[4:5]
	v_cndmask_b32_e64 v64, v66, v64, s[4:5]
	v_cndmask_b32_e64 v67, v189, v190, s[4:5]
	v_cndmask_b32_e64 v66, v191, v197, s[4:5]
	v_lshlrev_b64 v[64:65], 12, v[64:65]
	v_lshl_add_u64 v[64:65], v[66:67], 0, v[64:65]
	v_lshl_add_u64 v[64:65], v[64:65], 0, v[198:199]
	global_load_dwordx4 v[120:123], v[64:65], off
	v_add_u32_e32 v64, 0x90, v196
	v_add_u32_e32 v66, 0xffff0090, v196
	v_ashrrev_i32_e32 v65, 31, v64
	v_cmp_gt_i32_e64 s[4:5], s66, v64
	s_nop 1
	v_cndmask_b32_e64 v65, 0, v65, s[4:5]
	v_cndmask_b32_e64 v64, v66, v64, s[4:5]
	v_cndmask_b32_e64 v67, v189, v190, s[4:5]
	v_cndmask_b32_e64 v66, v191, v197, s[4:5]
	v_lshlrev_b64 v[64:65], 12, v[64:65]
	v_lshl_add_u64 v[64:65], v[66:67], 0, v[64:65]
	v_lshl_add_u64 v[64:65], v[64:65], 0, v[198:199]
	global_load_dwordx4 v[116:119], v[64:65], off
	v_add_u32_e32 v64, 0x98, v196
	v_add_u32_e32 v66, 0xffff0098, v196
	v_ashrrev_i32_e32 v65, 31, v64
	v_cmp_gt_i32_e64 s[4:5], s66, v64
	s_nop 1
	v_cndmask_b32_e64 v65, 0, v65, s[4:5]
	v_cndmask_b32_e64 v64, v66, v64, s[4:5]
	v_cndmask_b32_e64 v67, v189, v190, s[4:5]
	v_cndmask_b32_e64 v66, v191, v197, s[4:5]
	v_lshlrev_b64 v[64:65], 12, v[64:65]
	v_lshl_add_u64 v[64:65], v[66:67], 0, v[64:65]
	v_lshl_add_u64 v[64:65], v[64:65], 0, v[198:199]
	global_load_dwordx4 v[112:115], v[64:65], off
	v_add_u32_e32 v64, 0xa0, v196
	v_add_u32_e32 v66, 0xffff00a0, v196
	v_ashrrev_i32_e32 v65, 31, v64
	v_cmp_gt_i32_e64 s[4:5], s66, v64
	s_nop 1
	v_cndmask_b32_e64 v65, 0, v65, s[4:5]
	v_cndmask_b32_e64 v64, v66, v64, s[4:5]
	v_cndmask_b32_e64 v67, v189, v190, s[4:5]
	v_cndmask_b32_e64 v66, v191, v197, s[4:5]
	v_lshlrev_b64 v[64:65], 12, v[64:65]
	v_lshl_add_u64 v[64:65], v[66:67], 0, v[64:65]
	v_lshl_add_u64 v[64:65], v[64:65], 0, v[198:199]
	global_load_dwordx4 v[108:111], v[64:65], off
	v_add_u32_e32 v64, 0xa8, v196
	v_add_u32_e32 v66, 0xffff00a8, v196
	v_ashrrev_i32_e32 v65, 31, v64
	v_cmp_gt_i32_e64 s[4:5], s66, v64
	s_nop 1
	v_cndmask_b32_e64 v65, 0, v65, s[4:5]
	v_cndmask_b32_e64 v64, v66, v64, s[4:5]
	v_cndmask_b32_e64 v67, v189, v190, s[4:5]
	v_cndmask_b32_e64 v66, v191, v197, s[4:5]
	v_lshlrev_b64 v[64:65], 12, v[64:65]
	v_lshl_add_u64 v[64:65], v[66:67], 0, v[64:65]
	v_lshl_add_u64 v[64:65], v[64:65], 0, v[198:199]
	global_load_dwordx4 v[104:107], v[64:65], off
	v_add_u32_e32 v64, 0xb0, v196
	v_add_u32_e32 v66, 0xffff00b0, v196
	v_ashrrev_i32_e32 v65, 31, v64
	v_cmp_gt_i32_e64 s[4:5], s66, v64
	s_nop 1
	v_cndmask_b32_e64 v65, 0, v65, s[4:5]
	v_cndmask_b32_e64 v64, v66, v64, s[4:5]
	v_cndmask_b32_e64 v67, v189, v190, s[4:5]
	v_cndmask_b32_e64 v66, v191, v197, s[4:5]
	v_lshlrev_b64 v[64:65], 12, v[64:65]
	v_lshl_add_u64 v[64:65], v[66:67], 0, v[64:65]
	v_lshl_add_u64 v[64:65], v[64:65], 0, v[198:199]
	global_load_dwordx4 v[100:103], v[64:65], off
	v_add_u32_e32 v64, 0xb8, v196
	v_add_u32_e32 v66, 0xffff00b8, v196
	v_ashrrev_i32_e32 v65, 31, v64
	v_cmp_gt_i32_e64 s[4:5], s66, v64
	s_nop 1
	v_cndmask_b32_e64 v65, 0, v65, s[4:5]
	v_cndmask_b32_e64 v64, v66, v64, s[4:5]
	v_cndmask_b32_e64 v67, v189, v190, s[4:5]
	v_cndmask_b32_e64 v66, v191, v197, s[4:5]
	v_lshlrev_b64 v[64:65], 12, v[64:65]
	v_lshl_add_u64 v[64:65], v[66:67], 0, v[64:65]
	v_lshl_add_u64 v[64:65], v[64:65], 0, v[198:199]
	global_load_dwordx4 v[96:99], v[64:65], off
	v_add_u32_e32 v64, 0xc0, v196
	v_add_u32_e32 v66, 0xffff00c0, v196
	v_ashrrev_i32_e32 v65, 31, v64
	v_cmp_gt_i32_e64 s[4:5], s66, v64
	s_nop 1
	v_cndmask_b32_e64 v65, 0, v65, s[4:5]
	v_cndmask_b32_e64 v64, v66, v64, s[4:5]
	v_cndmask_b32_e64 v67, v189, v190, s[4:5]
	v_cndmask_b32_e64 v66, v191, v197, s[4:5]
	v_lshlrev_b64 v[64:65], 12, v[64:65]
	v_lshl_add_u64 v[64:65], v[66:67], 0, v[64:65]
	v_lshl_add_u64 v[64:65], v[64:65], 0, v[198:199]
	global_load_dwordx4 v[92:95], v[64:65], off
	v_add_u32_e32 v64, 0xc8, v196
	v_add_u32_e32 v66, 0xffff00c8, v196
	v_ashrrev_i32_e32 v65, 31, v64
	v_cmp_gt_i32_e64 s[4:5], s66, v64
	s_nop 1
	v_cndmask_b32_e64 v65, 0, v65, s[4:5]
	v_cndmask_b32_e64 v64, v66, v64, s[4:5]
	v_cndmask_b32_e64 v67, v189, v190, s[4:5]
	v_cndmask_b32_e64 v66, v191, v197, s[4:5]
	v_lshlrev_b64 v[64:65], 12, v[64:65]
	v_lshl_add_u64 v[64:65], v[66:67], 0, v[64:65]
	v_lshl_add_u64 v[64:65], v[64:65], 0, v[198:199]
	global_load_dwordx4 v[88:91], v[64:65], off
	v_add_u32_e32 v64, 0xd0, v196
	v_add_u32_e32 v66, 0xffff00d0, v196
	v_ashrrev_i32_e32 v65, 31, v64
	v_cmp_gt_i32_e64 s[4:5], s66, v64
	s_nop 1
	v_cndmask_b32_e64 v65, 0, v65, s[4:5]
	v_cndmask_b32_e64 v64, v66, v64, s[4:5]
	v_cndmask_b32_e64 v67, v189, v190, s[4:5]
	v_cndmask_b32_e64 v66, v191, v197, s[4:5]
	v_lshlrev_b64 v[64:65], 12, v[64:65]
	v_lshl_add_u64 v[64:65], v[66:67], 0, v[64:65]
	v_lshl_add_u64 v[64:65], v[64:65], 0, v[198:199]
	global_load_dwordx4 v[84:87], v[64:65], off
	v_add_u32_e32 v64, 0xd8, v196
	v_add_u32_e32 v66, 0xffff00d8, v196
; __device__ __forceinline__ u32x2 pack4(f32x4 v) { return u32x2{cvtpk(v[0], v[1]), cvtpk(v[2], v[3])}; }
; __device__ __forceinline__ f32x4 unpack4(u32x2 w) { return f32x4{bflo(w[0]), bfhi(w[0]), bflo(w[1]), bfhi(w[1])}; }
; template <int EPI, int nN, int lda, int ldb, int K, int ldc>
; __device__ __forceinline__ void gemm_phase(const Params& p, const u16* __restrict__ A, const u16* __restrict__ Bt, u16* C, u16* shm, int wave_s) {
;     ...
;         _Pragma("unroll") for (int m = 0; m < 4; ++m) _Pragma("unroll") for (int bj = 0; bj < 2; ++bj) _Pragma("unroll") for (int n = 0; n < 2; ++n)
;           stg_w32(stg, wr * 64 + m * 16 + fr, tcol + E_C, acc[ai][bj][m][n]);
;         __syncthreads();
; #pragma unroll
;         for (int i = 0; i < 16; ++i) {
;           const int r = i * 8 + wid;
;           const f32x4 v = stg_r32(stg, r, lane);
;           const size_t grow = (size_t)(brow + ai * 128 + r);
;           const int col = bcol + lane * 4;
;           if constexpr (EPI == EPI_CONVG) {
;             *reinterpret_cast<u32x2*>(C + grow * 1024 + col) = pack4(v * unpack4u8(pre8[i]));
;           } else if constexpr (EPI == EPI_MERGE) {
;             __builtin_nontemporal_store(pack4(v * unpack4u8(pre8[i]) + unpack4(pre16b[i])), reinterpret_cast<u32x2*>(C + grow * 1024 + col));
;           } else if constexpr (EPI == EPI_RESX) {
;             const f32x4 o = pre32[i] + v;
;             __builtin_nontemporal_store(pack4(o), reinterpret_cast<u32x2*>((u16*)(p.ws + OFF_HFN) + grow * DM + col));
;             const float ss = wave_sum(o[0] * o[0] + o[1] * o[1] + o[2] * o[2] + o[3] * o[3]);
;             if (lane == 0) ((float*)(p.ws + OFF_PSQ))[grow * 4 + pn] = ss;
	v_ashrrev_i32_e32 v65, 31, v64
	v_cmp_gt_i32_e64 s[4:5], s66, v64
	s_nop 1
	v_cndmask_b32_e64 v65, 0, v65, s[4:5]
	v_cndmask_b32_e64 v64, v66, v64, s[4:5]
	v_cndmask_b32_e64 v67, v189, v190, s[4:5]
	v_cndmask_b32_e64 v66, v191, v197, s[4:5]
	v_lshlrev_b64 v[64:65], 12, v[64:65]
	v_lshl_add_u64 v[64:65], v[66:67], 0, v[64:65]
	v_lshl_add_u64 v[64:65], v[64:65], 0, v[198:199]
	global_load_dwordx4 v[80:83], v[64:65], off
	v_add_u32_e32 v64, 0xe0, v196
	v_add_u32_e32 v66, 0xffff00e0, v196
	v_ashrrev_i32_e32 v65, 31, v64
	v_cmp_gt_i32_e64 s[4:5], s66, v64
	s_nop 1
	v_cndmask_b32_e64 v65, 0, v65, s[4:5]
	v_cndmask_b32_e64 v64, v66, v64, s[4:5]
	v_cndmask_b32_e64 v67, v189, v190, s[4:5]
	v_cndmask_b32_e64 v66, v191, v197, s[4:5]
	v_lshlrev_b64 v[64:65], 12, v[64:65]
	v_lshl_add_u64 v[64:65], v[66:67], 0, v[64:65]
	v_lshl_add_u64 v[64:65], v[64:65], 0, v[198:199]
	global_load_dwordx4 v[76:79], v[64:65], off
	v_add_u32_e32 v64, 0xe8, v196
	v_add_u32_e32 v66, 0xffff00e8, v196
	v_ashrrev_i32_e32 v65, 31, v64
	v_cmp_gt_i32_e64 s[4:5], s66, v64
	s_nop 1
	v_cndmask_b32_e64 v65, 0, v65, s[4:5]
	v_cndmask_b32_e64 v64, v66, v64, s[4:5]
	v_cndmask_b32_e64 v67, v189, v190, s[4:5]
	v_cndmask_b32_e64 v66, v191, v197, s[4:5]
	v_lshlrev_b64 v[64:65], 12, v[64:65]
	v_lshl_add_u64 v[64:65], v[66:67], 0, v[64:65]
	v_lshl_add_u64 v[64:65], v[64:65], 0, v[198:199]
	global_load_dwordx4 v[72:75], v[64:65], off
	v_add_u32_e32 v64, 0xf0, v196
	v_add_u32_e32 v66, 0xffff00f0, v196
	v_ashrrev_i32_e32 v65, 31, v64
	v_cmp_gt_i32_e64 s[4:5], s66, v64
	s_nop 1
	v_cndmask_b32_e64 v65, 0, v65, s[4:5]
	v_cndmask_b32_e64 v64, v66, v64, s[4:5]
	v_cndmask_b32_e64 v67, v189, v190, s[4:5]
	v_cndmask_b32_e64 v66, v191, v197, s[4:5]
	v_lshlrev_b64 v[64:65], 12, v[64:65]
	v_lshl_add_u64 v[64:65], v[66:67], 0, v[64:65]
	v_lshl_add_u64 v[64:65], v[64:65], 0, v[198:199]
	global_load_dwordx4 v[68:71], v[64:65], off
	v_add_u32_e32 v64, 0xf8, v196
	v_add_u32_e32 v66, 0xffff00f8, v196
	v_ashrrev_i32_e32 v65, 31, v64
	v_cmp_gt_i32_e64 s[4:5], s66, v64
	s_nop 1
	v_cndmask_b32_e64 v65, 0, v65, s[4:5]
	v_cndmask_b32_e64 v64, v66, v64, s[4:5]
	v_cndmask_b32_e64 v67, v189, v190, s[4:5]
	v_cndmask_b32_e64 v66, v191, v197, s[4:5]
	v_lshlrev_b64 v[64:65], 12, v[64:65]
	v_lshl_add_u64 v[64:65], v[66:67], 0, v[64:65]
	v_lshl_add_u64 v[64:65], v[64:65], 0, v[198:199]
	global_load_dwordx4 v[64:67], v[64:65], off
	v_add_u32_e32 v189, v209, v210
	ds_write_b128 v189, v[24:27]
	v_add_u32_e32 v24, v209, v164
	ds_write_b128 v24, v[28:31]
	v_add_u32_e32 v24, v209, v160
	ds_write_b128 v24, v[56:59]
	v_add_u32_e32 v24, v209, v161
	ds_write_b128 v24, v[60:63]
	v_add_u32_e32 v24, v209, v162
	ds_write_b128 v24, v[16:19] offset:16384
	v_add_u32_e32 v16, v209, v148
	ds_write_b128 v16, v[20:23] offset:16384
	v_add_u32_e32 v16, v209, v144
	ds_write_b128 v16, v[48:51] offset:16384
	v_add_u32_e32 v16, v209, v145
	ds_write_b128 v16, v[52:55] offset:16384
	v_add_u32_e32 v16, v209, v146
	ds_write_b128 v16, v[8:11] offset:32768
	v_add_u32_e32 v8, v209, v135
	ds_write_b128 v8, v[12:15] offset:32768
	v_add_u32_e32 v8, v209, v147
	ds_write_b128 v8, v[40:43] offset:32768
	v_add_u32_e32 v8, v209, v149
	ds_write_b128 v8, v[44:47] offset:32768
	v_add_u32_e32 v8, v209, v150
	ds_write_b128 v8, v[0:3] offset:49152
	v_add_u32_e32 v0, v209, v151
	ds_write_b128 v0, v[4:7] offset:49152
	v_add_u32_e32 v0, v209, v152
	ds_write_b128 v0, v[32:35] offset:49152
	v_add_u32_e32 v0, v209, v140
	ds_write_b128 v0, v[36:39] offset:49152
	v_add_u32_e32 v0, v139, v128
	s_waitcnt lgkmcnt(0)
	s_barrier
	ds_read_b128 v[0:3], v0
	s_waitcnt vmcnt(15) lgkmcnt(0)
	v_pk_add_f32 v[4:5], v[124:125], v[0:1]
	s_nop 0
	v_mul_f32_e32 v0, v5, v5
	v_pk_add_f32 v[2:3], v[126:127], v[2:3]
	v_fmac_f32_e32 v0, v4, v4
	v_fmac_f32_e32 v0, v2, v2
	v_fmac_f32_e32 v0, v3, v3
	v_mov_b32_e32 v1, v0
	s_nop 0
	v_cvt_pk_bf16_f32 v4, v4, v5
	s_nop 0
	v_cvt_pk_bf16_f32 v5, v2, v3
	s_waitcnt lgkmcnt(0)
	s_nop 1
	v_permlane32_swap_b32_e32 v0, v1
	v_add_f32_e32 v0, v0, v1
	ds_bpermute_b32 v1, v201, v0
	s_waitcnt lgkmcnt(0)
	v_add_f32_e32 v0, v0, v1
	s_nop 1
	v_mov_b32_dpp v1, v0 row_mirror row_mask:0xf bank_mask:0xf
	s_waitcnt lgkmcnt(0)
	v_add_f32_e32 v0, v0, v1
	s_nop 1
	v_mov_b32_dpp v1, v0 row_half_mirror row_mask:0xf bank_mask:0xf
	s_waitcnt lgkmcnt(0)
	v_add_f32_e32 v6, v0, v1
	s_nop 1
	v_mov_b32_dpp v7, v6 quad_perm:[2,3,0,1] row_mask:0xf bank_mask:0xf
	v_add_u32_e32 v0, s44, v192
	v_ashrrev_i32_e32 v1, 31, v0
	s_waitcnt lgkmcnt(0)
	v_add_f32_e32 v2, v6, v7
	s_nop 1
	v_mov_b32_dpp v3, v2 quad_perm:[1,0,3,2] row_mask:0xf bank_mask:0xf
	v_lshlrev_b64 v[6:7], 11, v[0:1]
	v_lshl_add_u64 v[6:7], s[30:31], 0, v[6:7]
	v_lshl_add_u64 v[6:7], v[194:195], 1, v[6:7]
	global_store_dwordx2 v[6:7], v[4:5], off nt
	s_and_saveexec_b64 s[4:5], vcc
	s_cbranch_execz .LBB0_856
	v_lshl_add_u64 v[0:1], v[0:1], 4, s[8:9]
	s_waitcnt lgkmcnt(0)
	v_add_f32_e32 v2, v2, v3
	v_lshl_add_u64 v[0:1], s[42:43], 2, v[0:1]
	global_store_dword v[0:1], v2, off
; __device__ __forceinline__ u32x2 pack4(f32x4 v) { return u32x2{cvtpk(v[0], v[1]), cvtpk(v[2], v[3])}; }
; __device__ __forceinline__ f32x4 unpack4(u32x2 w) { return f32x4{bflo(w[0]), bfhi(w[0]), bflo(w[1]), bfhi(w[1])}; }
; template <int EPI, int nN, int lda, int ldb, int K, int ldc>
; __device__ __forceinline__ void gemm_phase(const Params& p, const u16* __restrict__ A, const u16* __restrict__ Bt, u16* C, u16* shm, int wave_s) {
;     ...
;         for (int i = 0; i < 16; ++i) {
;           const int r = i * 8 + wid;
;           const f32x4 v = stg_r32(stg, r, lane);
;           const size_t grow = (size_t)(brow + ai * 128 + r);
;           const int col = bcol + lane * 4;
;           if constexpr (EPI == EPI_CONVG) {
;             *reinterpret_cast<u32x2*>(C + grow * 1024 + col) = pack4(v * unpack4u8(pre8[i]));
;           } else if constexpr (EPI == EPI_MERGE) {
;             __builtin_nontemporal_store(pack4(v * unpack4u8(pre8[i]) + unpack4(pre16b[i])), reinterpret_cast<u32x2*>(C + grow * 1024 + col));
;           } else if constexpr (EPI == EPI_RESX) {
;             const f32x4 o = pre32[i] + v;
;             __builtin_nontemporal_store(pack4(o), reinterpret_cast<u32x2*>((u16*)(p.ws + OFF_HFN) + grow * DM + col));
;             const float ss = wave_sum(o[0] * o[0] + o[1] * o[1] + o[2] * o[2] + o[3] * o[3]);
;             if (lane == 0) ((float*)(p.ws + OFF_PSQ))[grow * 4 + pn] = ss;
.LBB0_856:
	s_or_b64 exec, exec, s[4:5]
	v_add_u32_e32 v0, v141, v143
	s_waitcnt lgkmcnt(0)
	ds_read_b128 v[0:3], v0
	s_waitcnt vmcnt(15) lgkmcnt(0)
	v_pk_add_f32 v[4:5], v[120:121], v[0:1]
	s_nop 0
	v_mul_f32_e32 v0, v5, v5
	v_pk_add_f32 v[2:3], v[122:123], v[2:3]
	v_fmac_f32_e32 v0, v4, v4
	v_fmac_f32_e32 v0, v2, v2
	v_fmac_f32_e32 v0, v3, v3
	v_mov_b32_e32 v1, v0
	s_nop 0
	v_cvt_pk_bf16_f32 v4, v4, v5
	s_nop 0
	v_cvt_pk_bf16_f32 v5, v2, v3
	s_waitcnt lgkmcnt(0)
	s_nop 1
	v_permlane32_swap_b32_e32 v0, v1
	v_add_f32_e32 v0, v0, v1
	ds_bpermute_b32 v1, v201, v0
	s_waitcnt lgkmcnt(0)
	v_add_f32_e32 v0, v0, v1
	s_nop 1
	v_mov_b32_dpp v1, v0 row_mirror row_mask:0xf bank_mask:0xf
	s_waitcnt lgkmcnt(0)
	v_add_f32_e32 v0, v0, v1
	s_nop 1
	v_mov_b32_dpp v1, v0 row_half_mirror row_mask:0xf bank_mask:0xf
	s_waitcnt lgkmcnt(0)
	v_add_f32_e32 v6, v0, v1
	s_nop 1
	v_mov_b32_dpp v7, v6 quad_perm:[2,3,0,1] row_mask:0xf bank_mask:0xf
	v_add_u32_e32 v0, s44, v129
	v_ashrrev_i32_e32 v1, 31, v0
	s_waitcnt lgkmcnt(0)
	v_add_f32_e32 v2, v6, v7
	s_nop 1
	v_mov_b32_dpp v3, v2 quad_perm:[1,0,3,2] row_mask:0xf bank_mask:0xf
	v_lshlrev_b64 v[6:7], 11, v[0:1]
	v_lshl_add_u64 v[6:7], s[30:31], 0, v[6:7]
	v_lshl_add_u64 v[6:7], v[194:195], 1, v[6:7]
	global_store_dwordx2 v[6:7], v[4:5], off nt
	s_and_saveexec_b64 s[4:5], vcc
	s_cbranch_execz .LBB0_858
	v_lshl_add_u64 v[0:1], v[0:1], 4, s[8:9]
	s_waitcnt lgkmcnt(0)
	v_add_f32_e32 v2, v2, v3
	v_lshl_add_u64 v[0:1], s[42:43], 2, v[0:1]
	global_store_dword v[0:1], v2, off
.LBB0_858:
	s_or_b64 exec, exec, s[4:5]
	v_add_u32_e32 v0, v153, v155
	s_waitcnt lgkmcnt(0)
	ds_read_b128 v[0:3], v0
	s_waitcnt vmcnt(15) lgkmcnt(0)
	v_pk_add_f32 v[4:5], v[116:117], v[0:1]
	s_nop 0
	v_mul_f32_e32 v0, v5, v5
	v_pk_add_f32 v[2:3], v[118:119], v[2:3]
	v_fmac_f32_e32 v0, v4, v4
	v_fmac_f32_e32 v0, v2, v2
	v_fmac_f32_e32 v0, v3, v3
	v_mov_b32_e32 v1, v0
	s_nop 0
	v_cvt_pk_bf16_f32 v4, v4, v5
	s_nop 0
	v_cvt_pk_bf16_f32 v5, v2, v3
	s_waitcnt lgkmcnt(0)
	s_nop 1
	v_permlane32_swap_b32_e32 v0, v1
	v_add_f32_e32 v0, v0, v1
	ds_bpermute_b32 v1, v201, v0
	s_waitcnt lgkmcnt(0)
	v_add_f32_e32 v0, v0, v1
	s_nop 1
	v_mov_b32_dpp v1, v0 row_mirror row_mask:0xf bank_mask:0xf
	s_waitcnt lgkmcnt(0)
	v_add_f32_e32 v0, v0, v1
	s_nop 1
	v_mov_b32_dpp v1, v0 row_half_mirror row_mask:0xf bank_mask:0xf
	s_waitcnt lgkmcnt(0)
	v_add_f32_e32 v6, v0, v1
	s_nop 1
	v_mov_b32_dpp v7, v6 quad_perm:[2,3,0,1] row_mask:0xf bank_mask:0xf
	v_add_u32_e32 v0, s44, v130
	v_ashrrev_i32_e32 v1, 31, v0
	s_waitcnt lgkmcnt(0)
	v_add_f32_e32 v2, v6, v7
	s_nop 1
	v_mov_b32_dpp v3, v2 quad_perm:[1,0,3,2] row_mask:0xf bank_mask:0xf
	v_lshlrev_b64 v[6:7], 11, v[0:1]
	v_lshl_add_u64 v[6:7], s[30:31], 0, v[6:7]
	v_lshl_add_u64 v[6:7], v[194:195], 1, v[6:7]
	global_store_dwordx2 v[6:7], v[4:5], off nt
	s_and_saveexec_b64 s[4:5], vcc
	s_cbranch_execz .LBB0_860
	v_lshl_add_u64 v[0:1], v[0:1], 4, s[8:9]
	s_waitcnt lgkmcnt(0)
	v_add_f32_e32 v2, v2, v3
	v_lshl_add_u64 v[0:1], s[42:43], 2, v[0:1]
	global_store_dword v[0:1], v2, off
.LBB0_860:
	s_or_b64 exec, exec, s[4:5]
	v_add_u32_e32 v0, v156, v158
	s_waitcnt lgkmcnt(0)
	ds_read_b128 v[0:3], v0
	s_waitcnt vmcnt(15) lgkmcnt(0)
	v_pk_add_f32 v[4:5], v[112:113], v[0:1]
	s_nop 0
	v_mul_f32_e32 v0, v5, v5
	v_pk_add_f32 v[2:3], v[114:115], v[2:3]
	v_fmac_f32_e32 v0, v4, v4
	v_fmac_f32_e32 v0, v2, v2
	v_fmac_f32_e32 v0, v3, v3
	v_mov_b32_e32 v1, v0
	s_nop 0
	v_cvt_pk_bf16_f32 v4, v4, v5
	s_nop 0
	v_cvt_pk_bf16_f32 v5, v2, v3
	s_waitcnt lgkmcnt(0)
	s_nop 1
	v_permlane32_swap_b32_e32 v0, v1
	v_add_f32_e32 v0, v0, v1
	ds_bpermute_b32 v1, v201, v0
	s_waitcnt lgkmcnt(0)
	v_add_f32_e32 v0, v0, v1
	s_nop 1
	v_mov_b32_dpp v1, v0 row_mirror row_mask:0xf bank_mask:0xf
	s_waitcnt lgkmcnt(0)
	v_add_f32_e32 v0, v0, v1
	s_nop 1
	v_mov_b32_dpp v1, v0 row_half_mirror row_mask:0xf bank_mask:0xf
	s_waitcnt lgkmcnt(0)
	v_add_f32_e32 v6, v0, v1
	s_nop 1
	v_mov_b32_dpp v7, v6 quad_perm:[2,3,0,1] row_mask:0xf bank_mask:0xf
	v_add_u32_e32 v0, s44, v131
	v_ashrrev_i32_e32 v1, 31, v0
	s_waitcnt lgkmcnt(0)
	v_add_f32_e32 v2, v6, v7
	s_nop 1
	v_mov_b32_dpp v3, v2 quad_perm:[1,0,3,2] row_mask:0xf bank_mask:0xf
	v_lshlrev_b64 v[6:7], 11, v[0:1]
	v_lshl_add_u64 v[6:7], s[30:31], 0, v[6:7]
	v_lshl_add_u64 v[6:7], v[194:195], 1, v[6:7]
	global_store_dwordx2 v[6:7], v[4:5], off nt
	s_and_saveexec_b64 s[4:5], vcc
	s_cbranch_execz .LBB0_862
	v_lshl_add_u64 v[0:1], v[0:1], 4, s[8:9]
	s_waitcnt lgkmcnt(0)
	v_add_f32_e32 v2, v2, v3
	v_lshl_add_u64 v[0:1], s[42:43], 2, v[0:1]
	global_store_dword v[0:1], v2, off
.LBB0_862:
	s_or_b64 exec, exec, s[4:5]
	v_add_u32_e32 v0, v159, v165
	s_waitcnt lgkmcnt(0)
	ds_read_b128 v[0:3], v0
	s_waitcnt vmcnt(15) lgkmcnt(0)
	v_pk_add_f32 v[4:5], v[108:109], v[0:1]
	s_nop 0
	v_mul_f32_e32 v0, v5, v5
	v_pk_add_f32 v[2:3], v[110:111], v[2:3]
	v_fmac_f32_e32 v0, v4, v4
	v_fmac_f32_e32 v0, v2, v2
	v_fmac_f32_e32 v0, v3, v3
	v_mov_b32_e32 v1, v0
	s_nop 0
	v_cvt_pk_bf16_f32 v4, v4, v5
	s_nop 0
	v_cvt_pk_bf16_f32 v5, v2, v3
	s_waitcnt lgkmcnt(0)
	s_nop 1
	v_permlane32_swap_b32_e32 v0, v1
	v_add_f32_e32 v0, v0, v1
	ds_bpermute_b32 v1, v201, v0
	s_waitcnt lgkmcnt(0)
	v_add_f32_e32 v0, v0, v1
	s_nop 1
	v_mov_b32_dpp v1, v0 row_mirror row_mask:0xf bank_mask:0xf
	s_waitcnt lgkmcnt(0)
	v_add_f32_e32 v0, v0, v1
	s_nop 1
	v_mov_b32_dpp v1, v0 row_half_mirror row_mask:0xf bank_mask:0xf
	s_waitcnt lgkmcnt(0)
	v_add_f32_e32 v6, v0, v1
	s_nop 1
	v_mov_b32_dpp v7, v6 quad_perm:[2,3,0,1] row_mask:0xf bank_mask:0xf
	v_add_u32_e32 v0, s44, v132
	v_ashrrev_i32_e32 v1, 31, v0
	s_waitcnt lgkmcnt(0)
	v_add_f32_e32 v2, v6, v7
	s_nop 1
	v_mov_b32_dpp v3, v2 quad_perm:[1,0,3,2] row_mask:0xf bank_mask:0xf
	v_lshlrev_b64 v[6:7], 11, v[0:1]
	v_lshl_add_u64 v[6:7], s[30:31], 0, v[6:7]
	v_lshl_add_u64 v[6:7], v[194:195], 1, v[6:7]
	global_store_dwordx2 v[6:7], v[4:5], off nt
	s_and_saveexec_b64 s[4:5], vcc
	s_cbranch_execz .LBB0_864
	v_lshl_add_u64 v[0:1], v[0:1], 4, s[8:9]
	s_waitcnt lgkmcnt(0)
	v_add_f32_e32 v2, v2, v3
	v_lshl_add_u64 v[0:1], s[42:43], 2, v[0:1]
	global_store_dword v[0:1], v2, off
; __device__ __forceinline__ u32x2 pack4(f32x4 v) { return u32x2{cvtpk(v[0], v[1]), cvtpk(v[2], v[3])}; }
; __device__ __forceinline__ f32x4 unpack4(u32x2 w) { return f32x4{bflo(w[0]), bfhi(w[0]), bflo(w[1]), bfhi(w[1])}; }
; template <int EPI, int nN, int lda, int ldb, int K, int ldc>
; __device__ __forceinline__ void gemm_phase(const Params& p, const u16* __restrict__ A, const u16* __restrict__ Bt, u16* C, u16* shm, int wave_s) {
;     ...
;         for (int i = 0; i < 16; ++i) {
;           const int r = i * 8 + wid;
;           const f32x4 v = stg_r32(stg, r, lane);
;           const size_t grow = (size_t)(brow + ai * 128 + r);
;           const int col = bcol + lane * 4;
;           if constexpr (EPI == EPI_CONVG) {
;             *reinterpret_cast<u32x2*>(C + grow * 1024 + col) = pack4(v * unpack4u8(pre8[i]));
;           } else if constexpr (EPI == EPI_MERGE) {
;             __builtin_nontemporal_store(pack4(v * unpack4u8(pre8[i]) + unpack4(pre16b[i])), reinterpret_cast<u32x2*>(C + grow * 1024 + col));
;           } else if constexpr (EPI == EPI_RESX) {
;             const f32x4 o = pre32[i] + v;
;             __builtin_nontemporal_store(pack4(o), reinterpret_cast<u32x2*>((u16*)(p.ws + OFF_HFN) + grow * DM + col));
;             const float ss = wave_sum(o[0] * o[0] + o[1] * o[1] + o[2] * o[2] + o[3] * o[3]);
;             if (lane == 0) ((float*)(p.ws + OFF_PSQ))[grow * 4 + pn] = ss;
.LBB0_864:
	s_or_b64 exec, exec, s[4:5]
	v_add_u32_e32 v0, v166, v168
	s_waitcnt lgkmcnt(0)
	ds_read_b128 v[0:3], v0
	s_waitcnt vmcnt(15) lgkmcnt(0)
	v_pk_add_f32 v[4:5], v[104:105], v[0:1]
	s_nop 0
	v_mul_f32_e32 v0, v5, v5
	v_pk_add_f32 v[2:3], v[106:107], v[2:3]
	v_fmac_f32_e32 v0, v4, v4
	v_fmac_f32_e32 v0, v2, v2
	v_fmac_f32_e32 v0, v3, v3
	v_mov_b32_e32 v1, v0
	s_nop 0
	v_cvt_pk_bf16_f32 v4, v4, v5
	s_nop 0
	v_cvt_pk_bf16_f32 v5, v2, v3
	s_waitcnt lgkmcnt(0)
	s_nop 1
	v_permlane32_swap_b32_e32 v0, v1
	v_add_f32_e32 v0, v0, v1
	ds_bpermute_b32 v1, v201, v0
	s_waitcnt lgkmcnt(0)
	v_add_f32_e32 v0, v0, v1
	s_nop 1
	v_mov_b32_dpp v1, v0 row_mirror row_mask:0xf bank_mask:0xf
	s_waitcnt lgkmcnt(0)
	v_add_f32_e32 v0, v0, v1
	s_nop 1
	v_mov_b32_dpp v1, v0 row_half_mirror row_mask:0xf bank_mask:0xf
	s_waitcnt lgkmcnt(0)
	v_add_f32_e32 v6, v0, v1
	s_nop 1
	v_mov_b32_dpp v7, v6 quad_perm:[2,3,0,1] row_mask:0xf bank_mask:0xf
	v_add_u32_e32 v0, s44, v133
	v_ashrrev_i32_e32 v1, 31, v0
	s_waitcnt lgkmcnt(0)
	v_add_f32_e32 v2, v6, v7
	s_nop 1
	v_mov_b32_dpp v3, v2 quad_perm:[1,0,3,2] row_mask:0xf bank_mask:0xf
	v_lshlrev_b64 v[6:7], 11, v[0:1]
	v_lshl_add_u64 v[6:7], s[30:31], 0, v[6:7]
	v_lshl_add_u64 v[6:7], v[194:195], 1, v[6:7]
	global_store_dwordx2 v[6:7], v[4:5], off nt
	s_and_saveexec_b64 s[4:5], vcc
	s_cbranch_execz .LBB0_866
	v_lshl_add_u64 v[0:1], v[0:1], 4, s[8:9]
	s_waitcnt lgkmcnt(0)
	v_add_f32_e32 v2, v2, v3
	v_lshl_add_u64 v[0:1], s[42:43], 2, v[0:1]
	global_store_dword v[0:1], v2, off
.LBB0_866:
	s_or_b64 exec, exec, s[4:5]
	v_add_u32_e32 v0, v169, v171
	s_waitcnt lgkmcnt(0)
	ds_read_b128 v[0:3], v0
	s_waitcnt vmcnt(15) lgkmcnt(0)
	v_pk_add_f32 v[4:5], v[100:101], v[0:1]
	s_nop 0
	v_mul_f32_e32 v0, v5, v5
	v_pk_add_f32 v[2:3], v[102:103], v[2:3]
	v_fmac_f32_e32 v0, v4, v4
	v_fmac_f32_e32 v0, v2, v2
	v_fmac_f32_e32 v0, v3, v3
	v_mov_b32_e32 v1, v0
	s_nop 0
	v_cvt_pk_bf16_f32 v4, v4, v5
	s_nop 0
	v_cvt_pk_bf16_f32 v5, v2, v3
	s_waitcnt lgkmcnt(0)
	s_nop 1
	v_permlane32_swap_b32_e32 v0, v1
	v_add_f32_e32 v0, v0, v1
	ds_bpermute_b32 v1, v201, v0
	s_waitcnt lgkmcnt(0)
	v_add_f32_e32 v0, v0, v1
	s_nop 1
	v_mov_b32_dpp v1, v0 row_mirror row_mask:0xf bank_mask:0xf
	s_waitcnt lgkmcnt(0)
	v_add_f32_e32 v0, v0, v1
	s_nop 1
	v_mov_b32_dpp v1, v0 row_half_mirror row_mask:0xf bank_mask:0xf
	s_waitcnt lgkmcnt(0)
	v_add_f32_e32 v6, v0, v1
	s_nop 1
	v_mov_b32_dpp v7, v6 quad_perm:[2,3,0,1] row_mask:0xf bank_mask:0xf
	v_add_u32_e32 v0, s44, v134
	v_ashrrev_i32_e32 v1, 31, v0
	s_waitcnt lgkmcnt(0)
	v_add_f32_e32 v2, v6, v7
	s_nop 1
	v_mov_b32_dpp v3, v2 quad_perm:[1,0,3,2] row_mask:0xf bank_mask:0xf
	v_lshlrev_b64 v[6:7], 11, v[0:1]
	v_lshl_add_u64 v[6:7], s[30:31], 0, v[6:7]
	v_lshl_add_u64 v[6:7], v[194:195], 1, v[6:7]
	global_store_dwordx2 v[6:7], v[4:5], off nt
	s_and_saveexec_b64 s[4:5], vcc
	s_cbranch_execz .LBB0_868
	v_lshl_add_u64 v[0:1], v[0:1], 4, s[8:9]
	s_waitcnt lgkmcnt(0)
	v_add_f32_e32 v2, v2, v3
	v_lshl_add_u64 v[0:1], s[42:43], 2, v[0:1]
	global_store_dword v[0:1], v2, off
.LBB0_868:
	s_or_b64 exec, exec, s[4:5]
	v_add_u32_e32 v0, v172, v173
	s_waitcnt lgkmcnt(0)
	ds_read_b128 v[0:3], v0
	s_waitcnt vmcnt(15) lgkmcnt(0)
	v_pk_add_f32 v[4:5], v[96:97], v[0:1]
	s_nop 0
	v_mul_f32_e32 v0, v5, v5
	v_pk_add_f32 v[2:3], v[98:99], v[2:3]
	v_fmac_f32_e32 v0, v4, v4
	v_fmac_f32_e32 v0, v2, v2
	v_fmac_f32_e32 v0, v3, v3
	v_mov_b32_e32 v1, v0
	s_nop 0
	v_cvt_pk_bf16_f32 v4, v4, v5
	s_nop 0
	v_cvt_pk_bf16_f32 v5, v2, v3
	s_waitcnt lgkmcnt(0)
	s_nop 1
	v_permlane32_swap_b32_e32 v0, v1
	v_add_f32_e32 v0, v0, v1
	ds_bpermute_b32 v1, v201, v0
	s_waitcnt lgkmcnt(0)
	v_add_f32_e32 v0, v0, v1
	s_nop 1
	v_mov_b32_dpp v1, v0 row_mirror row_mask:0xf bank_mask:0xf
	s_waitcnt lgkmcnt(0)
	v_add_f32_e32 v0, v0, v1
	s_nop 1
	v_mov_b32_dpp v1, v0 row_half_mirror row_mask:0xf bank_mask:0xf
	s_waitcnt lgkmcnt(0)
	v_add_f32_e32 v6, v0, v1
	s_nop 1
	v_mov_b32_dpp v7, v6 quad_perm:[2,3,0,1] row_mask:0xf bank_mask:0xf
	v_add_u32_e32 v0, s44, v136
	v_ashrrev_i32_e32 v1, 31, v0
	s_waitcnt lgkmcnt(0)
	v_add_f32_e32 v2, v6, v7
	s_nop 1
	v_mov_b32_dpp v3, v2 quad_perm:[1,0,3,2] row_mask:0xf bank_mask:0xf
	v_lshlrev_b64 v[6:7], 11, v[0:1]
	v_lshl_add_u64 v[6:7], s[30:31], 0, v[6:7]
	v_lshl_add_u64 v[6:7], v[194:195], 1, v[6:7]
	global_store_dwordx2 v[6:7], v[4:5], off nt
	s_and_saveexec_b64 s[4:5], vcc
	s_cbranch_execz .LBB0_870
	v_lshl_add_u64 v[0:1], v[0:1], 4, s[8:9]
	s_waitcnt lgkmcnt(0)
	v_add_f32_e32 v2, v2, v3
	v_lshl_add_u64 v[0:1], s[42:43], 2, v[0:1]
	global_store_dword v[0:1], v2, off
.LBB0_870:
	s_or_b64 exec, exec, s[4:5]
	v_add_u32_e32 v0, v174, v128
	s_waitcnt lgkmcnt(0)
	ds_read_b128 v[0:3], v0
	s_waitcnt vmcnt(15) lgkmcnt(0)
	v_pk_add_f32 v[4:5], v[92:93], v[0:1]
	s_nop 0
	v_mul_f32_e32 v0, v5, v5
	v_pk_add_f32 v[2:3], v[94:95], v[2:3]
	v_fmac_f32_e32 v0, v4, v4
	v_fmac_f32_e32 v0, v2, v2
	v_fmac_f32_e32 v0, v3, v3
	v_mov_b32_e32 v1, v0
	s_nop 0
	v_cvt_pk_bf16_f32 v4, v4, v5
	s_nop 0
	v_cvt_pk_bf16_f32 v5, v2, v3
	s_waitcnt lgkmcnt(0)
	s_nop 1
	v_permlane32_swap_b32_e32 v0, v1
	v_add_f32_e32 v0, v0, v1
	ds_bpermute_b32 v1, v201, v0
	s_waitcnt lgkmcnt(0)
	v_add_f32_e32 v0, v0, v1
	s_nop 1
	v_mov_b32_dpp v1, v0 row_mirror row_mask:0xf bank_mask:0xf
	s_waitcnt lgkmcnt(0)
	v_add_f32_e32 v0, v0, v1
	s_nop 1
	v_mov_b32_dpp v1, v0 row_half_mirror row_mask:0xf bank_mask:0xf
	s_waitcnt lgkmcnt(0)
	v_add_f32_e32 v6, v0, v1
	s_nop 1
	v_mov_b32_dpp v7, v6 quad_perm:[2,3,0,1] row_mask:0xf bank_mask:0xf
	v_add_u32_e32 v0, s44, v137
	v_ashrrev_i32_e32 v1, 31, v0
	s_waitcnt lgkmcnt(0)
	v_add_f32_e32 v2, v6, v7
	s_nop 1
	v_mov_b32_dpp v3, v2 quad_perm:[1,0,3,2] row_mask:0xf bank_mask:0xf
	v_lshlrev_b64 v[6:7], 11, v[0:1]
	v_lshl_add_u64 v[6:7], s[30:31], 0, v[6:7]
	v_lshl_add_u64 v[6:7], v[194:195], 1, v[6:7]
	global_store_dwordx2 v[6:7], v[4:5], off nt
	s_and_saveexec_b64 s[4:5], vcc
	s_cbranch_execz .LBB0_872
	v_lshl_add_u64 v[0:1], v[0:1], 4, s[8:9]
	s_waitcnt lgkmcnt(0)
	v_add_f32_e32 v2, v2, v3
	v_lshl_add_u64 v[0:1], s[42:43], 2, v[0:1]
	global_store_dword v[0:1], v2, off
; __device__ __forceinline__ u32x2 pack4(f32x4 v) { return u32x2{cvtpk(v[0], v[1]), cvtpk(v[2], v[3])}; }
; __device__ __forceinline__ f32x4 unpack4(u32x2 w) { return f32x4{bflo(w[0]), bfhi(w[0]), bflo(w[1]), bfhi(w[1])}; }
; __device__ __forceinline__ float wave_sum(float v) {
; #pragma unroll
;   for (int o = 32; o > 0; o >>= 1) v += __shfl_xor(v, o);
;   return v;
; template <int EPI, int nN, int lda, int ldb, int K, int ldc>
; __device__ __forceinline__ void gemm_phase(const Params& p, const u16* __restrict__ A, const u16* __restrict__ Bt, u16* C, u16* shm, int wave_s) {
;     ...
;         for (int i = 0; i < 16; ++i) {
;           const int r = i * 8 + wid;
;           const f32x4 v = stg_r32(stg, r, lane);
;           const size_t grow = (size_t)(brow + ai * 128 + r);
;           const int col = bcol + lane * 4;
;           if constexpr (EPI == EPI_CONVG) {
;             *reinterpret_cast<u32x2*>(C + grow * 1024 + col) = pack4(v * unpack4u8(pre8[i]));
;           } else if constexpr (EPI == EPI_MERGE) {
;             __builtin_nontemporal_store(pack4(v * unpack4u8(pre8[i]) + unpack4(pre16b[i])), reinterpret_cast<u32x2*>(C + grow * 1024 + col));
;           } else if constexpr (EPI == EPI_RESX) {
;             const f32x4 o = pre32[i] + v;
;             __builtin_nontemporal_store(pack4(o), reinterpret_cast<u32x2*>((u16*)(p.ws + OFF_HFN) + grow * DM + col));
;             const float ss = wave_sum(o[0] * o[0] + o[1] * o[1] + o[2] * o[2] + o[3] * o[3]);
;             if (lane == 0) ((float*)(p.ws + OFF_PSQ))[grow * 4 + pn] = ss;
.LBB0_872:
	s_or_b64 exec, exec, s[4:5]
	v_add_u32_e32 v0, v175, v176
	s_waitcnt lgkmcnt(0)
	ds_read_b128 v[0:3], v0
	s_waitcnt vmcnt(15) lgkmcnt(0)
	v_pk_add_f32 v[4:5], v[88:89], v[0:1]
	s_nop 0
	v_mul_f32_e32 v0, v5, v5
	v_pk_add_f32 v[2:3], v[90:91], v[2:3]
	v_fmac_f32_e32 v0, v4, v4
	v_fmac_f32_e32 v0, v2, v2
	v_fmac_f32_e32 v0, v3, v3
	v_mov_b32_e32 v1, v0
	s_nop 0
	v_cvt_pk_bf16_f32 v4, v4, v5
	s_nop 0
	v_cvt_pk_bf16_f32 v5, v2, v3
	s_waitcnt lgkmcnt(0)
	s_nop 1
	v_permlane32_swap_b32_e32 v0, v1
	v_add_f32_e32 v0, v0, v1
	ds_bpermute_b32 v1, v201, v0
	s_waitcnt lgkmcnt(0)
	v_add_f32_e32 v0, v0, v1
	s_nop 1
	v_mov_b32_dpp v1, v0 row_mirror row_mask:0xf bank_mask:0xf
	s_waitcnt lgkmcnt(0)
	v_add_f32_e32 v0, v0, v1
	s_nop 1
	v_mov_b32_dpp v1, v0 row_half_mirror row_mask:0xf bank_mask:0xf
	s_waitcnt lgkmcnt(0)
	v_add_f32_e32 v6, v0, v1
	s_nop 1
	v_mov_b32_dpp v7, v6 quad_perm:[2,3,0,1] row_mask:0xf bank_mask:0xf
	v_add_u32_e32 v0, s44, v138
	v_ashrrev_i32_e32 v1, 31, v0
	s_waitcnt lgkmcnt(0)
	v_add_f32_e32 v2, v6, v7
	s_nop 1
	v_mov_b32_dpp v3, v2 quad_perm:[1,0,3,2] row_mask:0xf bank_mask:0xf
	v_lshlrev_b64 v[6:7], 11, v[0:1]
	v_lshl_add_u64 v[6:7], s[30:31], 0, v[6:7]
	v_lshl_add_u64 v[6:7], v[194:195], 1, v[6:7]
	global_store_dwordx2 v[6:7], v[4:5], off nt
	s_and_saveexec_b64 s[4:5], vcc
	s_cbranch_execz .LBB0_874
	v_lshl_add_u64 v[0:1], v[0:1], 4, s[8:9]
	s_waitcnt lgkmcnt(0)
	v_add_f32_e32 v2, v2, v3
	v_lshl_add_u64 v[0:1], s[42:43], 2, v[0:1]
	global_store_dword v[0:1], v2, off
.LBB0_874:
	s_or_b64 exec, exec, s[4:5]
	v_add_u32_e32 v0, v177, v178
	s_waitcnt lgkmcnt(0)
	ds_read_b128 v[0:3], v0
	s_waitcnt vmcnt(15) lgkmcnt(0)
	v_pk_add_f32 v[4:5], v[84:85], v[0:1]
	s_nop 0
	v_mul_f32_e32 v0, v5, v5
	v_pk_add_f32 v[2:3], v[86:87], v[2:3]
	v_fmac_f32_e32 v0, v4, v4
	v_fmac_f32_e32 v0, v2, v2
	v_fmac_f32_e32 v0, v3, v3
	v_mov_b32_e32 v1, v0
	s_nop 0
	v_cvt_pk_bf16_f32 v4, v4, v5
	s_nop 0
	v_cvt_pk_bf16_f32 v5, v2, v3
	s_waitcnt lgkmcnt(0)
	s_nop 1
	v_permlane32_swap_b32_e32 v0, v1
	v_add_f32_e32 v0, v0, v1
	ds_bpermute_b32 v1, v201, v0
	s_waitcnt lgkmcnt(0)
	v_add_f32_e32 v0, v0, v1
	s_nop 1
	v_mov_b32_dpp v1, v0 row_mirror row_mask:0xf bank_mask:0xf
	s_waitcnt lgkmcnt(0)
	v_add_f32_e32 v0, v0, v1
	s_nop 1
	v_mov_b32_dpp v1, v0 row_half_mirror row_mask:0xf bank_mask:0xf
	s_waitcnt lgkmcnt(0)
	v_add_f32_e32 v6, v0, v1
	s_nop 1
	v_mov_b32_dpp v7, v6 quad_perm:[2,3,0,1] row_mask:0xf bank_mask:0xf
	v_add_u32_e32 v0, s44, v142
	v_ashrrev_i32_e32 v1, 31, v0
	s_waitcnt lgkmcnt(0)
	v_add_f32_e32 v2, v6, v7
	s_nop 1
	v_mov_b32_dpp v3, v2 quad_perm:[1,0,3,2] row_mask:0xf bank_mask:0xf
	v_lshlrev_b64 v[6:7], 11, v[0:1]
	v_lshl_add_u64 v[6:7], s[30:31], 0, v[6:7]
	v_lshl_add_u64 v[6:7], v[194:195], 1, v[6:7]
	global_store_dwordx2 v[6:7], v[4:5], off nt
	s_and_saveexec_b64 s[4:5], vcc
	s_cbranch_execz .LBB0_876
	v_lshl_add_u64 v[0:1], v[0:1], 4, s[8:9]
	s_waitcnt lgkmcnt(0)
	v_add_f32_e32 v2, v2, v3
	v_lshl_add_u64 v[0:1], s[42:43], 2, v[0:1]
	global_store_dword v[0:1], v2, off
.LBB0_876:
	s_or_b64 exec, exec, s[4:5]
	v_add_u32_e32 v0, v179, v180
	s_waitcnt lgkmcnt(0)
	ds_read_b128 v[0:3], v0
	s_waitcnt vmcnt(15) lgkmcnt(0)
	v_pk_add_f32 v[4:5], v[80:81], v[0:1]
	s_nop 0
	v_mul_f32_e32 v0, v5, v5
	v_pk_add_f32 v[2:3], v[82:83], v[2:3]
	v_fmac_f32_e32 v0, v4, v4
	v_fmac_f32_e32 v0, v2, v2
	v_fmac_f32_e32 v0, v3, v3
	v_mov_b32_e32 v1, v0
	s_nop 0
	v_cvt_pk_bf16_f32 v4, v4, v5
	s_nop 0
	v_cvt_pk_bf16_f32 v5, v2, v3
	s_waitcnt lgkmcnt(0)
	s_nop 1
	v_permlane32_swap_b32_e32 v0, v1
	v_add_f32_e32 v0, v0, v1
	ds_bpermute_b32 v1, v201, v0
	s_waitcnt lgkmcnt(0)
	v_add_f32_e32 v0, v0, v1
	s_nop 1
	v_mov_b32_dpp v1, v0 row_mirror row_mask:0xf bank_mask:0xf
	s_waitcnt lgkmcnt(0)
	v_add_f32_e32 v0, v0, v1
	s_nop 1
	v_mov_b32_dpp v1, v0 row_half_mirror row_mask:0xf bank_mask:0xf
	s_waitcnt lgkmcnt(0)
	v_add_f32_e32 v6, v0, v1
	s_nop 1
	v_mov_b32_dpp v7, v6 quad_perm:[2,3,0,1] row_mask:0xf bank_mask:0xf
	v_add_u32_e32 v0, s44, v154
	v_ashrrev_i32_e32 v1, 31, v0
	s_waitcnt lgkmcnt(0)
	v_add_f32_e32 v2, v6, v7
	s_nop 1
	v_mov_b32_dpp v3, v2 quad_perm:[1,0,3,2] row_mask:0xf bank_mask:0xf
	v_lshlrev_b64 v[6:7], 11, v[0:1]
	v_lshl_add_u64 v[6:7], s[30:31], 0, v[6:7]
	v_lshl_add_u64 v[6:7], v[194:195], 1, v[6:7]
	global_store_dwordx2 v[6:7], v[4:5], off nt
	s_and_saveexec_b64 s[4:5], vcc
	s_cbranch_execz .LBB0_878
	v_lshl_add_u64 v[0:1], v[0:1], 4, s[8:9]
	s_waitcnt lgkmcnt(0)
	v_add_f32_e32 v2, v2, v3
	v_lshl_add_u64 v[0:1], s[42:43], 2, v[0:1]
	global_store_dword v[0:1], v2, off
.LBB0_878:
	s_or_b64 exec, exec, s[4:5]
	v_add_u32_e32 v0, v181, v182
	s_waitcnt lgkmcnt(0)
	ds_read_b128 v[0:3], v0
	s_waitcnt vmcnt(15) lgkmcnt(0)
	v_pk_add_f32 v[4:5], v[76:77], v[0:1]
	s_nop 0
	v_mul_f32_e32 v0, v5, v5
	v_pk_add_f32 v[2:3], v[78:79], v[2:3]
	v_fmac_f32_e32 v0, v4, v4
	v_fmac_f32_e32 v0, v2, v2
	v_fmac_f32_e32 v0, v3, v3
	v_mov_b32_e32 v1, v0
	s_nop 0
	v_cvt_pk_bf16_f32 v4, v4, v5
	s_nop 0
	v_cvt_pk_bf16_f32 v5, v2, v3
	s_waitcnt lgkmcnt(0)
	s_nop 1
	v_permlane32_swap_b32_e32 v0, v1
	v_add_f32_e32 v0, v0, v1
	ds_bpermute_b32 v1, v201, v0
	s_waitcnt lgkmcnt(0)
	v_add_f32_e32 v0, v0, v1
	s_nop 1
	v_mov_b32_dpp v1, v0 row_mirror row_mask:0xf bank_mask:0xf
	s_waitcnt lgkmcnt(0)
	v_add_f32_e32 v0, v0, v1
	s_nop 1
	v_mov_b32_dpp v1, v0 row_half_mirror row_mask:0xf bank_mask:0xf
	s_waitcnt lgkmcnt(0)
	v_add_f32_e32 v6, v0, v1
	s_nop 1
	v_mov_b32_dpp v7, v6 quad_perm:[2,3,0,1] row_mask:0xf bank_mask:0xf
	v_add_u32_e32 v0, s44, v157
	v_ashrrev_i32_e32 v1, 31, v0
	s_waitcnt lgkmcnt(0)
	v_add_f32_e32 v2, v6, v7
	s_nop 1
	v_mov_b32_dpp v3, v2 quad_perm:[1,0,3,2] row_mask:0xf bank_mask:0xf
	v_lshlrev_b64 v[6:7], 11, v[0:1]
	v_lshl_add_u64 v[6:7], s[30:31], 0, v[6:7]
	v_lshl_add_u64 v[6:7], v[194:195], 1, v[6:7]
	global_store_dwordx2 v[6:7], v[4:5], off nt
	s_and_saveexec_b64 s[4:5], vcc
	s_cbranch_execz .LBB0_880
	v_lshl_add_u64 v[0:1], v[0:1], 4, s[8:9]
	s_waitcnt lgkmcnt(0)
	v_add_f32_e32 v2, v2, v3
	v_lshl_add_u64 v[0:1], s[42:43], 2, v[0:1]
	global_store_dword v[0:1], v2, off
; __device__ __forceinline__ u32x2 pack4(f32x4 v) { return u32x2{cvtpk(v[0], v[1]), cvtpk(v[2], v[3])}; }
; __device__ __forceinline__ f32x4 unpack4(u32x2 w) { return f32x4{bflo(w[0]), bfhi(w[0]), bflo(w[1]), bfhi(w[1])}; }
; __device__ __forceinline__ float wave_sum(float v) {
; #pragma unroll
;   for (int o = 32; o > 0; o >>= 1) v += __shfl_xor(v, o);
;   return v;
; template <int EPI, int nN, int lda, int ldb, int K, int ldc>
; __device__ __forceinline__ void gemm_phase(const Params& p, const u16* __restrict__ A, const u16* __restrict__ Bt, u16* C, u16* shm, int wave_s) {
;     ...
;         for (int i = 0; i < 16; ++i) {
;           const int r = i * 8 + wid;
;           const f32x4 v = stg_r32(stg, r, lane);
;           const size_t grow = (size_t)(brow + ai * 128 + r);
;           const int col = bcol + lane * 4;
;           if constexpr (EPI == EPI_CONVG) {
;             *reinterpret_cast<u32x2*>(C + grow * 1024 + col) = pack4(v * unpack4u8(pre8[i]));
;           } else if constexpr (EPI == EPI_MERGE) {
;             __builtin_nontemporal_store(pack4(v * unpack4u8(pre8[i]) + unpack4(pre16b[i])), reinterpret_cast<u32x2*>(C + grow * 1024 + col));
;           } else if constexpr (EPI == EPI_RESX) {
;             const f32x4 o = pre32[i] + v;
;             __builtin_nontemporal_store(pack4(o), reinterpret_cast<u32x2*>((u16*)(p.ws + OFF_HFN) + grow * DM + col));
;             const float ss = wave_sum(o[0] * o[0] + o[1] * o[1] + o[2] * o[2] + o[3] * o[3]);
;             if (lane == 0) ((float*)(p.ws + OFF_PSQ))[grow * 4 + pn] = ss;
.LBB0_880:
	s_or_b64 exec, exec, s[4:5]
	v_add_u32_e32 v0, v183, v184
	s_waitcnt lgkmcnt(0)
	ds_read_b128 v[0:3], v0
	s_waitcnt vmcnt(15) lgkmcnt(0)
	v_pk_add_f32 v[4:5], v[72:73], v[0:1]
	s_nop 0
	v_mul_f32_e32 v0, v5, v5
	v_pk_add_f32 v[2:3], v[74:75], v[2:3]
	v_fmac_f32_e32 v0, v4, v4
	v_fmac_f32_e32 v0, v2, v2
	v_fmac_f32_e32 v0, v3, v3
	v_mov_b32_e32 v1, v0
	s_nop 0
	v_cvt_pk_bf16_f32 v4, v4, v5
	s_nop 0
	v_cvt_pk_bf16_f32 v5, v2, v3
	s_waitcnt lgkmcnt(0)
	s_nop 1
	v_permlane32_swap_b32_e32 v0, v1
	v_add_f32_e32 v0, v0, v1
	ds_bpermute_b32 v1, v201, v0
	s_waitcnt lgkmcnt(0)
	v_add_f32_e32 v0, v0, v1
	s_nop 1
	v_mov_b32_dpp v1, v0 row_mirror row_mask:0xf bank_mask:0xf
	s_waitcnt lgkmcnt(0)
	v_add_f32_e32 v0, v0, v1
	s_nop 1
	v_mov_b32_dpp v1, v0 row_half_mirror row_mask:0xf bank_mask:0xf
	s_waitcnt lgkmcnt(0)
	v_add_f32_e32 v6, v0, v1
	s_nop 1
	v_mov_b32_dpp v7, v6 quad_perm:[2,3,0,1] row_mask:0xf bank_mask:0xf
	v_add_u32_e32 v0, s44, v163
	v_ashrrev_i32_e32 v1, 31, v0
	s_waitcnt lgkmcnt(0)
	v_add_f32_e32 v2, v6, v7
	s_nop 1
	v_mov_b32_dpp v3, v2 quad_perm:[1,0,3,2] row_mask:0xf bank_mask:0xf
	v_lshlrev_b64 v[6:7], 11, v[0:1]
	v_lshl_add_u64 v[6:7], s[30:31], 0, v[6:7]
	v_lshl_add_u64 v[6:7], v[194:195], 1, v[6:7]
	global_store_dwordx2 v[6:7], v[4:5], off nt
	s_and_saveexec_b64 s[4:5], vcc
	s_cbranch_execz .LBB0_882
	v_lshl_add_u64 v[0:1], v[0:1], 4, s[8:9]
	s_waitcnt lgkmcnt(0)
	v_add_f32_e32 v2, v2, v3
	v_lshl_add_u64 v[0:1], s[42:43], 2, v[0:1]
	global_store_dword v[0:1], v2, off
.LBB0_882:
	s_or_b64 exec, exec, s[4:5]
	v_add_u32_e32 v0, v185, v186
	s_waitcnt lgkmcnt(0)
	ds_read_b128 v[0:3], v0
	s_waitcnt vmcnt(15) lgkmcnt(0)
	v_pk_add_f32 v[4:5], v[68:69], v[0:1]
	s_nop 0
	v_mul_f32_e32 v0, v5, v5
	v_pk_add_f32 v[2:3], v[70:71], v[2:3]
	v_fmac_f32_e32 v0, v4, v4
	v_fmac_f32_e32 v0, v2, v2
	v_fmac_f32_e32 v0, v3, v3
	v_mov_b32_e32 v1, v0
	s_nop 0
	v_cvt_pk_bf16_f32 v4, v4, v5
	s_nop 0
	v_cvt_pk_bf16_f32 v5, v2, v3
	s_waitcnt lgkmcnt(0)
	s_nop 1
	v_permlane32_swap_b32_e32 v0, v1
	v_add_f32_e32 v0, v0, v1
	ds_bpermute_b32 v1, v201, v0
	s_waitcnt lgkmcnt(0)
	v_add_f32_e32 v0, v0, v1
	s_nop 1
	v_mov_b32_dpp v1, v0 row_mirror row_mask:0xf bank_mask:0xf
	s_waitcnt lgkmcnt(0)
	v_add_f32_e32 v0, v0, v1
	s_nop 1
	v_mov_b32_dpp v1, v0 row_half_mirror row_mask:0xf bank_mask:0xf
	s_waitcnt lgkmcnt(0)
	v_add_f32_e32 v6, v0, v1
	s_nop 1
	v_mov_b32_dpp v7, v6 quad_perm:[2,3,0,1] row_mask:0xf bank_mask:0xf
	v_add_u32_e32 v0, s44, v167
	v_ashrrev_i32_e32 v1, 31, v0
	s_waitcnt lgkmcnt(0)
	v_add_f32_e32 v2, v6, v7
	s_nop 1
	v_mov_b32_dpp v3, v2 quad_perm:[1,0,3,2] row_mask:0xf bank_mask:0xf
	v_lshlrev_b64 v[6:7], 11, v[0:1]
	v_lshl_add_u64 v[6:7], s[30:31], 0, v[6:7]
	v_lshl_add_u64 v[6:7], v[194:195], 1, v[6:7]
	global_store_dwordx2 v[6:7], v[4:5], off nt
	s_and_saveexec_b64 s[4:5], vcc
	s_cbranch_execz .LBB0_884
	v_lshl_add_u64 v[0:1], v[0:1], 4, s[8:9]
	s_waitcnt lgkmcnt(0)
	v_add_f32_e32 v2, v2, v3
	v_lshl_add_u64 v[0:1], s[42:43], 2, v[0:1]
	global_store_dword v[0:1], v2, off
.LBB0_884:
	s_or_b64 exec, exec, s[4:5]
	v_add_u32_e32 v0, v187, v188
	s_waitcnt lgkmcnt(0)
	ds_read_b128 v[0:3], v0
	s_waitcnt vmcnt(15) lgkmcnt(0)
	v_pk_add_f32 v[4:5], v[64:65], v[0:1]
	s_nop 0
	v_mul_f32_e32 v0, v5, v5
	v_pk_add_f32 v[2:3], v[66:67], v[2:3]
	v_fmac_f32_e32 v0, v4, v4
	v_fmac_f32_e32 v0, v2, v2
	v_fmac_f32_e32 v0, v3, v3
	v_mov_b32_e32 v1, v0
	s_nop 0
	v_cvt_pk_bf16_f32 v4, v4, v5
	s_nop 0
	v_cvt_pk_bf16_f32 v5, v2, v3
	s_waitcnt lgkmcnt(0)
	s_nop 1
	v_permlane32_swap_b32_e32 v0, v1
	v_add_f32_e32 v0, v0, v1
	ds_bpermute_b32 v1, v201, v0
	s_waitcnt lgkmcnt(0)
	v_add_f32_e32 v0, v0, v1
	s_nop 1
	v_mov_b32_dpp v1, v0 row_mirror row_mask:0xf bank_mask:0xf
	s_waitcnt lgkmcnt(0)
	v_add_f32_e32 v0, v0, v1
	s_nop 1
	v_mov_b32_dpp v1, v0 row_half_mirror row_mask:0xf bank_mask:0xf
	s_waitcnt lgkmcnt(0)
	v_add_f32_e32 v6, v0, v1
	s_nop 1
	v_mov_b32_dpp v7, v6 quad_perm:[2,3,0,1] row_mask:0xf bank_mask:0xf
	v_add_u32_e32 v0, s44, v170
	v_ashrrev_i32_e32 v1, 31, v0
	s_waitcnt lgkmcnt(0)
	v_add_f32_e32 v2, v6, v7
	s_nop 1
	v_mov_b32_dpp v3, v2 quad_perm:[1,0,3,2] row_mask:0xf bank_mask:0xf
	v_lshlrev_b64 v[6:7], 11, v[0:1]
	v_lshl_add_u64 v[6:7], s[30:31], 0, v[6:7]
	v_lshl_add_u64 v[6:7], v[194:195], 1, v[6:7]
	global_store_dwordx2 v[6:7], v[4:5], off nt
	s_and_saveexec_b64 s[4:5], vcc
	s_cbranch_execz .LBB0_815
	v_lshl_add_u64 v[0:1], v[0:1], 4, s[8:9]
	v_lshl_add_u64 v[0:1], s[42:43], 2, v[0:1]
	s_waitcnt lgkmcnt(0)
	v_add_f32_e32 v2, v2, v3
	global_store_dword v[0:1], v2, off
	s_branch .LBB0_815
